# scan chunk body rewritten: row-pair packed layout, hazard gaps filled with LDS prefetch and independent pk ops (1352 vs 1703 instr per 32-step chunk)
# speedup vs baseline: 1.0532x; 1.0532x over previous
.LBB0_1186:
	s_sleep 1
	global_load_dword v2, v1, s[14:15] sc1
	s_add_i32 s5, s4, 1
	s_cmp_lt_u32 s4, 0x1000000
	s_mov_b32 s4, s5
	s_cselect_b64 s[6:7], -1, 0
	s_waitcnt vmcnt(0)
	v_readfirstlane_b32 s5, v2
	s_cmp_eq_u32 s5, 0
	s_cselect_b64 s[8:9], -1, 0
	s_and_b64 s[6:7], s[6:7], s[8:9]
	s_and_b64 vcc, exec, s[6:7]
	s_cbranch_vccnz .LBB0_1186
	s_ashr_i32 s6, s0, 1
	s_lshl_b32 s0, s0, 5
	s_lshl_b32 s4, s1, 3
	s_and_b32 s0, s0, 32
	s_and_b32 s4, s4, 24
	s_or_b32 s7, s4, s0
	s_lshl_b32 s4, s6, 6
	s_ashr_i32 s5, s4, 31
	s_lshl_b64 s[4:5], s[4:5], 2
	s_add_u32 s4, s2, s4
	s_addc_u32 s5, s3, s5
	s_mul_hi_i32 s0, s6, 0xc00000
	s_mul_i32 s6, s6, 0xc00000
	s_add_u32 s2, s2, s6
	s_mul_i32 s9, s1, 0x1800
	s_addc_u32 s0, s3, s0
	v_lshlrev_b32_e32 v2, 4, v0
	s_mul_hi_i32 s8, s1, 0x1800
	s_add_u32 s2, s2, s9
	v_ashrrev_i32_e32 v3, 31, v2
	s_addc_u32 s3, s0, s8
	v_lshl_add_u64 v[2:3], s[2:3], 0, v[2:3]
	s_add_i32 s0, s9, 0
	v_lshl_add_u64 v[184:185], v[2:3], 0, s[60:61]
	s_mov_b32 m0, s0
	v_lshl_add_u64 v[4:5], v[2:3], 0, s[68:69]
	global_load_lds_dwordx4 v[184:185], off sc1
	s_add_i32 m0, s0, 0x400
	s_mov_b64 s[2:3], 0x44c00800
	global_load_lds_dwordx4 v[4:5], off sc1
	v_lshl_add_u64 v[4:5], v[2:3], 0, s[2:3]
	s_add_i32 m0, s0, 0x800
	s_mov_b64 s[2:3], 0x44c00c00
	global_load_lds_dwordx4 v[4:5], off sc1
	v_lshl_add_u64 v[4:5], v[2:3], 0, s[2:3]
	s_add_i32 m0, s0, 0xc00
	s_mov_b64 s[2:3], 0x44c01000
	global_load_lds_dwordx4 v[4:5], off sc1
	v_lshl_add_u64 v[4:5], v[2:3], 0, s[2:3]
	s_add_i32 m0, s0, 0x1000
	s_mov_b64 s[2:3], 0x44c01400
	global_load_lds_dwordx4 v[4:5], off sc1
	v_lshl_add_u64 v[2:3], v[2:3], 0, s[2:3]
	s_add_i32 m0, s0, 0x1400
	s_mov_b64 s[2:3], 0x5cd00000
	global_load_lds_dwordx4 v[2:3], off sc1
	global_load_dword v195, v1, s[14:15] offset:16 sc1
	v_ashrrev_i32_e32 v2, 3, v0
	v_and_b32_e32 v2, -2, v2
	v_add_u32_e32 v2, s7, v2
	v_ashrrev_i32_e32 v3, 31, v2
	v_lshl_add_u64 v[4:5], v[2:3], 2, s[4:5]
	v_and_b32_e32 v189, 1, v0
	v_lshl_add_u64 v[182:183], v[4:5], 0, s[2:3]
	v_and_b32_e32 v188, 15, v0
	v_lshlrev_b32_e32 v190, 2, v2
	v_and_b32_e32 v2, 2, v0
	s_cmp_lt_i32 s1, 4
	v_bfe_u32 v3, v0, 2, 2
	v_lshlrev_b32_e32 v0, 2, v189
	v_lshlrev_b32_e32 v191, 4, v188
	s_cselect_b64 s[16:17], -1, 0
	s_cmp_gt_i32 s1, 3
	v_lshl_add_u64 v[186:187], v[182:183], 0, v[0:1]
	v_mov_b32_e32 v0, v1
	s_mov_b32 s25, 0
	v_cmp_eq_u32_e64 s[2:3], 0, v189
	v_cmp_eq_u32_e64 s[4:5], 0, v2
	s_cselect_b64 s[18:19], -1, 0
	v_add_u32_e32 v192, 0, v191
	v_cmp_gt_u32_e64 s[6:7], 4, v188
	v_add_u32_e32 v193, -1, v3
	v_cmp_ne_u32_e64 s[8:9], 0, v2
	v_cmp_eq_u32_e64 s[10:11], 1, v3
	v_cmp_eq_u32_e64 s[12:13], 2, v3
	v_add_u32_e32 v194, 3, v3
	v_mov_b64_e32 v[14:15], v[0:1]
	v_mov_b64_e32 v[30:31], v[0:1]
	v_mov_b64_e32 v[22:23], v[0:1]
	v_mov_b64_e32 v[24:25], v[0:1]
	v_mov_b64_e32 v[16:17], v[0:1]
	v_mov_b64_e32 v[32:33], v[0:1]
	v_mov_b64_e32 v[120:121], v[0:1]
	v_mov_b64_e32 v[122:123], v[0:1]
	v_mov_b64_e32 v[124:125], v[0:1]
	v_mov_b64_e32 v[126:127], v[0:1]
	v_mov_b64_e32 v[128:129], v[0:1]
	s_waitcnt vmcnt(0) lgkmcnt(0)
	s_barrier

.LBB0_1196:
	s_cmpk_eq_i32 s1, 0x100
	s_cbranch_scc0 .LBB0_1218
	s_branch .LBB0_1219

.LBB0_1198:
	s_mul_i32 s22, s24, 0xc000
	s_lshl_b32 s23, s25, 5
	v_add_u32_e32 v196, s22, v191
	v_add_u32_e32 v197, s22, v190
	v_add_u32_e32 v104, s23, v193
	s_mov_b64 s[26:27], 0x8000
	s_andn2_b64 s[30:31], s[8:9], s[6:7]
	s_cmp_eq_u32 s25, 0
	s_cselect_b64 s[30:31], s[30:31], s[8:9]
	ds_read_b128 v[8:11], v196 offset:0
	ds_read_b128 v[12:15], v196 offset:256
	ds_read_b128 v[16:19], v196 offset:512
	ds_read_b128 v[20:23], v196 offset:768
	ds_read_b128 v[24:27], v196 offset:1024
	ds_read_b64 v[28:29], v197 offset:1280
	ds_read_b128 v[32:35], v196 offset:1536
	ds_read_b128 v[36:39], v196 offset:1792
	ds_read_b128 v[40:43], v196 offset:2048
	ds_read_b128 v[44:47], v196 offset:2304
	ds_read_b128 v[48:51], v196 offset:2560
	ds_read_b64 v[52:53], v197 offset:2816
	v_ashrrev_i32_e32 v105, 31, v104
	v_lshlrev_b64 v[104:105], 13, v[104:105]
	v_lshl_add_u64 v[104:105], v[104:105], 0, v[186:187]
	s_waitcnt lgkmcnt(6)
	ds_read_b128 v[56:59], v196 offset:3072
	ds_read_b128 v[60:63], v196 offset:3328
	ds_read_b128 v[64:67], v196 offset:3584
	ds_read_b128 v[68:71], v196 offset:3840
	ds_read_b128 v[72:75], v196 offset:4096
	ds_read_b64 v[76:77], v197 offset:4352
	v_pk_mul_f32 v[132:133], v[120:121], v[20:21] op_sel:[0,0] op_sel_hi:[1,0]
	v_pk_fma_f32 v[132:133], v[122:123], v[20:21], v[132:133] op_sel:[0,1,0] op_sel_hi:[1,1,1]
	v_pk_fma_f32 v[132:133], v[124:125], v[22:23], v[132:133] op_sel:[0,0,0] op_sel_hi:[1,0,1]
	v_pk_fma_f32 v[132:133], v[126:127], v[22:23], v[132:133] op_sel:[0,1,0] op_sel_hi:[1,1,1]
	s_waitcnt lgkmcnt(6)
	v_cndmask_b32_e64 v134, v133, v132, s[2:3]
	v_cndmask_b32_e64 v135, v132, v133, s[2:3]
	v_cndmask_b32_e64 v136, v129, v128, s[2:3]
	v_cndmask_b32_e64 v137, v128, v129, s[2:3]
	v_add_f32_dpp v138, v135, v134 quad_perm:[1,0,3,2] row_mask:0xf bank_mask:0xf bound_ctrl:1
	v_pk_mul_f32 v[150:151], v[16:17], v[28:29] op_sel:[0,0] op_sel_hi:[0,1]
	v_add_f32_dpp v139, v137, v136 quad_perm:[1,0,3,2] row_mask:0xf bank_mask:0xf bound_ctrl:1
	v_cndmask_b32_e64 v140, v139, v138, s[4:5]
	v_cndmask_b32_e64 v141, v138, v139, s[4:5]
	v_pk_mul_f32 v[152:153], v[16:17], v[28:29] op_sel:[1,0] op_sel_hi:[1,1]
	v_pk_mul_f32 v[154:155], v[18:19], v[28:29] op_sel:[0,0] op_sel_hi:[0,1]
	v_add_f32_dpp v142, v141, v140 quad_perm:[2,3,0,1] row_mask:0xf bank_mask:0xf bound_ctrl:1
	v_pk_mul_f32 v[156:157], v[18:19], v[28:29] op_sel:[1,0] op_sel_hi:[1,1]
	v_pk_fma_f32 v[150:151], v[120:121], v[8:9], v[150:151] op_sel:[0,0,0] op_sel_hi:[1,0,1]
	v_add_f32_dpp v142, v142, v142 row_ror:4 row_mask:0xf bank_mask:0xf bound_ctrl:1
	v_pk_fma_f32 v[152:153], v[122:123], v[8:9], v[152:153] op_sel:[0,1,0] op_sel_hi:[1,1,1]
	v_pk_fma_f32 v[154:155], v[124:125], v[10:11], v[154:155] op_sel:[0,0,0] op_sel_hi:[1,0,1]
	v_add_f32_dpp v144, v142, v142 row_ror:8 row_mask:0xf bank_mask:0xf bound_ctrl:1
	v_pk_fma_f32 v[156:157], v[126:127], v[10:11], v[156:157] op_sel:[0,1,0] op_sel_hi:[1,1,1]
	ds_read_b128 v[80:83], v196 offset:4608
	v_mov_b32_dpp v148, v144 quad_perm:[0,0,0,0] row_mask:0xf bank_mask:0xf
	v_mov_b32_dpp v149, v144 quad_perm:[1,1,1,1] row_mask:0xf bank_mask:0xf
	v_pk_fma_f32 v[120:121], v[24:25], v[148:149], v[150:151] op_sel:[0,0,0] op_sel_hi:[0,1,1]
	ds_read_b128 v[84:87], v196 offset:4864
	v_pk_fma_f32 v[122:123], v[24:25], v[148:149], v[152:153] op_sel:[1,0,0] op_sel_hi:[1,1,1]
	ds_read_b128 v[88:91], v196 offset:5120
	v_pk_fma_f32 v[124:125], v[26:27], v[148:149], v[154:155] op_sel:[0,0,0] op_sel_hi:[0,1,1]
	ds_read_b128 v[92:95], v196 offset:5376
	v_pk_fma_f32 v[126:127], v[26:27], v[148:149], v[156:157] op_sel:[1,0,0] op_sel_hi:[1,1,1]
	ds_read_b128 v[96:99], v196 offset:5632
	v_pk_mul_f32 v[132:133], v[120:121], v[44:45] op_sel:[0,0] op_sel_hi:[1,0]
	v_pk_mul_f32 v[128:129], v[120:121], v[12:13] op_sel:[0,0] op_sel_hi:[1,0]
	v_pk_fma_f32 v[132:133], v[122:123], v[44:45], v[132:133] op_sel:[0,1,0] op_sel_hi:[1,1,1]
	v_pk_fma_f32 v[128:129], v[122:123], v[12:13], v[128:129] op_sel:[0,1,0] op_sel_hi:[1,1,1]
	v_pk_fma_f32 v[132:133], v[124:125], v[46:47], v[132:133] op_sel:[0,0,0] op_sel_hi:[1,0,1]
	v_pk_fma_f32 v[128:129], v[124:125], v[14:15], v[128:129] op_sel:[0,0,0] op_sel_hi:[1,0,1]
	v_pk_fma_f32 v[132:133], v[126:127], v[46:47], v[132:133] op_sel:[0,1,0] op_sel_hi:[1,1,1]
	v_pk_fma_f32 v[128:129], v[126:127], v[14:15], v[128:129] op_sel:[0,1,0] op_sel_hi:[1,1,1]
	ds_read_b64 v[100:101], v197 offset:5888
	s_waitcnt lgkmcnt(6)
	v_cndmask_b32_e64 v134, v133, v132, s[2:3]
	v_cndmask_b32_e64 v135, v132, v133, s[2:3]
	v_cndmask_b32_e64 v136, v129, v128, s[2:3]
	v_cndmask_b32_e64 v137, v128, v129, s[2:3]
	v_add_f32_dpp v138, v135, v134 quad_perm:[1,0,3,2] row_mask:0xf bank_mask:0xf bound_ctrl:1
	v_pk_mul_f32 v[150:151], v[40:41], v[52:53] op_sel:[0,0] op_sel_hi:[0,1]
	v_add_f32_dpp v139, v137, v136 quad_perm:[1,0,3,2] row_mask:0xf bank_mask:0xf bound_ctrl:1
	v_cndmask_b32_e64 v140, v139, v138, s[4:5]
	v_cndmask_b32_e64 v141, v138, v139, s[4:5]
	v_pk_mul_f32 v[152:153], v[40:41], v[52:53] op_sel:[1,0] op_sel_hi:[1,1]
	v_pk_mul_f32 v[154:155], v[42:43], v[52:53] op_sel:[0,0] op_sel_hi:[0,1]
	v_add_f32_dpp v142, v141, v140 quad_perm:[2,3,0,1] row_mask:0xf bank_mask:0xf bound_ctrl:1
	v_pk_mul_f32 v[156:157], v[42:43], v[52:53] op_sel:[1,0] op_sel_hi:[1,1]
	v_pk_fma_f32 v[150:151], v[120:121], v[32:33], v[150:151] op_sel:[0,0,0] op_sel_hi:[1,0,1]
	v_add_f32_dpp v142, v142, v142 row_ror:4 row_mask:0xf bank_mask:0xf bound_ctrl:1
	v_pk_fma_f32 v[152:153], v[122:123], v[32:33], v[152:153] op_sel:[0,1,0] op_sel_hi:[1,1,1]
	v_pk_fma_f32 v[154:155], v[124:125], v[34:35], v[154:155] op_sel:[0,0,0] op_sel_hi:[1,0,1]
	v_add_f32_dpp v145, v142, v142 row_ror:8 row_mask:0xf bank_mask:0xf bound_ctrl:1
	v_pk_fma_f32 v[156:157], v[126:127], v[34:35], v[156:157] op_sel:[0,1,0] op_sel_hi:[1,1,1]
	ds_read_b128 v[8:11], v196 offset:6144
	v_mov_b32_dpp v148, v145 quad_perm:[0,0,0,0] row_mask:0xf bank_mask:0xf
	v_mov_b32_dpp v149, v145 quad_perm:[1,1,1,1] row_mask:0xf bank_mask:0xf
	v_pk_fma_f32 v[120:121], v[48:49], v[148:149], v[150:151] op_sel:[0,0,0] op_sel_hi:[0,1,1]
	ds_read_b128 v[12:15], v196 offset:6400
	v_pk_fma_f32 v[122:123], v[48:49], v[148:149], v[152:153] op_sel:[1,0,0] op_sel_hi:[1,1,1]
	ds_read_b128 v[16:19], v196 offset:6656
	v_pk_fma_f32 v[124:125], v[50:51], v[148:149], v[154:155] op_sel:[0,0,0] op_sel_hi:[0,1,1]
	ds_read_b128 v[20:23], v196 offset:6912
	v_pk_fma_f32 v[126:127], v[50:51], v[148:149], v[156:157] op_sel:[1,0,0] op_sel_hi:[1,1,1]
	ds_read_b128 v[24:27], v196 offset:7168
	v_pk_mul_f32 v[132:133], v[120:121], v[68:69] op_sel:[0,0] op_sel_hi:[1,0]
	v_pk_mul_f32 v[128:129], v[120:121], v[36:37] op_sel:[0,0] op_sel_hi:[1,0]
	v_pk_fma_f32 v[132:133], v[122:123], v[68:69], v[132:133] op_sel:[0,1,0] op_sel_hi:[1,1,1]
	v_pk_fma_f32 v[128:129], v[122:123], v[36:37], v[128:129] op_sel:[0,1,0] op_sel_hi:[1,1,1]
	v_pk_fma_f32 v[132:133], v[124:125], v[70:71], v[132:133] op_sel:[0,0,0] op_sel_hi:[1,0,1]
	v_pk_fma_f32 v[128:129], v[124:125], v[38:39], v[128:129] op_sel:[0,0,0] op_sel_hi:[1,0,1]
	v_pk_fma_f32 v[132:133], v[126:127], v[70:71], v[132:133] op_sel:[0,1,0] op_sel_hi:[1,1,1]
	v_pk_fma_f32 v[128:129], v[126:127], v[38:39], v[128:129] op_sel:[0,1,0] op_sel_hi:[1,1,1]
	ds_read_b64 v[28:29], v197 offset:7424
	s_waitcnt lgkmcnt(6)
	v_cndmask_b32_e64 v134, v133, v132, s[2:3]
	v_cndmask_b32_e64 v135, v132, v133, s[2:3]
	v_cndmask_b32_e64 v136, v129, v128, s[2:3]
	v_cndmask_b32_e64 v137, v128, v129, s[2:3]
	v_add_f32_dpp v138, v135, v134 quad_perm:[1,0,3,2] row_mask:0xf bank_mask:0xf bound_ctrl:1
	v_pk_mul_f32 v[150:151], v[64:65], v[76:77] op_sel:[0,0] op_sel_hi:[0,1]
	v_add_f32_dpp v139, v137, v136 quad_perm:[1,0,3,2] row_mask:0xf bank_mask:0xf bound_ctrl:1
	v_cndmask_b32_e64 v140, v139, v138, s[4:5]
	v_cndmask_b32_e64 v141, v138, v139, s[4:5]
	v_pk_mul_f32 v[152:153], v[64:65], v[76:77] op_sel:[1,0] op_sel_hi:[1,1]
	v_pk_mul_f32 v[154:155], v[66:67], v[76:77] op_sel:[0,0] op_sel_hi:[0,1]
	v_add_f32_dpp v142, v141, v140 quad_perm:[2,3,0,1] row_mask:0xf bank_mask:0xf bound_ctrl:1
	v_pk_mul_f32 v[156:157], v[66:67], v[76:77] op_sel:[1,0] op_sel_hi:[1,1]
	v_pk_fma_f32 v[150:151], v[120:121], v[56:57], v[150:151] op_sel:[0,0,0] op_sel_hi:[1,0,1]
	v_add_f32_dpp v142, v142, v142 row_ror:4 row_mask:0xf bank_mask:0xf bound_ctrl:1
	v_pk_fma_f32 v[152:153], v[122:123], v[56:57], v[152:153] op_sel:[0,1,0] op_sel_hi:[1,1,1]
	v_pk_fma_f32 v[154:155], v[124:125], v[58:59], v[154:155] op_sel:[0,0,0] op_sel_hi:[1,0,1]
	v_add_f32_dpp v146, v142, v142 row_ror:8 row_mask:0xf bank_mask:0xf bound_ctrl:1
	v_pk_fma_f32 v[156:157], v[126:127], v[58:59], v[156:157] op_sel:[0,1,0] op_sel_hi:[1,1,1]
	ds_read_b128 v[32:35], v196 offset:7680
	v_mov_b32_dpp v148, v146 quad_perm:[0,0,0,0] row_mask:0xf bank_mask:0xf
	v_mov_b32_dpp v149, v146 quad_perm:[1,1,1,1] row_mask:0xf bank_mask:0xf
	v_pk_fma_f32 v[120:121], v[72:73], v[148:149], v[150:151] op_sel:[0,0,0] op_sel_hi:[0,1,1]
	ds_read_b128 v[36:39], v196 offset:7936
	v_pk_fma_f32 v[122:123], v[72:73], v[148:149], v[152:153] op_sel:[1,0,0] op_sel_hi:[1,1,1]
	ds_read_b128 v[40:43], v196 offset:8192
	v_pk_fma_f32 v[124:125], v[74:75], v[148:149], v[154:155] op_sel:[0,0,0] op_sel_hi:[0,1,1]
	ds_read_b128 v[44:47], v196 offset:8448
	v_pk_fma_f32 v[126:127], v[74:75], v[148:149], v[156:157] op_sel:[1,0,0] op_sel_hi:[1,1,1]
	ds_read_b128 v[48:51], v196 offset:8704
	v_pk_mul_f32 v[132:133], v[120:121], v[92:93] op_sel:[0,0] op_sel_hi:[1,0]
	v_pk_mul_f32 v[128:129], v[120:121], v[60:61] op_sel:[0,0] op_sel_hi:[1,0]
	v_pk_fma_f32 v[132:133], v[122:123], v[92:93], v[132:133] op_sel:[0,1,0] op_sel_hi:[1,1,1]
	v_pk_fma_f32 v[128:129], v[122:123], v[60:61], v[128:129] op_sel:[0,1,0] op_sel_hi:[1,1,1]
	v_pk_fma_f32 v[132:133], v[124:125], v[94:95], v[132:133] op_sel:[0,0,0] op_sel_hi:[1,0,1]
	v_pk_fma_f32 v[128:129], v[124:125], v[62:63], v[128:129] op_sel:[0,0,0] op_sel_hi:[1,0,1]
	v_pk_fma_f32 v[132:133], v[126:127], v[94:95], v[132:133] op_sel:[0,1,0] op_sel_hi:[1,1,1]
	v_pk_fma_f32 v[128:129], v[126:127], v[62:63], v[128:129] op_sel:[0,1,0] op_sel_hi:[1,1,1]
	ds_read_b64 v[52:53], v197 offset:8960
	s_waitcnt lgkmcnt(6)
	v_cndmask_b32_e64 v134, v133, v132, s[2:3]
	v_cndmask_b32_e64 v135, v132, v133, s[2:3]
	v_cndmask_b32_e64 v136, v129, v128, s[2:3]
	v_cndmask_b32_e64 v137, v128, v129, s[2:3]
	v_add_f32_dpp v138, v135, v134 quad_perm:[1,0,3,2] row_mask:0xf bank_mask:0xf bound_ctrl:1
	v_pk_mul_f32 v[150:151], v[88:89], v[100:101] op_sel:[0,0] op_sel_hi:[0,1]
	v_add_f32_dpp v139, v137, v136 quad_perm:[1,0,3,2] row_mask:0xf bank_mask:0xf bound_ctrl:1
	v_cndmask_b32_e64 v140, v139, v138, s[4:5]
	v_cndmask_b32_e64 v141, v138, v139, s[4:5]
	v_pk_mul_f32 v[152:153], v[88:89], v[100:101] op_sel:[1,0] op_sel_hi:[1,1]
	v_pk_mul_f32 v[154:155], v[90:91], v[100:101] op_sel:[0,0] op_sel_hi:[0,1]
	v_add_f32_dpp v142, v141, v140 quad_perm:[2,3,0,1] row_mask:0xf bank_mask:0xf bound_ctrl:1
	v_pk_mul_f32 v[156:157], v[90:91], v[100:101] op_sel:[1,0] op_sel_hi:[1,1]
	v_pk_fma_f32 v[150:151], v[120:121], v[80:81], v[150:151] op_sel:[0,0,0] op_sel_hi:[1,0,1]
	v_add_f32_dpp v142, v142, v142 row_ror:4 row_mask:0xf bank_mask:0xf bound_ctrl:1
	v_pk_fma_f32 v[152:153], v[122:123], v[80:81], v[152:153] op_sel:[0,1,0] op_sel_hi:[1,1,1]
	v_pk_fma_f32 v[154:155], v[124:125], v[82:83], v[154:155] op_sel:[0,0,0] op_sel_hi:[1,0,1]
	v_add_f32_dpp v147, v142, v142 row_ror:8 row_mask:0xf bank_mask:0xf bound_ctrl:1
	v_pk_fma_f32 v[156:157], v[126:127], v[82:83], v[156:157] op_sel:[0,1,0] op_sel_hi:[1,1,1]
	ds_read_b128 v[56:59], v196 offset:9216
	v_mov_b32_dpp v148, v147 quad_perm:[0,0,0,0] row_mask:0xf bank_mask:0xf
	v_mov_b32_dpp v149, v147 quad_perm:[1,1,1,1] row_mask:0xf bank_mask:0xf
	v_pk_fma_f32 v[120:121], v[96:97], v[148:149], v[150:151] op_sel:[0,0,0] op_sel_hi:[0,1,1]
	ds_read_b128 v[60:63], v196 offset:9472
	v_pk_fma_f32 v[122:123], v[96:97], v[148:149], v[152:153] op_sel:[1,0,0] op_sel_hi:[1,1,1]
	ds_read_b128 v[64:67], v196 offset:9728
	v_pk_fma_f32 v[124:125], v[98:99], v[148:149], v[154:155] op_sel:[0,0,0] op_sel_hi:[0,1,1]
	ds_read_b128 v[68:71], v196 offset:9984
	v_pk_fma_f32 v[126:127], v[98:99], v[148:149], v[156:157] op_sel:[1,0,0] op_sel_hi:[1,1,1]
	ds_read_b128 v[72:75], v196 offset:10240
	v_pk_mul_f32 v[132:133], v[120:121], v[20:21] op_sel:[0,0] op_sel_hi:[1,0]
	v_pk_mul_f32 v[128:129], v[120:121], v[84:85] op_sel:[0,0] op_sel_hi:[1,0]
	v_pk_fma_f32 v[132:133], v[122:123], v[20:21], v[132:133] op_sel:[0,1,0] op_sel_hi:[1,1,1]
	v_pk_fma_f32 v[128:129], v[122:123], v[84:85], v[128:129] op_sel:[0,1,0] op_sel_hi:[1,1,1]
	v_pk_fma_f32 v[132:133], v[124:125], v[22:23], v[132:133] op_sel:[0,0,0] op_sel_hi:[1,0,1]
	v_pk_fma_f32 v[128:129], v[124:125], v[86:87], v[128:129] op_sel:[0,0,0] op_sel_hi:[1,0,1]
	v_pk_fma_f32 v[132:133], v[126:127], v[22:23], v[132:133] op_sel:[0,1,0] op_sel_hi:[1,1,1]
	v_pk_fma_f32 v[128:129], v[126:127], v[86:87], v[128:129] op_sel:[0,1,0] op_sel_hi:[1,1,1]
	ds_read_b64 v[76:77], v197 offset:10496
	v_cndmask_b32_e64 v106, v147, v146, s[12:13]
	v_cndmask_b32_e64 v106, v106, v145, s[10:11]
	v_cndmask_b32_e64 v106, v106, v144, s[6:7]
	s_and_saveexec_b64 s[28:29], s[30:31]
	global_store_dword v[104:105], v106, off
	s_mov_b64 exec, s[28:29]
	v_lshl_add_u64 v[104:105], v[104:105], 0, s[26:27]
	s_waitcnt lgkmcnt(6)
	v_cndmask_b32_e64 v134, v133, v132, s[2:3]
	v_cndmask_b32_e64 v135, v132, v133, s[2:3]
	v_cndmask_b32_e64 v136, v129, v128, s[2:3]
	v_cndmask_b32_e64 v137, v128, v129, s[2:3]
	v_add_f32_dpp v138, v135, v134 quad_perm:[1,0,3,2] row_mask:0xf bank_mask:0xf bound_ctrl:1
	v_pk_mul_f32 v[150:151], v[16:17], v[28:29] op_sel:[0,0] op_sel_hi:[0,1]
	v_add_f32_dpp v139, v137, v136 quad_perm:[1,0,3,2] row_mask:0xf bank_mask:0xf bound_ctrl:1
	v_cndmask_b32_e64 v140, v139, v138, s[4:5]
	v_cndmask_b32_e64 v141, v138, v139, s[4:5]
	v_pk_mul_f32 v[152:153], v[16:17], v[28:29] op_sel:[1,0] op_sel_hi:[1,1]
	v_pk_mul_f32 v[154:155], v[18:19], v[28:29] op_sel:[0,0] op_sel_hi:[0,1]
	v_add_f32_dpp v142, v141, v140 quad_perm:[2,3,0,1] row_mask:0xf bank_mask:0xf bound_ctrl:1
	v_pk_mul_f32 v[156:157], v[18:19], v[28:29] op_sel:[1,0] op_sel_hi:[1,1]
	v_pk_fma_f32 v[150:151], v[120:121], v[8:9], v[150:151] op_sel:[0,0,0] op_sel_hi:[1,0,1]
	v_add_f32_dpp v142, v142, v142 row_ror:4 row_mask:0xf bank_mask:0xf bound_ctrl:1
	v_pk_fma_f32 v[152:153], v[122:123], v[8:9], v[152:153] op_sel:[0,1,0] op_sel_hi:[1,1,1]
	v_pk_fma_f32 v[154:155], v[124:125], v[10:11], v[154:155] op_sel:[0,0,0] op_sel_hi:[1,0,1]
	v_add_f32_dpp v144, v142, v142 row_ror:8 row_mask:0xf bank_mask:0xf bound_ctrl:1
	v_pk_fma_f32 v[156:157], v[126:127], v[10:11], v[156:157] op_sel:[0,1,0] op_sel_hi:[1,1,1]
	ds_read_b128 v[80:83], v196 offset:10752
	v_mov_b32_dpp v148, v144 quad_perm:[0,0,0,0] row_mask:0xf bank_mask:0xf
	v_mov_b32_dpp v149, v144 quad_perm:[1,1,1,1] row_mask:0xf bank_mask:0xf
	v_pk_fma_f32 v[120:121], v[24:25], v[148:149], v[150:151] op_sel:[0,0,0] op_sel_hi:[0,1,1]
	ds_read_b128 v[84:87], v196 offset:11008
	v_pk_fma_f32 v[122:123], v[24:25], v[148:149], v[152:153] op_sel:[1,0,0] op_sel_hi:[1,1,1]
	ds_read_b128 v[88:91], v196 offset:11264
	v_pk_fma_f32 v[124:125], v[26:27], v[148:149], v[154:155] op_sel:[0,0,0] op_sel_hi:[0,1,1]
	ds_read_b128 v[92:95], v196 offset:11520
	v_pk_fma_f32 v[126:127], v[26:27], v[148:149], v[156:157] op_sel:[1,0,0] op_sel_hi:[1,1,1]
	ds_read_b128 v[96:99], v196 offset:11776
	v_pk_mul_f32 v[132:133], v[120:121], v[44:45] op_sel:[0,0] op_sel_hi:[1,0]
	v_pk_mul_f32 v[128:129], v[120:121], v[12:13] op_sel:[0,0] op_sel_hi:[1,0]
	v_pk_fma_f32 v[132:133], v[122:123], v[44:45], v[132:133] op_sel:[0,1,0] op_sel_hi:[1,1,1]
	v_pk_fma_f32 v[128:129], v[122:123], v[12:13], v[128:129] op_sel:[0,1,0] op_sel_hi:[1,1,1]
	v_pk_fma_f32 v[132:133], v[124:125], v[46:47], v[132:133] op_sel:[0,0,0] op_sel_hi:[1,0,1]
	v_pk_fma_f32 v[128:129], v[124:125], v[14:15], v[128:129] op_sel:[0,0,0] op_sel_hi:[1,0,1]
	v_pk_fma_f32 v[132:133], v[126:127], v[46:47], v[132:133] op_sel:[0,1,0] op_sel_hi:[1,1,1]
	v_pk_fma_f32 v[128:129], v[126:127], v[14:15], v[128:129] op_sel:[0,1,0] op_sel_hi:[1,1,1]
	ds_read_b64 v[100:101], v197 offset:12032
	s_waitcnt lgkmcnt(6)
	v_cndmask_b32_e64 v134, v133, v132, s[2:3]
	v_cndmask_b32_e64 v135, v132, v133, s[2:3]
	v_cndmask_b32_e64 v136, v129, v128, s[2:3]
	v_cndmask_b32_e64 v137, v128, v129, s[2:3]
	v_add_f32_dpp v138, v135, v134 quad_perm:[1,0,3,2] row_mask:0xf bank_mask:0xf bound_ctrl:1
	v_pk_mul_f32 v[150:151], v[40:41], v[52:53] op_sel:[0,0] op_sel_hi:[0,1]
	v_add_f32_dpp v139, v137, v136 quad_perm:[1,0,3,2] row_mask:0xf bank_mask:0xf bound_ctrl:1
	v_cndmask_b32_e64 v140, v139, v138, s[4:5]
	v_cndmask_b32_e64 v141, v138, v139, s[4:5]
	v_pk_mul_f32 v[152:153], v[40:41], v[52:53] op_sel:[1,0] op_sel_hi:[1,1]
	v_pk_mul_f32 v[154:155], v[42:43], v[52:53] op_sel:[0,0] op_sel_hi:[0,1]
	v_add_f32_dpp v142, v141, v140 quad_perm:[2,3,0,1] row_mask:0xf bank_mask:0xf bound_ctrl:1
	v_pk_mul_f32 v[156:157], v[42:43], v[52:53] op_sel:[1,0] op_sel_hi:[1,1]
	v_pk_fma_f32 v[150:151], v[120:121], v[32:33], v[150:151] op_sel:[0,0,0] op_sel_hi:[1,0,1]
	v_add_f32_dpp v142, v142, v142 row_ror:4 row_mask:0xf bank_mask:0xf bound_ctrl:1
	v_pk_fma_f32 v[152:153], v[122:123], v[32:33], v[152:153] op_sel:[0,1,0] op_sel_hi:[1,1,1]
	v_pk_fma_f32 v[154:155], v[124:125], v[34:35], v[154:155] op_sel:[0,0,0] op_sel_hi:[1,0,1]
	v_add_f32_dpp v145, v142, v142 row_ror:8 row_mask:0xf bank_mask:0xf bound_ctrl:1
	v_pk_fma_f32 v[156:157], v[126:127], v[34:35], v[156:157] op_sel:[0,1,0] op_sel_hi:[1,1,1]
	ds_read_b128 v[8:11], v196 offset:12288
	v_mov_b32_dpp v148, v145 quad_perm:[0,0,0,0] row_mask:0xf bank_mask:0xf
	v_mov_b32_dpp v149, v145 quad_perm:[1,1,1,1] row_mask:0xf bank_mask:0xf
	v_pk_fma_f32 v[120:121], v[48:49], v[148:149], v[150:151] op_sel:[0,0,0] op_sel_hi:[0,1,1]
	ds_read_b128 v[12:15], v196 offset:12544
	v_pk_fma_f32 v[122:123], v[48:49], v[148:149], v[152:153] op_sel:[1,0,0] op_sel_hi:[1,1,1]
	ds_read_b128 v[16:19], v196 offset:12800
	v_pk_fma_f32 v[124:125], v[50:51], v[148:149], v[154:155] op_sel:[0,0,0] op_sel_hi:[0,1,1]
	ds_read_b128 v[20:23], v196 offset:13056
	v_pk_fma_f32 v[126:127], v[50:51], v[148:149], v[156:157] op_sel:[1,0,0] op_sel_hi:[1,1,1]
	ds_read_b128 v[24:27], v196 offset:13312
	v_pk_mul_f32 v[132:133], v[120:121], v[68:69] op_sel:[0,0] op_sel_hi:[1,0]
	v_pk_mul_f32 v[128:129], v[120:121], v[36:37] op_sel:[0,0] op_sel_hi:[1,0]
	v_pk_fma_f32 v[132:133], v[122:123], v[68:69], v[132:133] op_sel:[0,1,0] op_sel_hi:[1,1,1]
	v_pk_fma_f32 v[128:129], v[122:123], v[36:37], v[128:129] op_sel:[0,1,0] op_sel_hi:[1,1,1]
	v_pk_fma_f32 v[132:133], v[124:125], v[70:71], v[132:133] op_sel:[0,0,0] op_sel_hi:[1,0,1]
	v_pk_fma_f32 v[128:129], v[124:125], v[38:39], v[128:129] op_sel:[0,0,0] op_sel_hi:[1,0,1]
	v_pk_fma_f32 v[132:133], v[126:127], v[70:71], v[132:133] op_sel:[0,1,0] op_sel_hi:[1,1,1]
	v_pk_fma_f32 v[128:129], v[126:127], v[38:39], v[128:129] op_sel:[0,1,0] op_sel_hi:[1,1,1]
	ds_read_b64 v[28:29], v197 offset:13568
	s_waitcnt lgkmcnt(6)
	v_cndmask_b32_e64 v134, v133, v132, s[2:3]
	v_cndmask_b32_e64 v135, v132, v133, s[2:3]
	v_cndmask_b32_e64 v136, v129, v128, s[2:3]
	v_cndmask_b32_e64 v137, v128, v129, s[2:3]
	v_add_f32_dpp v138, v135, v134 quad_perm:[1,0,3,2] row_mask:0xf bank_mask:0xf bound_ctrl:1
	v_pk_mul_f32 v[150:151], v[64:65], v[76:77] op_sel:[0,0] op_sel_hi:[0,1]
	v_add_f32_dpp v139, v137, v136 quad_perm:[1,0,3,2] row_mask:0xf bank_mask:0xf bound_ctrl:1
	v_cndmask_b32_e64 v140, v139, v138, s[4:5]
	v_cndmask_b32_e64 v141, v138, v139, s[4:5]
	v_pk_mul_f32 v[152:153], v[64:65], v[76:77] op_sel:[1,0] op_sel_hi:[1,1]
	v_pk_mul_f32 v[154:155], v[66:67], v[76:77] op_sel:[0,0] op_sel_hi:[0,1]
	v_add_f32_dpp v142, v141, v140 quad_perm:[2,3,0,1] row_mask:0xf bank_mask:0xf bound_ctrl:1
	v_pk_mul_f32 v[156:157], v[66:67], v[76:77] op_sel:[1,0] op_sel_hi:[1,1]
	v_pk_fma_f32 v[150:151], v[120:121], v[56:57], v[150:151] op_sel:[0,0,0] op_sel_hi:[1,0,1]
	v_add_f32_dpp v142, v142, v142 row_ror:4 row_mask:0xf bank_mask:0xf bound_ctrl:1
	v_pk_fma_f32 v[152:153], v[122:123], v[56:57], v[152:153] op_sel:[0,1,0] op_sel_hi:[1,1,1]
	v_pk_fma_f32 v[154:155], v[124:125], v[58:59], v[154:155] op_sel:[0,0,0] op_sel_hi:[1,0,1]
	v_add_f32_dpp v146, v142, v142 row_ror:8 row_mask:0xf bank_mask:0xf bound_ctrl:1
	v_pk_fma_f32 v[156:157], v[126:127], v[58:59], v[156:157] op_sel:[0,1,0] op_sel_hi:[1,1,1]
	ds_read_b128 v[32:35], v196 offset:13824
	v_mov_b32_dpp v148, v146 quad_perm:[0,0,0,0] row_mask:0xf bank_mask:0xf
	v_mov_b32_dpp v149, v146 quad_perm:[1,1,1,1] row_mask:0xf bank_mask:0xf
	v_pk_fma_f32 v[120:121], v[72:73], v[148:149], v[150:151] op_sel:[0,0,0] op_sel_hi:[0,1,1]
	ds_read_b128 v[36:39], v196 offset:14080
	v_pk_fma_f32 v[122:123], v[72:73], v[148:149], v[152:153] op_sel:[1,0,0] op_sel_hi:[1,1,1]
	ds_read_b128 v[40:43], v196 offset:14336
	v_pk_fma_f32 v[124:125], v[74:75], v[148:149], v[154:155] op_sel:[0,0,0] op_sel_hi:[0,1,1]
	ds_read_b128 v[44:47], v196 offset:14592
	v_pk_fma_f32 v[126:127], v[74:75], v[148:149], v[156:157] op_sel:[1,0,0] op_sel_hi:[1,1,1]
	ds_read_b128 v[48:51], v196 offset:14848
	v_pk_mul_f32 v[132:133], v[120:121], v[92:93] op_sel:[0,0] op_sel_hi:[1,0]
	v_pk_mul_f32 v[128:129], v[120:121], v[60:61] op_sel:[0,0] op_sel_hi:[1,0]
	v_pk_fma_f32 v[132:133], v[122:123], v[92:93], v[132:133] op_sel:[0,1,0] op_sel_hi:[1,1,1]
	v_pk_fma_f32 v[128:129], v[122:123], v[60:61], v[128:129] op_sel:[0,1,0] op_sel_hi:[1,1,1]
	v_pk_fma_f32 v[132:133], v[124:125], v[94:95], v[132:133] op_sel:[0,0,0] op_sel_hi:[1,0,1]
	v_pk_fma_f32 v[128:129], v[124:125], v[62:63], v[128:129] op_sel:[0,0,0] op_sel_hi:[1,0,1]
	v_pk_fma_f32 v[132:133], v[126:127], v[94:95], v[132:133] op_sel:[0,1,0] op_sel_hi:[1,1,1]
	v_pk_fma_f32 v[128:129], v[126:127], v[62:63], v[128:129] op_sel:[0,1,0] op_sel_hi:[1,1,1]
	ds_read_b64 v[52:53], v197 offset:15104
	s_waitcnt lgkmcnt(6)
	v_cndmask_b32_e64 v134, v133, v132, s[2:3]
	v_cndmask_b32_e64 v135, v132, v133, s[2:3]
	v_cndmask_b32_e64 v136, v129, v128, s[2:3]
	v_cndmask_b32_e64 v137, v128, v129, s[2:3]
	v_add_f32_dpp v138, v135, v134 quad_perm:[1,0,3,2] row_mask:0xf bank_mask:0xf bound_ctrl:1
	v_pk_mul_f32 v[150:151], v[88:89], v[100:101] op_sel:[0,0] op_sel_hi:[0,1]
	v_add_f32_dpp v139, v137, v136 quad_perm:[1,0,3,2] row_mask:0xf bank_mask:0xf bound_ctrl:1
	v_cndmask_b32_e64 v140, v139, v138, s[4:5]
	v_cndmask_b32_e64 v141, v138, v139, s[4:5]
	v_pk_mul_f32 v[152:153], v[88:89], v[100:101] op_sel:[1,0] op_sel_hi:[1,1]
	v_pk_mul_f32 v[154:155], v[90:91], v[100:101] op_sel:[0,0] op_sel_hi:[0,1]
	v_add_f32_dpp v142, v141, v140 quad_perm:[2,3,0,1] row_mask:0xf bank_mask:0xf bound_ctrl:1
	v_pk_mul_f32 v[156:157], v[90:91], v[100:101] op_sel:[1,0] op_sel_hi:[1,1]
	v_pk_fma_f32 v[150:151], v[120:121], v[80:81], v[150:151] op_sel:[0,0,0] op_sel_hi:[1,0,1]
	v_add_f32_dpp v142, v142, v142 row_ror:4 row_mask:0xf bank_mask:0xf bound_ctrl:1
	v_pk_fma_f32 v[152:153], v[122:123], v[80:81], v[152:153] op_sel:[0,1,0] op_sel_hi:[1,1,1]
	v_pk_fma_f32 v[154:155], v[124:125], v[82:83], v[154:155] op_sel:[0,0,0] op_sel_hi:[1,0,1]
	v_add_f32_dpp v147, v142, v142 row_ror:8 row_mask:0xf bank_mask:0xf bound_ctrl:1
	v_pk_fma_f32 v[156:157], v[126:127], v[82:83], v[156:157] op_sel:[0,1,0] op_sel_hi:[1,1,1]
	ds_read_b128 v[56:59], v196 offset:15360
	v_mov_b32_dpp v148, v147 quad_perm:[0,0,0,0] row_mask:0xf bank_mask:0xf
	v_mov_b32_dpp v149, v147 quad_perm:[1,1,1,1] row_mask:0xf bank_mask:0xf
	v_pk_fma_f32 v[120:121], v[96:97], v[148:149], v[150:151] op_sel:[0,0,0] op_sel_hi:[0,1,1]
	ds_read_b128 v[60:63], v196 offset:15616
	v_pk_fma_f32 v[122:123], v[96:97], v[148:149], v[152:153] op_sel:[1,0,0] op_sel_hi:[1,1,1]
	ds_read_b128 v[64:67], v196 offset:15872
	v_pk_fma_f32 v[124:125], v[98:99], v[148:149], v[154:155] op_sel:[0,0,0] op_sel_hi:[0,1,1]
	ds_read_b128 v[68:71], v196 offset:16128
	v_pk_fma_f32 v[126:127], v[98:99], v[148:149], v[156:157] op_sel:[1,0,0] op_sel_hi:[1,1,1]
	ds_read_b128 v[72:75], v196 offset:16384
	v_pk_mul_f32 v[132:133], v[120:121], v[20:21] op_sel:[0,0] op_sel_hi:[1,0]
	v_pk_mul_f32 v[128:129], v[120:121], v[84:85] op_sel:[0,0] op_sel_hi:[1,0]
	v_pk_fma_f32 v[132:133], v[122:123], v[20:21], v[132:133] op_sel:[0,1,0] op_sel_hi:[1,1,1]
	v_pk_fma_f32 v[128:129], v[122:123], v[84:85], v[128:129] op_sel:[0,1,0] op_sel_hi:[1,1,1]
	v_pk_fma_f32 v[132:133], v[124:125], v[22:23], v[132:133] op_sel:[0,0,0] op_sel_hi:[1,0,1]
	v_pk_fma_f32 v[128:129], v[124:125], v[86:87], v[128:129] op_sel:[0,0,0] op_sel_hi:[1,0,1]
	v_pk_fma_f32 v[132:133], v[126:127], v[22:23], v[132:133] op_sel:[0,1,0] op_sel_hi:[1,1,1]
	v_pk_fma_f32 v[128:129], v[126:127], v[86:87], v[128:129] op_sel:[0,1,0] op_sel_hi:[1,1,1]
	ds_read_b64 v[76:77], v197 offset:16640
	v_cndmask_b32_e64 v106, v147, v146, s[12:13]
	v_cndmask_b32_e64 v106, v106, v145, s[10:11]
	v_cndmask_b32_e64 v106, v106, v144, s[6:7]
	s_and_saveexec_b64 s[28:29], s[8:9]
	global_store_dword v[104:105], v106, off
	s_mov_b64 exec, s[28:29]
	v_lshl_add_u64 v[104:105], v[104:105], 0, s[26:27]
	s_waitcnt lgkmcnt(6)
	v_cndmask_b32_e64 v134, v133, v132, s[2:3]
	v_cndmask_b32_e64 v135, v132, v133, s[2:3]
	v_cndmask_b32_e64 v136, v129, v128, s[2:3]
	v_cndmask_b32_e64 v137, v128, v129, s[2:3]
	v_add_f32_dpp v138, v135, v134 quad_perm:[1,0,3,2] row_mask:0xf bank_mask:0xf bound_ctrl:1
	v_pk_mul_f32 v[150:151], v[16:17], v[28:29] op_sel:[0,0] op_sel_hi:[0,1]
	v_add_f32_dpp v139, v137, v136 quad_perm:[1,0,3,2] row_mask:0xf bank_mask:0xf bound_ctrl:1
	v_cndmask_b32_e64 v140, v139, v138, s[4:5]
	v_cndmask_b32_e64 v141, v138, v139, s[4:5]
	v_pk_mul_f32 v[152:153], v[16:17], v[28:29] op_sel:[1,0] op_sel_hi:[1,1]
	v_pk_mul_f32 v[154:155], v[18:19], v[28:29] op_sel:[0,0] op_sel_hi:[0,1]
	v_add_f32_dpp v142, v141, v140 quad_perm:[2,3,0,1] row_mask:0xf bank_mask:0xf bound_ctrl:1
	v_pk_mul_f32 v[156:157], v[18:19], v[28:29] op_sel:[1,0] op_sel_hi:[1,1]
	v_pk_fma_f32 v[150:151], v[120:121], v[8:9], v[150:151] op_sel:[0,0,0] op_sel_hi:[1,0,1]
	v_add_f32_dpp v142, v142, v142 row_ror:4 row_mask:0xf bank_mask:0xf bound_ctrl:1
	v_pk_fma_f32 v[152:153], v[122:123], v[8:9], v[152:153] op_sel:[0,1,0] op_sel_hi:[1,1,1]
	v_pk_fma_f32 v[154:155], v[124:125], v[10:11], v[154:155] op_sel:[0,0,0] op_sel_hi:[1,0,1]
	v_add_f32_dpp v144, v142, v142 row_ror:8 row_mask:0xf bank_mask:0xf bound_ctrl:1
	v_pk_fma_f32 v[156:157], v[126:127], v[10:11], v[156:157] op_sel:[0,1,0] op_sel_hi:[1,1,1]
	ds_read_b128 v[80:83], v196 offset:16896
	v_mov_b32_dpp v148, v144 quad_perm:[0,0,0,0] row_mask:0xf bank_mask:0xf
	v_mov_b32_dpp v149, v144 quad_perm:[1,1,1,1] row_mask:0xf bank_mask:0xf
	v_pk_fma_f32 v[120:121], v[24:25], v[148:149], v[150:151] op_sel:[0,0,0] op_sel_hi:[0,1,1]
	ds_read_b128 v[84:87], v196 offset:17152
	v_pk_fma_f32 v[122:123], v[24:25], v[148:149], v[152:153] op_sel:[1,0,0] op_sel_hi:[1,1,1]
	ds_read_b128 v[88:91], v196 offset:17408
	v_pk_fma_f32 v[124:125], v[26:27], v[148:149], v[154:155] op_sel:[0,0,0] op_sel_hi:[0,1,1]
	ds_read_b128 v[92:95], v196 offset:17664
	v_pk_fma_f32 v[126:127], v[26:27], v[148:149], v[156:157] op_sel:[1,0,0] op_sel_hi:[1,1,1]
	ds_read_b128 v[96:99], v196 offset:17920
	v_pk_mul_f32 v[132:133], v[120:121], v[44:45] op_sel:[0,0] op_sel_hi:[1,0]
	v_pk_mul_f32 v[128:129], v[120:121], v[12:13] op_sel:[0,0] op_sel_hi:[1,0]
	v_pk_fma_f32 v[132:133], v[122:123], v[44:45], v[132:133] op_sel:[0,1,0] op_sel_hi:[1,1,1]
	v_pk_fma_f32 v[128:129], v[122:123], v[12:13], v[128:129] op_sel:[0,1,0] op_sel_hi:[1,1,1]
	v_pk_fma_f32 v[132:133], v[124:125], v[46:47], v[132:133] op_sel:[0,0,0] op_sel_hi:[1,0,1]
	v_pk_fma_f32 v[128:129], v[124:125], v[14:15], v[128:129] op_sel:[0,0,0] op_sel_hi:[1,0,1]
	v_pk_fma_f32 v[132:133], v[126:127], v[46:47], v[132:133] op_sel:[0,1,0] op_sel_hi:[1,1,1]
	v_pk_fma_f32 v[128:129], v[126:127], v[14:15], v[128:129] op_sel:[0,1,0] op_sel_hi:[1,1,1]
	ds_read_b64 v[100:101], v197 offset:18176
	s_waitcnt lgkmcnt(6)
	v_cndmask_b32_e64 v134, v133, v132, s[2:3]
	v_cndmask_b32_e64 v135, v132, v133, s[2:3]
	v_cndmask_b32_e64 v136, v129, v128, s[2:3]
	v_cndmask_b32_e64 v137, v128, v129, s[2:3]
	v_add_f32_dpp v138, v135, v134 quad_perm:[1,0,3,2] row_mask:0xf bank_mask:0xf bound_ctrl:1
	v_pk_mul_f32 v[150:151], v[40:41], v[52:53] op_sel:[0,0] op_sel_hi:[0,1]
	v_add_f32_dpp v139, v137, v136 quad_perm:[1,0,3,2] row_mask:0xf bank_mask:0xf bound_ctrl:1
	v_cndmask_b32_e64 v140, v139, v138, s[4:5]
	v_cndmask_b32_e64 v141, v138, v139, s[4:5]
	v_pk_mul_f32 v[152:153], v[40:41], v[52:53] op_sel:[1,0] op_sel_hi:[1,1]
	v_pk_mul_f32 v[154:155], v[42:43], v[52:53] op_sel:[0,0] op_sel_hi:[0,1]
	v_add_f32_dpp v142, v141, v140 quad_perm:[2,3,0,1] row_mask:0xf bank_mask:0xf bound_ctrl:1
	v_pk_mul_f32 v[156:157], v[42:43], v[52:53] op_sel:[1,0] op_sel_hi:[1,1]
	v_pk_fma_f32 v[150:151], v[120:121], v[32:33], v[150:151] op_sel:[0,0,0] op_sel_hi:[1,0,1]
	v_add_f32_dpp v142, v142, v142 row_ror:4 row_mask:0xf bank_mask:0xf bound_ctrl:1
	v_pk_fma_f32 v[152:153], v[122:123], v[32:33], v[152:153] op_sel:[0,1,0] op_sel_hi:[1,1,1]
	v_pk_fma_f32 v[154:155], v[124:125], v[34:35], v[154:155] op_sel:[0,0,0] op_sel_hi:[1,0,1]
	v_add_f32_dpp v145, v142, v142 row_ror:8 row_mask:0xf bank_mask:0xf bound_ctrl:1
	v_pk_fma_f32 v[156:157], v[126:127], v[34:35], v[156:157] op_sel:[0,1,0] op_sel_hi:[1,1,1]
	ds_read_b128 v[8:11], v196 offset:18432
	v_mov_b32_dpp v148, v145 quad_perm:[0,0,0,0] row_mask:0xf bank_mask:0xf
	v_mov_b32_dpp v149, v145 quad_perm:[1,1,1,1] row_mask:0xf bank_mask:0xf
	v_pk_fma_f32 v[120:121], v[48:49], v[148:149], v[150:151] op_sel:[0,0,0] op_sel_hi:[0,1,1]
	ds_read_b128 v[12:15], v196 offset:18688
	v_pk_fma_f32 v[122:123], v[48:49], v[148:149], v[152:153] op_sel:[1,0,0] op_sel_hi:[1,1,1]
	ds_read_b128 v[16:19], v196 offset:18944
	v_pk_fma_f32 v[124:125], v[50:51], v[148:149], v[154:155] op_sel:[0,0,0] op_sel_hi:[0,1,1]
	ds_read_b128 v[20:23], v196 offset:19200
	v_pk_fma_f32 v[126:127], v[50:51], v[148:149], v[156:157] op_sel:[1,0,0] op_sel_hi:[1,1,1]
	ds_read_b128 v[24:27], v196 offset:19456
	v_pk_mul_f32 v[132:133], v[120:121], v[68:69] op_sel:[0,0] op_sel_hi:[1,0]
	v_pk_mul_f32 v[128:129], v[120:121], v[36:37] op_sel:[0,0] op_sel_hi:[1,0]
	v_pk_fma_f32 v[132:133], v[122:123], v[68:69], v[132:133] op_sel:[0,1,0] op_sel_hi:[1,1,1]
	v_pk_fma_f32 v[128:129], v[122:123], v[36:37], v[128:129] op_sel:[0,1,0] op_sel_hi:[1,1,1]
	v_pk_fma_f32 v[132:133], v[124:125], v[70:71], v[132:133] op_sel:[0,0,0] op_sel_hi:[1,0,1]
	v_pk_fma_f32 v[128:129], v[124:125], v[38:39], v[128:129] op_sel:[0,0,0] op_sel_hi:[1,0,1]
	v_pk_fma_f32 v[132:133], v[126:127], v[70:71], v[132:133] op_sel:[0,1,0] op_sel_hi:[1,1,1]
	v_pk_fma_f32 v[128:129], v[126:127], v[38:39], v[128:129] op_sel:[0,1,0] op_sel_hi:[1,1,1]
	ds_read_b64 v[28:29], v197 offset:19712
	s_waitcnt lgkmcnt(6)
	v_cndmask_b32_e64 v134, v133, v132, s[2:3]
	v_cndmask_b32_e64 v135, v132, v133, s[2:3]
	v_cndmask_b32_e64 v136, v129, v128, s[2:3]
	v_cndmask_b32_e64 v137, v128, v129, s[2:3]
	v_add_f32_dpp v138, v135, v134 quad_perm:[1,0,3,2] row_mask:0xf bank_mask:0xf bound_ctrl:1
	v_pk_mul_f32 v[150:151], v[64:65], v[76:77] op_sel:[0,0] op_sel_hi:[0,1]
	v_add_f32_dpp v139, v137, v136 quad_perm:[1,0,3,2] row_mask:0xf bank_mask:0xf bound_ctrl:1
	v_cndmask_b32_e64 v140, v139, v138, s[4:5]
	v_cndmask_b32_e64 v141, v138, v139, s[4:5]
	v_pk_mul_f32 v[152:153], v[64:65], v[76:77] op_sel:[1,0] op_sel_hi:[1,1]
	v_pk_mul_f32 v[154:155], v[66:67], v[76:77] op_sel:[0,0] op_sel_hi:[0,1]
	v_add_f32_dpp v142, v141, v140 quad_perm:[2,3,0,1] row_mask:0xf bank_mask:0xf bound_ctrl:1
	v_pk_mul_f32 v[156:157], v[66:67], v[76:77] op_sel:[1,0] op_sel_hi:[1,1]
	v_pk_fma_f32 v[150:151], v[120:121], v[56:57], v[150:151] op_sel:[0,0,0] op_sel_hi:[1,0,1]
	v_add_f32_dpp v142, v142, v142 row_ror:4 row_mask:0xf bank_mask:0xf bound_ctrl:1
	v_pk_fma_f32 v[152:153], v[122:123], v[56:57], v[152:153] op_sel:[0,1,0] op_sel_hi:[1,1,1]
	v_pk_fma_f32 v[154:155], v[124:125], v[58:59], v[154:155] op_sel:[0,0,0] op_sel_hi:[1,0,1]
	v_add_f32_dpp v146, v142, v142 row_ror:8 row_mask:0xf bank_mask:0xf bound_ctrl:1
	v_pk_fma_f32 v[156:157], v[126:127], v[58:59], v[156:157] op_sel:[0,1,0] op_sel_hi:[1,1,1]
	ds_read_b128 v[32:35], v196 offset:19968
	v_mov_b32_dpp v148, v146 quad_perm:[0,0,0,0] row_mask:0xf bank_mask:0xf
	v_mov_b32_dpp v149, v146 quad_perm:[1,1,1,1] row_mask:0xf bank_mask:0xf
	v_pk_fma_f32 v[120:121], v[72:73], v[148:149], v[150:151] op_sel:[0,0,0] op_sel_hi:[0,1,1]
	ds_read_b128 v[36:39], v196 offset:20224
	v_pk_fma_f32 v[122:123], v[72:73], v[148:149], v[152:153] op_sel:[1,0,0] op_sel_hi:[1,1,1]
	ds_read_b128 v[40:43], v196 offset:20480
	v_pk_fma_f32 v[124:125], v[74:75], v[148:149], v[154:155] op_sel:[0,0,0] op_sel_hi:[0,1,1]
	ds_read_b128 v[44:47], v196 offset:20736
	v_pk_fma_f32 v[126:127], v[74:75], v[148:149], v[156:157] op_sel:[1,0,0] op_sel_hi:[1,1,1]
	ds_read_b128 v[48:51], v196 offset:20992
	v_pk_mul_f32 v[132:133], v[120:121], v[92:93] op_sel:[0,0] op_sel_hi:[1,0]
	v_pk_mul_f32 v[128:129], v[120:121], v[60:61] op_sel:[0,0] op_sel_hi:[1,0]
	v_pk_fma_f32 v[132:133], v[122:123], v[92:93], v[132:133] op_sel:[0,1,0] op_sel_hi:[1,1,1]
	v_pk_fma_f32 v[128:129], v[122:123], v[60:61], v[128:129] op_sel:[0,1,0] op_sel_hi:[1,1,1]
	v_pk_fma_f32 v[132:133], v[124:125], v[94:95], v[132:133] op_sel:[0,0,0] op_sel_hi:[1,0,1]
	v_pk_fma_f32 v[128:129], v[124:125], v[62:63], v[128:129] op_sel:[0,0,0] op_sel_hi:[1,0,1]
	v_pk_fma_f32 v[132:133], v[126:127], v[94:95], v[132:133] op_sel:[0,1,0] op_sel_hi:[1,1,1]
	v_pk_fma_f32 v[128:129], v[126:127], v[62:63], v[128:129] op_sel:[0,1,0] op_sel_hi:[1,1,1]
	ds_read_b64 v[52:53], v197 offset:21248
	s_waitcnt lgkmcnt(6)
	v_cndmask_b32_e64 v134, v133, v132, s[2:3]
	v_cndmask_b32_e64 v135, v132, v133, s[2:3]
	v_cndmask_b32_e64 v136, v129, v128, s[2:3]
	v_cndmask_b32_e64 v137, v128, v129, s[2:3]
	v_add_f32_dpp v138, v135, v134 quad_perm:[1,0,3,2] row_mask:0xf bank_mask:0xf bound_ctrl:1
	v_pk_mul_f32 v[150:151], v[88:89], v[100:101] op_sel:[0,0] op_sel_hi:[0,1]
	v_add_f32_dpp v139, v137, v136 quad_perm:[1,0,3,2] row_mask:0xf bank_mask:0xf bound_ctrl:1
	v_cndmask_b32_e64 v140, v139, v138, s[4:5]
	v_cndmask_b32_e64 v141, v138, v139, s[4:5]
	v_pk_mul_f32 v[152:153], v[88:89], v[100:101] op_sel:[1,0] op_sel_hi:[1,1]
	v_pk_mul_f32 v[154:155], v[90:91], v[100:101] op_sel:[0,0] op_sel_hi:[0,1]
	v_add_f32_dpp v142, v141, v140 quad_perm:[2,3,0,1] row_mask:0xf bank_mask:0xf bound_ctrl:1
	v_pk_mul_f32 v[156:157], v[90:91], v[100:101] op_sel:[1,0] op_sel_hi:[1,1]
	v_pk_fma_f32 v[150:151], v[120:121], v[80:81], v[150:151] op_sel:[0,0,0] op_sel_hi:[1,0,1]
	v_add_f32_dpp v142, v142, v142 row_ror:4 row_mask:0xf bank_mask:0xf bound_ctrl:1
	v_pk_fma_f32 v[152:153], v[122:123], v[80:81], v[152:153] op_sel:[0,1,0] op_sel_hi:[1,1,1]
	v_pk_fma_f32 v[154:155], v[124:125], v[82:83], v[154:155] op_sel:[0,0,0] op_sel_hi:[1,0,1]
	v_add_f32_dpp v147, v142, v142 row_ror:8 row_mask:0xf bank_mask:0xf bound_ctrl:1
	v_pk_fma_f32 v[156:157], v[126:127], v[82:83], v[156:157] op_sel:[0,1,0] op_sel_hi:[1,1,1]
	ds_read_b128 v[56:59], v196 offset:21504
	v_mov_b32_dpp v148, v147 quad_perm:[0,0,0,0] row_mask:0xf bank_mask:0xf
	v_mov_b32_dpp v149, v147 quad_perm:[1,1,1,1] row_mask:0xf bank_mask:0xf
	v_pk_fma_f32 v[120:121], v[96:97], v[148:149], v[150:151] op_sel:[0,0,0] op_sel_hi:[0,1,1]
	ds_read_b128 v[60:63], v196 offset:21760
	v_pk_fma_f32 v[122:123], v[96:97], v[148:149], v[152:153] op_sel:[1,0,0] op_sel_hi:[1,1,1]
	ds_read_b128 v[64:67], v196 offset:22016
	v_pk_fma_f32 v[124:125], v[98:99], v[148:149], v[154:155] op_sel:[0,0,0] op_sel_hi:[0,1,1]
	ds_read_b128 v[68:71], v196 offset:22272
	v_pk_fma_f32 v[126:127], v[98:99], v[148:149], v[156:157] op_sel:[1,0,0] op_sel_hi:[1,1,1]
	ds_read_b128 v[72:75], v196 offset:22528
	v_pk_mul_f32 v[132:133], v[120:121], v[20:21] op_sel:[0,0] op_sel_hi:[1,0]
	v_pk_mul_f32 v[128:129], v[120:121], v[84:85] op_sel:[0,0] op_sel_hi:[1,0]
	v_pk_fma_f32 v[132:133], v[122:123], v[20:21], v[132:133] op_sel:[0,1,0] op_sel_hi:[1,1,1]
	v_pk_fma_f32 v[128:129], v[122:123], v[84:85], v[128:129] op_sel:[0,1,0] op_sel_hi:[1,1,1]
	v_pk_fma_f32 v[132:133], v[124:125], v[22:23], v[132:133] op_sel:[0,0,0] op_sel_hi:[1,0,1]
	v_pk_fma_f32 v[128:129], v[124:125], v[86:87], v[128:129] op_sel:[0,0,0] op_sel_hi:[1,0,1]
	v_pk_fma_f32 v[132:133], v[126:127], v[22:23], v[132:133] op_sel:[0,1,0] op_sel_hi:[1,1,1]
	v_pk_fma_f32 v[128:129], v[126:127], v[86:87], v[128:129] op_sel:[0,1,0] op_sel_hi:[1,1,1]
	ds_read_b64 v[76:77], v197 offset:22784
	v_cndmask_b32_e64 v106, v147, v146, s[12:13]
	v_cndmask_b32_e64 v106, v106, v145, s[10:11]
	v_cndmask_b32_e64 v106, v106, v144, s[6:7]
	s_and_saveexec_b64 s[28:29], s[8:9]
	global_store_dword v[104:105], v106, off
	s_mov_b64 exec, s[28:29]
	v_lshl_add_u64 v[104:105], v[104:105], 0, s[26:27]
	s_waitcnt lgkmcnt(6)
	v_cndmask_b32_e64 v134, v133, v132, s[2:3]
	v_cndmask_b32_e64 v135, v132, v133, s[2:3]
	v_cndmask_b32_e64 v136, v129, v128, s[2:3]
	v_cndmask_b32_e64 v137, v128, v129, s[2:3]
	v_add_f32_dpp v138, v135, v134 quad_perm:[1,0,3,2] row_mask:0xf bank_mask:0xf bound_ctrl:1
	v_pk_mul_f32 v[150:151], v[16:17], v[28:29] op_sel:[0,0] op_sel_hi:[0,1]
	v_add_f32_dpp v139, v137, v136 quad_perm:[1,0,3,2] row_mask:0xf bank_mask:0xf bound_ctrl:1
	v_cndmask_b32_e64 v140, v139, v138, s[4:5]
	v_cndmask_b32_e64 v141, v138, v139, s[4:5]
	v_pk_mul_f32 v[152:153], v[16:17], v[28:29] op_sel:[1,0] op_sel_hi:[1,1]
	v_pk_mul_f32 v[154:155], v[18:19], v[28:29] op_sel:[0,0] op_sel_hi:[0,1]
	v_add_f32_dpp v142, v141, v140 quad_perm:[2,3,0,1] row_mask:0xf bank_mask:0xf bound_ctrl:1
	v_pk_mul_f32 v[156:157], v[18:19], v[28:29] op_sel:[1,0] op_sel_hi:[1,1]
	v_pk_fma_f32 v[150:151], v[120:121], v[8:9], v[150:151] op_sel:[0,0,0] op_sel_hi:[1,0,1]
	v_add_f32_dpp v142, v142, v142 row_ror:4 row_mask:0xf bank_mask:0xf bound_ctrl:1
	v_pk_fma_f32 v[152:153], v[122:123], v[8:9], v[152:153] op_sel:[0,1,0] op_sel_hi:[1,1,1]
	v_pk_fma_f32 v[154:155], v[124:125], v[10:11], v[154:155] op_sel:[0,0,0] op_sel_hi:[1,0,1]
	v_add_f32_dpp v144, v142, v142 row_ror:8 row_mask:0xf bank_mask:0xf bound_ctrl:1
	v_pk_fma_f32 v[156:157], v[126:127], v[10:11], v[156:157] op_sel:[0,1,0] op_sel_hi:[1,1,1]
	ds_read_b128 v[80:83], v196 offset:23040
	v_mov_b32_dpp v148, v144 quad_perm:[0,0,0,0] row_mask:0xf bank_mask:0xf
	v_mov_b32_dpp v149, v144 quad_perm:[1,1,1,1] row_mask:0xf bank_mask:0xf
	v_pk_fma_f32 v[120:121], v[24:25], v[148:149], v[150:151] op_sel:[0,0,0] op_sel_hi:[0,1,1]
	ds_read_b128 v[84:87], v196 offset:23296
	v_pk_fma_f32 v[122:123], v[24:25], v[148:149], v[152:153] op_sel:[1,0,0] op_sel_hi:[1,1,1]
	ds_read_b128 v[88:91], v196 offset:23552
	v_pk_fma_f32 v[124:125], v[26:27], v[148:149], v[154:155] op_sel:[0,0,0] op_sel_hi:[0,1,1]
	ds_read_b128 v[92:95], v196 offset:23808
	v_pk_fma_f32 v[126:127], v[26:27], v[148:149], v[156:157] op_sel:[1,0,0] op_sel_hi:[1,1,1]
	ds_read_b128 v[96:99], v196 offset:24064
	v_pk_mul_f32 v[132:133], v[120:121], v[44:45] op_sel:[0,0] op_sel_hi:[1,0]
	v_pk_mul_f32 v[128:129], v[120:121], v[12:13] op_sel:[0,0] op_sel_hi:[1,0]
	v_pk_fma_f32 v[132:133], v[122:123], v[44:45], v[132:133] op_sel:[0,1,0] op_sel_hi:[1,1,1]
	v_pk_fma_f32 v[128:129], v[122:123], v[12:13], v[128:129] op_sel:[0,1,0] op_sel_hi:[1,1,1]
	v_pk_fma_f32 v[132:133], v[124:125], v[46:47], v[132:133] op_sel:[0,0,0] op_sel_hi:[1,0,1]
	v_pk_fma_f32 v[128:129], v[124:125], v[14:15], v[128:129] op_sel:[0,0,0] op_sel_hi:[1,0,1]
	v_pk_fma_f32 v[132:133], v[126:127], v[46:47], v[132:133] op_sel:[0,1,0] op_sel_hi:[1,1,1]
	v_pk_fma_f32 v[128:129], v[126:127], v[14:15], v[128:129] op_sel:[0,1,0] op_sel_hi:[1,1,1]
	ds_read_b64 v[100:101], v197 offset:24320
	s_waitcnt lgkmcnt(6)
	v_cndmask_b32_e64 v134, v133, v132, s[2:3]
	v_cndmask_b32_e64 v135, v132, v133, s[2:3]
	v_cndmask_b32_e64 v136, v129, v128, s[2:3]
	v_cndmask_b32_e64 v137, v128, v129, s[2:3]
	v_add_f32_dpp v138, v135, v134 quad_perm:[1,0,3,2] row_mask:0xf bank_mask:0xf bound_ctrl:1
	v_pk_mul_f32 v[150:151], v[40:41], v[52:53] op_sel:[0,0] op_sel_hi:[0,1]
	v_add_f32_dpp v139, v137, v136 quad_perm:[1,0,3,2] row_mask:0xf bank_mask:0xf bound_ctrl:1
	v_cndmask_b32_e64 v140, v139, v138, s[4:5]
	v_cndmask_b32_e64 v141, v138, v139, s[4:5]
	v_pk_mul_f32 v[152:153], v[40:41], v[52:53] op_sel:[1,0] op_sel_hi:[1,1]
	v_pk_mul_f32 v[154:155], v[42:43], v[52:53] op_sel:[0,0] op_sel_hi:[0,1]
	v_add_f32_dpp v142, v141, v140 quad_perm:[2,3,0,1] row_mask:0xf bank_mask:0xf bound_ctrl:1
	v_pk_mul_f32 v[156:157], v[42:43], v[52:53] op_sel:[1,0] op_sel_hi:[1,1]
	v_pk_fma_f32 v[150:151], v[120:121], v[32:33], v[150:151] op_sel:[0,0,0] op_sel_hi:[1,0,1]
	v_add_f32_dpp v142, v142, v142 row_ror:4 row_mask:0xf bank_mask:0xf bound_ctrl:1
	v_pk_fma_f32 v[152:153], v[122:123], v[32:33], v[152:153] op_sel:[0,1,0] op_sel_hi:[1,1,1]
	v_pk_fma_f32 v[154:155], v[124:125], v[34:35], v[154:155] op_sel:[0,0,0] op_sel_hi:[1,0,1]
	v_add_f32_dpp v145, v142, v142 row_ror:8 row_mask:0xf bank_mask:0xf bound_ctrl:1
	v_pk_fma_f32 v[156:157], v[126:127], v[34:35], v[156:157] op_sel:[0,1,0] op_sel_hi:[1,1,1]
	ds_read_b128 v[8:11], v196 offset:24576
	v_mov_b32_dpp v148, v145 quad_perm:[0,0,0,0] row_mask:0xf bank_mask:0xf
	v_mov_b32_dpp v149, v145 quad_perm:[1,1,1,1] row_mask:0xf bank_mask:0xf
	v_pk_fma_f32 v[120:121], v[48:49], v[148:149], v[150:151] op_sel:[0,0,0] op_sel_hi:[0,1,1]
	ds_read_b128 v[12:15], v196 offset:24832
	v_pk_fma_f32 v[122:123], v[48:49], v[148:149], v[152:153] op_sel:[1,0,0] op_sel_hi:[1,1,1]
	ds_read_b128 v[16:19], v196 offset:25088
	v_pk_fma_f32 v[124:125], v[50:51], v[148:149], v[154:155] op_sel:[0,0,0] op_sel_hi:[0,1,1]
	ds_read_b128 v[20:23], v196 offset:25344
	v_pk_fma_f32 v[126:127], v[50:51], v[148:149], v[156:157] op_sel:[1,0,0] op_sel_hi:[1,1,1]
	ds_read_b128 v[24:27], v196 offset:25600
	v_pk_mul_f32 v[132:133], v[120:121], v[68:69] op_sel:[0,0] op_sel_hi:[1,0]
	v_pk_mul_f32 v[128:129], v[120:121], v[36:37] op_sel:[0,0] op_sel_hi:[1,0]
	v_pk_fma_f32 v[132:133], v[122:123], v[68:69], v[132:133] op_sel:[0,1,0] op_sel_hi:[1,1,1]
	v_pk_fma_f32 v[128:129], v[122:123], v[36:37], v[128:129] op_sel:[0,1,0] op_sel_hi:[1,1,1]
	v_pk_fma_f32 v[132:133], v[124:125], v[70:71], v[132:133] op_sel:[0,0,0] op_sel_hi:[1,0,1]
	v_pk_fma_f32 v[128:129], v[124:125], v[38:39], v[128:129] op_sel:[0,0,0] op_sel_hi:[1,0,1]
	v_pk_fma_f32 v[132:133], v[126:127], v[70:71], v[132:133] op_sel:[0,1,0] op_sel_hi:[1,1,1]
	v_pk_fma_f32 v[128:129], v[126:127], v[38:39], v[128:129] op_sel:[0,1,0] op_sel_hi:[1,1,1]
	ds_read_b64 v[28:29], v197 offset:25856
	s_waitcnt lgkmcnt(6)
	v_cndmask_b32_e64 v134, v133, v132, s[2:3]
	v_cndmask_b32_e64 v135, v132, v133, s[2:3]
	v_cndmask_b32_e64 v136, v129, v128, s[2:3]
	v_cndmask_b32_e64 v137, v128, v129, s[2:3]
	v_add_f32_dpp v138, v135, v134 quad_perm:[1,0,3,2] row_mask:0xf bank_mask:0xf bound_ctrl:1
	v_pk_mul_f32 v[150:151], v[64:65], v[76:77] op_sel:[0,0] op_sel_hi:[0,1]
	v_add_f32_dpp v139, v137, v136 quad_perm:[1,0,3,2] row_mask:0xf bank_mask:0xf bound_ctrl:1
	v_cndmask_b32_e64 v140, v139, v138, s[4:5]
	v_cndmask_b32_e64 v141, v138, v139, s[4:5]
	v_pk_mul_f32 v[152:153], v[64:65], v[76:77] op_sel:[1,0] op_sel_hi:[1,1]
	v_pk_mul_f32 v[154:155], v[66:67], v[76:77] op_sel:[0,0] op_sel_hi:[0,1]
	v_add_f32_dpp v142, v141, v140 quad_perm:[2,3,0,1] row_mask:0xf bank_mask:0xf bound_ctrl:1
	v_pk_mul_f32 v[156:157], v[66:67], v[76:77] op_sel:[1,0] op_sel_hi:[1,1]
	v_pk_fma_f32 v[150:151], v[120:121], v[56:57], v[150:151] op_sel:[0,0,0] op_sel_hi:[1,0,1]
	v_add_f32_dpp v142, v142, v142 row_ror:4 row_mask:0xf bank_mask:0xf bound_ctrl:1
	v_pk_fma_f32 v[152:153], v[122:123], v[56:57], v[152:153] op_sel:[0,1,0] op_sel_hi:[1,1,1]
	v_pk_fma_f32 v[154:155], v[124:125], v[58:59], v[154:155] op_sel:[0,0,0] op_sel_hi:[1,0,1]
	v_add_f32_dpp v146, v142, v142 row_ror:8 row_mask:0xf bank_mask:0xf bound_ctrl:1
	v_pk_fma_f32 v[156:157], v[126:127], v[58:59], v[156:157] op_sel:[0,1,0] op_sel_hi:[1,1,1]
	ds_read_b128 v[32:35], v196 offset:26112
	v_mov_b32_dpp v148, v146 quad_perm:[0,0,0,0] row_mask:0xf bank_mask:0xf
	v_mov_b32_dpp v149, v146 quad_perm:[1,1,1,1] row_mask:0xf bank_mask:0xf
	v_pk_fma_f32 v[120:121], v[72:73], v[148:149], v[150:151] op_sel:[0,0,0] op_sel_hi:[0,1,1]
	ds_read_b128 v[36:39], v196 offset:26368
	v_pk_fma_f32 v[122:123], v[72:73], v[148:149], v[152:153] op_sel:[1,0,0] op_sel_hi:[1,1,1]
	ds_read_b128 v[40:43], v196 offset:26624
	v_pk_fma_f32 v[124:125], v[74:75], v[148:149], v[154:155] op_sel:[0,0,0] op_sel_hi:[0,1,1]
	ds_read_b128 v[44:47], v196 offset:26880
	v_pk_fma_f32 v[126:127], v[74:75], v[148:149], v[156:157] op_sel:[1,0,0] op_sel_hi:[1,1,1]
	ds_read_b128 v[48:51], v196 offset:27136
	v_pk_mul_f32 v[132:133], v[120:121], v[92:93] op_sel:[0,0] op_sel_hi:[1,0]
	v_pk_mul_f32 v[128:129], v[120:121], v[60:61] op_sel:[0,0] op_sel_hi:[1,0]
	v_pk_fma_f32 v[132:133], v[122:123], v[92:93], v[132:133] op_sel:[0,1,0] op_sel_hi:[1,1,1]
	v_pk_fma_f32 v[128:129], v[122:123], v[60:61], v[128:129] op_sel:[0,1,0] op_sel_hi:[1,1,1]
	v_pk_fma_f32 v[132:133], v[124:125], v[94:95], v[132:133] op_sel:[0,0,0] op_sel_hi:[1,0,1]
	v_pk_fma_f32 v[128:129], v[124:125], v[62:63], v[128:129] op_sel:[0,0,0] op_sel_hi:[1,0,1]
	v_pk_fma_f32 v[132:133], v[126:127], v[94:95], v[132:133] op_sel:[0,1,0] op_sel_hi:[1,1,1]
	v_pk_fma_f32 v[128:129], v[126:127], v[62:63], v[128:129] op_sel:[0,1,0] op_sel_hi:[1,1,1]
	ds_read_b64 v[52:53], v197 offset:27392
	s_waitcnt lgkmcnt(6)
	v_cndmask_b32_e64 v134, v133, v132, s[2:3]
	v_cndmask_b32_e64 v135, v132, v133, s[2:3]
	v_cndmask_b32_e64 v136, v129, v128, s[2:3]
	v_cndmask_b32_e64 v137, v128, v129, s[2:3]
	v_add_f32_dpp v138, v135, v134 quad_perm:[1,0,3,2] row_mask:0xf bank_mask:0xf bound_ctrl:1
	v_pk_mul_f32 v[150:151], v[88:89], v[100:101] op_sel:[0,0] op_sel_hi:[0,1]
	v_add_f32_dpp v139, v137, v136 quad_perm:[1,0,3,2] row_mask:0xf bank_mask:0xf bound_ctrl:1
	v_cndmask_b32_e64 v140, v139, v138, s[4:5]
	v_cndmask_b32_e64 v141, v138, v139, s[4:5]
	v_pk_mul_f32 v[152:153], v[88:89], v[100:101] op_sel:[1,0] op_sel_hi:[1,1]
	v_pk_mul_f32 v[154:155], v[90:91], v[100:101] op_sel:[0,0] op_sel_hi:[0,1]
	v_add_f32_dpp v142, v141, v140 quad_perm:[2,3,0,1] row_mask:0xf bank_mask:0xf bound_ctrl:1
	v_pk_mul_f32 v[156:157], v[90:91], v[100:101] op_sel:[1,0] op_sel_hi:[1,1]
	v_pk_fma_f32 v[150:151], v[120:121], v[80:81], v[150:151] op_sel:[0,0,0] op_sel_hi:[1,0,1]
	v_add_f32_dpp v142, v142, v142 row_ror:4 row_mask:0xf bank_mask:0xf bound_ctrl:1
	v_pk_fma_f32 v[152:153], v[122:123], v[80:81], v[152:153] op_sel:[0,1,0] op_sel_hi:[1,1,1]
	v_pk_fma_f32 v[154:155], v[124:125], v[82:83], v[154:155] op_sel:[0,0,0] op_sel_hi:[1,0,1]
	v_add_f32_dpp v147, v142, v142 row_ror:8 row_mask:0xf bank_mask:0xf bound_ctrl:1
	v_pk_fma_f32 v[156:157], v[126:127], v[82:83], v[156:157] op_sel:[0,1,0] op_sel_hi:[1,1,1]
	ds_read_b128 v[56:59], v196 offset:27648
	v_mov_b32_dpp v148, v147 quad_perm:[0,0,0,0] row_mask:0xf bank_mask:0xf
	v_mov_b32_dpp v149, v147 quad_perm:[1,1,1,1] row_mask:0xf bank_mask:0xf
	v_pk_fma_f32 v[120:121], v[96:97], v[148:149], v[150:151] op_sel:[0,0,0] op_sel_hi:[0,1,1]
	ds_read_b128 v[60:63], v196 offset:27904
	v_pk_fma_f32 v[122:123], v[96:97], v[148:149], v[152:153] op_sel:[1,0,0] op_sel_hi:[1,1,1]
	ds_read_b128 v[64:67], v196 offset:28160
	v_pk_fma_f32 v[124:125], v[98:99], v[148:149], v[154:155] op_sel:[0,0,0] op_sel_hi:[0,1,1]
	ds_read_b128 v[68:71], v196 offset:28416
	v_pk_fma_f32 v[126:127], v[98:99], v[148:149], v[156:157] op_sel:[1,0,0] op_sel_hi:[1,1,1]
	ds_read_b128 v[72:75], v196 offset:28672
	v_pk_mul_f32 v[132:133], v[120:121], v[20:21] op_sel:[0,0] op_sel_hi:[1,0]
	v_pk_mul_f32 v[128:129], v[120:121], v[84:85] op_sel:[0,0] op_sel_hi:[1,0]
	v_pk_fma_f32 v[132:133], v[122:123], v[20:21], v[132:133] op_sel:[0,1,0] op_sel_hi:[1,1,1]
	v_pk_fma_f32 v[128:129], v[122:123], v[84:85], v[128:129] op_sel:[0,1,0] op_sel_hi:[1,1,1]
	v_pk_fma_f32 v[132:133], v[124:125], v[22:23], v[132:133] op_sel:[0,0,0] op_sel_hi:[1,0,1]
	v_pk_fma_f32 v[128:129], v[124:125], v[86:87], v[128:129] op_sel:[0,0,0] op_sel_hi:[1,0,1]
	v_pk_fma_f32 v[132:133], v[126:127], v[22:23], v[132:133] op_sel:[0,1,0] op_sel_hi:[1,1,1]
	v_pk_fma_f32 v[128:129], v[126:127], v[86:87], v[128:129] op_sel:[0,1,0] op_sel_hi:[1,1,1]
	ds_read_b64 v[76:77], v197 offset:28928
	v_cndmask_b32_e64 v106, v147, v146, s[12:13]
	v_cndmask_b32_e64 v106, v106, v145, s[10:11]
	v_cndmask_b32_e64 v106, v106, v144, s[6:7]
	s_and_saveexec_b64 s[28:29], s[8:9]
	global_store_dword v[104:105], v106, off
	s_mov_b64 exec, s[28:29]
	v_lshl_add_u64 v[104:105], v[104:105], 0, s[26:27]
	s_waitcnt lgkmcnt(6)
	v_cndmask_b32_e64 v134, v133, v132, s[2:3]
	v_cndmask_b32_e64 v135, v132, v133, s[2:3]
	v_cndmask_b32_e64 v136, v129, v128, s[2:3]
	v_cndmask_b32_e64 v137, v128, v129, s[2:3]
	v_add_f32_dpp v138, v135, v134 quad_perm:[1,0,3,2] row_mask:0xf bank_mask:0xf bound_ctrl:1
	v_pk_mul_f32 v[150:151], v[16:17], v[28:29] op_sel:[0,0] op_sel_hi:[0,1]
	v_add_f32_dpp v139, v137, v136 quad_perm:[1,0,3,2] row_mask:0xf bank_mask:0xf bound_ctrl:1
	v_cndmask_b32_e64 v140, v139, v138, s[4:5]
	v_cndmask_b32_e64 v141, v138, v139, s[4:5]
	v_pk_mul_f32 v[152:153], v[16:17], v[28:29] op_sel:[1,0] op_sel_hi:[1,1]
	v_pk_mul_f32 v[154:155], v[18:19], v[28:29] op_sel:[0,0] op_sel_hi:[0,1]
	v_add_f32_dpp v142, v141, v140 quad_perm:[2,3,0,1] row_mask:0xf bank_mask:0xf bound_ctrl:1
	v_pk_mul_f32 v[156:157], v[18:19], v[28:29] op_sel:[1,0] op_sel_hi:[1,1]
	v_pk_fma_f32 v[150:151], v[120:121], v[8:9], v[150:151] op_sel:[0,0,0] op_sel_hi:[1,0,1]
	v_add_f32_dpp v142, v142, v142 row_ror:4 row_mask:0xf bank_mask:0xf bound_ctrl:1
	v_pk_fma_f32 v[152:153], v[122:123], v[8:9], v[152:153] op_sel:[0,1,0] op_sel_hi:[1,1,1]
	v_pk_fma_f32 v[154:155], v[124:125], v[10:11], v[154:155] op_sel:[0,0,0] op_sel_hi:[1,0,1]
	v_add_f32_dpp v144, v142, v142 row_ror:8 row_mask:0xf bank_mask:0xf bound_ctrl:1
	v_pk_fma_f32 v[156:157], v[126:127], v[10:11], v[156:157] op_sel:[0,1,0] op_sel_hi:[1,1,1]
	ds_read_b128 v[80:83], v196 offset:29184
	v_mov_b32_dpp v148, v144 quad_perm:[0,0,0,0] row_mask:0xf bank_mask:0xf
	v_mov_b32_dpp v149, v144 quad_perm:[1,1,1,1] row_mask:0xf bank_mask:0xf
	v_pk_fma_f32 v[120:121], v[24:25], v[148:149], v[150:151] op_sel:[0,0,0] op_sel_hi:[0,1,1]
	ds_read_b128 v[84:87], v196 offset:29440
	v_pk_fma_f32 v[122:123], v[24:25], v[148:149], v[152:153] op_sel:[1,0,0] op_sel_hi:[1,1,1]
	ds_read_b128 v[88:91], v196 offset:29696
	v_pk_fma_f32 v[124:125], v[26:27], v[148:149], v[154:155] op_sel:[0,0,0] op_sel_hi:[0,1,1]
	ds_read_b128 v[92:95], v196 offset:29952
	v_pk_fma_f32 v[126:127], v[26:27], v[148:149], v[156:157] op_sel:[1,0,0] op_sel_hi:[1,1,1]
	ds_read_b128 v[96:99], v196 offset:30208
	v_pk_mul_f32 v[132:133], v[120:121], v[44:45] op_sel:[0,0] op_sel_hi:[1,0]
	v_pk_mul_f32 v[128:129], v[120:121], v[12:13] op_sel:[0,0] op_sel_hi:[1,0]
	v_pk_fma_f32 v[132:133], v[122:123], v[44:45], v[132:133] op_sel:[0,1,0] op_sel_hi:[1,1,1]
	v_pk_fma_f32 v[128:129], v[122:123], v[12:13], v[128:129] op_sel:[0,1,0] op_sel_hi:[1,1,1]
	v_pk_fma_f32 v[132:133], v[124:125], v[46:47], v[132:133] op_sel:[0,0,0] op_sel_hi:[1,0,1]
	v_pk_fma_f32 v[128:129], v[124:125], v[14:15], v[128:129] op_sel:[0,0,0] op_sel_hi:[1,0,1]
	v_pk_fma_f32 v[132:133], v[126:127], v[46:47], v[132:133] op_sel:[0,1,0] op_sel_hi:[1,1,1]
	v_pk_fma_f32 v[128:129], v[126:127], v[14:15], v[128:129] op_sel:[0,1,0] op_sel_hi:[1,1,1]
	ds_read_b64 v[100:101], v197 offset:30464
	s_waitcnt lgkmcnt(6)
	v_cndmask_b32_e64 v134, v133, v132, s[2:3]
	v_cndmask_b32_e64 v135, v132, v133, s[2:3]
	v_cndmask_b32_e64 v136, v129, v128, s[2:3]
	v_cndmask_b32_e64 v137, v128, v129, s[2:3]
	v_add_f32_dpp v138, v135, v134 quad_perm:[1,0,3,2] row_mask:0xf bank_mask:0xf bound_ctrl:1
	v_pk_mul_f32 v[150:151], v[40:41], v[52:53] op_sel:[0,0] op_sel_hi:[0,1]
	v_add_f32_dpp v139, v137, v136 quad_perm:[1,0,3,2] row_mask:0xf bank_mask:0xf bound_ctrl:1
	v_cndmask_b32_e64 v140, v139, v138, s[4:5]
	v_cndmask_b32_e64 v141, v138, v139, s[4:5]
	v_pk_mul_f32 v[152:153], v[40:41], v[52:53] op_sel:[1,0] op_sel_hi:[1,1]
	v_pk_mul_f32 v[154:155], v[42:43], v[52:53] op_sel:[0,0] op_sel_hi:[0,1]
	v_add_f32_dpp v142, v141, v140 quad_perm:[2,3,0,1] row_mask:0xf bank_mask:0xf bound_ctrl:1
	v_pk_mul_f32 v[156:157], v[42:43], v[52:53] op_sel:[1,0] op_sel_hi:[1,1]
	v_pk_fma_f32 v[150:151], v[120:121], v[32:33], v[150:151] op_sel:[0,0,0] op_sel_hi:[1,0,1]
	v_add_f32_dpp v142, v142, v142 row_ror:4 row_mask:0xf bank_mask:0xf bound_ctrl:1
	v_pk_fma_f32 v[152:153], v[122:123], v[32:33], v[152:153] op_sel:[0,1,0] op_sel_hi:[1,1,1]
	v_pk_fma_f32 v[154:155], v[124:125], v[34:35], v[154:155] op_sel:[0,0,0] op_sel_hi:[1,0,1]
	v_add_f32_dpp v145, v142, v142 row_ror:8 row_mask:0xf bank_mask:0xf bound_ctrl:1
	v_pk_fma_f32 v[156:157], v[126:127], v[34:35], v[156:157] op_sel:[0,1,0] op_sel_hi:[1,1,1]
	ds_read_b128 v[8:11], v196 offset:30720
	v_mov_b32_dpp v148, v145 quad_perm:[0,0,0,0] row_mask:0xf bank_mask:0xf
	v_mov_b32_dpp v149, v145 quad_perm:[1,1,1,1] row_mask:0xf bank_mask:0xf
	v_pk_fma_f32 v[120:121], v[48:49], v[148:149], v[150:151] op_sel:[0,0,0] op_sel_hi:[0,1,1]
	ds_read_b128 v[12:15], v196 offset:30976
	v_pk_fma_f32 v[122:123], v[48:49], v[148:149], v[152:153] op_sel:[1,0,0] op_sel_hi:[1,1,1]
	ds_read_b128 v[16:19], v196 offset:31232
	v_pk_fma_f32 v[124:125], v[50:51], v[148:149], v[154:155] op_sel:[0,0,0] op_sel_hi:[0,1,1]
	ds_read_b128 v[20:23], v196 offset:31488
	v_pk_fma_f32 v[126:127], v[50:51], v[148:149], v[156:157] op_sel:[1,0,0] op_sel_hi:[1,1,1]
	ds_read_b128 v[24:27], v196 offset:31744
	v_pk_mul_f32 v[132:133], v[120:121], v[68:69] op_sel:[0,0] op_sel_hi:[1,0]
	v_pk_mul_f32 v[128:129], v[120:121], v[36:37] op_sel:[0,0] op_sel_hi:[1,0]
	v_pk_fma_f32 v[132:133], v[122:123], v[68:69], v[132:133] op_sel:[0,1,0] op_sel_hi:[1,1,1]
	v_pk_fma_f32 v[128:129], v[122:123], v[36:37], v[128:129] op_sel:[0,1,0] op_sel_hi:[1,1,1]
	v_pk_fma_f32 v[132:133], v[124:125], v[70:71], v[132:133] op_sel:[0,0,0] op_sel_hi:[1,0,1]
	v_pk_fma_f32 v[128:129], v[124:125], v[38:39], v[128:129] op_sel:[0,0,0] op_sel_hi:[1,0,1]
	v_pk_fma_f32 v[132:133], v[126:127], v[70:71], v[132:133] op_sel:[0,1,0] op_sel_hi:[1,1,1]
	v_pk_fma_f32 v[128:129], v[126:127], v[38:39], v[128:129] op_sel:[0,1,0] op_sel_hi:[1,1,1]
	ds_read_b64 v[28:29], v197 offset:32000
	s_waitcnt lgkmcnt(6)
	v_cndmask_b32_e64 v134, v133, v132, s[2:3]
	v_cndmask_b32_e64 v135, v132, v133, s[2:3]
	v_cndmask_b32_e64 v136, v129, v128, s[2:3]
	v_cndmask_b32_e64 v137, v128, v129, s[2:3]
	v_add_f32_dpp v138, v135, v134 quad_perm:[1,0,3,2] row_mask:0xf bank_mask:0xf bound_ctrl:1
	v_pk_mul_f32 v[150:151], v[64:65], v[76:77] op_sel:[0,0] op_sel_hi:[0,1]
	v_add_f32_dpp v139, v137, v136 quad_perm:[1,0,3,2] row_mask:0xf bank_mask:0xf bound_ctrl:1
	v_cndmask_b32_e64 v140, v139, v138, s[4:5]
	v_cndmask_b32_e64 v141, v138, v139, s[4:5]
	v_pk_mul_f32 v[152:153], v[64:65], v[76:77] op_sel:[1,0] op_sel_hi:[1,1]
	v_pk_mul_f32 v[154:155], v[66:67], v[76:77] op_sel:[0,0] op_sel_hi:[0,1]
	v_add_f32_dpp v142, v141, v140 quad_perm:[2,3,0,1] row_mask:0xf bank_mask:0xf bound_ctrl:1
	v_pk_mul_f32 v[156:157], v[66:67], v[76:77] op_sel:[1,0] op_sel_hi:[1,1]
	v_pk_fma_f32 v[150:151], v[120:121], v[56:57], v[150:151] op_sel:[0,0,0] op_sel_hi:[1,0,1]
	v_add_f32_dpp v142, v142, v142 row_ror:4 row_mask:0xf bank_mask:0xf bound_ctrl:1
	v_pk_fma_f32 v[152:153], v[122:123], v[56:57], v[152:153] op_sel:[0,1,0] op_sel_hi:[1,1,1]
	v_pk_fma_f32 v[154:155], v[124:125], v[58:59], v[154:155] op_sel:[0,0,0] op_sel_hi:[1,0,1]
	v_add_f32_dpp v146, v142, v142 row_ror:8 row_mask:0xf bank_mask:0xf bound_ctrl:1
	v_pk_fma_f32 v[156:157], v[126:127], v[58:59], v[156:157] op_sel:[0,1,0] op_sel_hi:[1,1,1]
	ds_read_b128 v[32:35], v196 offset:32256
	v_mov_b32_dpp v148, v146 quad_perm:[0,0,0,0] row_mask:0xf bank_mask:0xf
	v_mov_b32_dpp v149, v146 quad_perm:[1,1,1,1] row_mask:0xf bank_mask:0xf
	v_pk_fma_f32 v[120:121], v[72:73], v[148:149], v[150:151] op_sel:[0,0,0] op_sel_hi:[0,1,1]
	ds_read_b128 v[36:39], v196 offset:32512
	v_pk_fma_f32 v[122:123], v[72:73], v[148:149], v[152:153] op_sel:[1,0,0] op_sel_hi:[1,1,1]
	ds_read_b128 v[40:43], v196 offset:32768
	v_pk_fma_f32 v[124:125], v[74:75], v[148:149], v[154:155] op_sel:[0,0,0] op_sel_hi:[0,1,1]
	ds_read_b128 v[44:47], v196 offset:33024
	v_pk_fma_f32 v[126:127], v[74:75], v[148:149], v[156:157] op_sel:[1,0,0] op_sel_hi:[1,1,1]
	ds_read_b128 v[48:51], v196 offset:33280
	v_pk_mul_f32 v[132:133], v[120:121], v[92:93] op_sel:[0,0] op_sel_hi:[1,0]
	v_pk_mul_f32 v[128:129], v[120:121], v[60:61] op_sel:[0,0] op_sel_hi:[1,0]
	v_pk_fma_f32 v[132:133], v[122:123], v[92:93], v[132:133] op_sel:[0,1,0] op_sel_hi:[1,1,1]
	v_pk_fma_f32 v[128:129], v[122:123], v[60:61], v[128:129] op_sel:[0,1,0] op_sel_hi:[1,1,1]
	v_pk_fma_f32 v[132:133], v[124:125], v[94:95], v[132:133] op_sel:[0,0,0] op_sel_hi:[1,0,1]
	v_pk_fma_f32 v[128:129], v[124:125], v[62:63], v[128:129] op_sel:[0,0,0] op_sel_hi:[1,0,1]
	v_pk_fma_f32 v[132:133], v[126:127], v[94:95], v[132:133] op_sel:[0,1,0] op_sel_hi:[1,1,1]
	v_pk_fma_f32 v[128:129], v[126:127], v[62:63], v[128:129] op_sel:[0,1,0] op_sel_hi:[1,1,1]
	ds_read_b64 v[52:53], v197 offset:33536
	s_waitcnt lgkmcnt(6)
	v_cndmask_b32_e64 v134, v133, v132, s[2:3]
	v_cndmask_b32_e64 v135, v132, v133, s[2:3]
	v_cndmask_b32_e64 v136, v129, v128, s[2:3]
	v_cndmask_b32_e64 v137, v128, v129, s[2:3]
	v_add_f32_dpp v138, v135, v134 quad_perm:[1,0,3,2] row_mask:0xf bank_mask:0xf bound_ctrl:1
	v_pk_mul_f32 v[150:151], v[88:89], v[100:101] op_sel:[0,0] op_sel_hi:[0,1]
	v_add_f32_dpp v139, v137, v136 quad_perm:[1,0,3,2] row_mask:0xf bank_mask:0xf bound_ctrl:1
	v_cndmask_b32_e64 v140, v139, v138, s[4:5]
	v_cndmask_b32_e64 v141, v138, v139, s[4:5]
	v_pk_mul_f32 v[152:153], v[88:89], v[100:101] op_sel:[1,0] op_sel_hi:[1,1]
	v_pk_mul_f32 v[154:155], v[90:91], v[100:101] op_sel:[0,0] op_sel_hi:[0,1]
	v_add_f32_dpp v142, v141, v140 quad_perm:[2,3,0,1] row_mask:0xf bank_mask:0xf bound_ctrl:1
	v_pk_mul_f32 v[156:157], v[90:91], v[100:101] op_sel:[1,0] op_sel_hi:[1,1]
	v_pk_fma_f32 v[150:151], v[120:121], v[80:81], v[150:151] op_sel:[0,0,0] op_sel_hi:[1,0,1]
	v_add_f32_dpp v142, v142, v142 row_ror:4 row_mask:0xf bank_mask:0xf bound_ctrl:1
	v_pk_fma_f32 v[152:153], v[122:123], v[80:81], v[152:153] op_sel:[0,1,0] op_sel_hi:[1,1,1]
	v_pk_fma_f32 v[154:155], v[124:125], v[82:83], v[154:155] op_sel:[0,0,0] op_sel_hi:[1,0,1]
	v_add_f32_dpp v147, v142, v142 row_ror:8 row_mask:0xf bank_mask:0xf bound_ctrl:1
	v_pk_fma_f32 v[156:157], v[126:127], v[82:83], v[156:157] op_sel:[0,1,0] op_sel_hi:[1,1,1]
	ds_read_b128 v[56:59], v196 offset:33792
	v_mov_b32_dpp v148, v147 quad_perm:[0,0,0,0] row_mask:0xf bank_mask:0xf
	v_mov_b32_dpp v149, v147 quad_perm:[1,1,1,1] row_mask:0xf bank_mask:0xf
	v_pk_fma_f32 v[120:121], v[96:97], v[148:149], v[150:151] op_sel:[0,0,0] op_sel_hi:[0,1,1]
	ds_read_b128 v[60:63], v196 offset:34048
	v_pk_fma_f32 v[122:123], v[96:97], v[148:149], v[152:153] op_sel:[1,0,0] op_sel_hi:[1,1,1]
	ds_read_b128 v[64:67], v196 offset:34304
	v_pk_fma_f32 v[124:125], v[98:99], v[148:149], v[154:155] op_sel:[0,0,0] op_sel_hi:[0,1,1]
	ds_read_b128 v[68:71], v196 offset:34560
	v_pk_fma_f32 v[126:127], v[98:99], v[148:149], v[156:157] op_sel:[1,0,0] op_sel_hi:[1,1,1]
	ds_read_b128 v[72:75], v196 offset:34816
	v_pk_mul_f32 v[132:133], v[120:121], v[20:21] op_sel:[0,0] op_sel_hi:[1,0]
	v_pk_mul_f32 v[128:129], v[120:121], v[84:85] op_sel:[0,0] op_sel_hi:[1,0]
	v_pk_fma_f32 v[132:133], v[122:123], v[20:21], v[132:133] op_sel:[0,1,0] op_sel_hi:[1,1,1]
	v_pk_fma_f32 v[128:129], v[122:123], v[84:85], v[128:129] op_sel:[0,1,0] op_sel_hi:[1,1,1]
	v_pk_fma_f32 v[132:133], v[124:125], v[22:23], v[132:133] op_sel:[0,0,0] op_sel_hi:[1,0,1]
	v_pk_fma_f32 v[128:129], v[124:125], v[86:87], v[128:129] op_sel:[0,0,0] op_sel_hi:[1,0,1]
	v_pk_fma_f32 v[132:133], v[126:127], v[22:23], v[132:133] op_sel:[0,1,0] op_sel_hi:[1,1,1]
	v_pk_fma_f32 v[128:129], v[126:127], v[86:87], v[128:129] op_sel:[0,1,0] op_sel_hi:[1,1,1]
	ds_read_b64 v[76:77], v197 offset:35072
	v_cndmask_b32_e64 v106, v147, v146, s[12:13]
	v_cndmask_b32_e64 v106, v106, v145, s[10:11]
	v_cndmask_b32_e64 v106, v106, v144, s[6:7]
	s_and_saveexec_b64 s[28:29], s[8:9]
	global_store_dword v[104:105], v106, off
	s_mov_b64 exec, s[28:29]
	v_lshl_add_u64 v[104:105], v[104:105], 0, s[26:27]
	s_waitcnt lgkmcnt(6)
	v_cndmask_b32_e64 v134, v133, v132, s[2:3]
	v_cndmask_b32_e64 v135, v132, v133, s[2:3]
	v_cndmask_b32_e64 v136, v129, v128, s[2:3]
	v_cndmask_b32_e64 v137, v128, v129, s[2:3]
	v_add_f32_dpp v138, v135, v134 quad_perm:[1,0,3,2] row_mask:0xf bank_mask:0xf bound_ctrl:1
	v_pk_mul_f32 v[150:151], v[16:17], v[28:29] op_sel:[0,0] op_sel_hi:[0,1]
	v_add_f32_dpp v139, v137, v136 quad_perm:[1,0,3,2] row_mask:0xf bank_mask:0xf bound_ctrl:1
	v_cndmask_b32_e64 v140, v139, v138, s[4:5]
	v_cndmask_b32_e64 v141, v138, v139, s[4:5]
	v_pk_mul_f32 v[152:153], v[16:17], v[28:29] op_sel:[1,0] op_sel_hi:[1,1]
	v_pk_mul_f32 v[154:155], v[18:19], v[28:29] op_sel:[0,0] op_sel_hi:[0,1]
	v_add_f32_dpp v142, v141, v140 quad_perm:[2,3,0,1] row_mask:0xf bank_mask:0xf bound_ctrl:1
	v_pk_mul_f32 v[156:157], v[18:19], v[28:29] op_sel:[1,0] op_sel_hi:[1,1]
	v_pk_fma_f32 v[150:151], v[120:121], v[8:9], v[150:151] op_sel:[0,0,0] op_sel_hi:[1,0,1]
	v_add_f32_dpp v142, v142, v142 row_ror:4 row_mask:0xf bank_mask:0xf bound_ctrl:1
	v_pk_fma_f32 v[152:153], v[122:123], v[8:9], v[152:153] op_sel:[0,1,0] op_sel_hi:[1,1,1]
	v_pk_fma_f32 v[154:155], v[124:125], v[10:11], v[154:155] op_sel:[0,0,0] op_sel_hi:[1,0,1]
	v_add_f32_dpp v144, v142, v142 row_ror:8 row_mask:0xf bank_mask:0xf bound_ctrl:1
	v_pk_fma_f32 v[156:157], v[126:127], v[10:11], v[156:157] op_sel:[0,1,0] op_sel_hi:[1,1,1]
	ds_read_b128 v[80:83], v196 offset:35328
	v_mov_b32_dpp v148, v144 quad_perm:[0,0,0,0] row_mask:0xf bank_mask:0xf
	v_mov_b32_dpp v149, v144 quad_perm:[1,1,1,1] row_mask:0xf bank_mask:0xf
	v_pk_fma_f32 v[120:121], v[24:25], v[148:149], v[150:151] op_sel:[0,0,0] op_sel_hi:[0,1,1]
	ds_read_b128 v[84:87], v196 offset:35584
	v_pk_fma_f32 v[122:123], v[24:25], v[148:149], v[152:153] op_sel:[1,0,0] op_sel_hi:[1,1,1]
	ds_read_b128 v[88:91], v196 offset:35840
	v_pk_fma_f32 v[124:125], v[26:27], v[148:149], v[154:155] op_sel:[0,0,0] op_sel_hi:[0,1,1]
	ds_read_b128 v[92:95], v196 offset:36096
	v_pk_fma_f32 v[126:127], v[26:27], v[148:149], v[156:157] op_sel:[1,0,0] op_sel_hi:[1,1,1]
	ds_read_b128 v[96:99], v196 offset:36352
	v_pk_mul_f32 v[132:133], v[120:121], v[44:45] op_sel:[0,0] op_sel_hi:[1,0]
	v_pk_mul_f32 v[128:129], v[120:121], v[12:13] op_sel:[0,0] op_sel_hi:[1,0]
	v_pk_fma_f32 v[132:133], v[122:123], v[44:45], v[132:133] op_sel:[0,1,0] op_sel_hi:[1,1,1]
	v_pk_fma_f32 v[128:129], v[122:123], v[12:13], v[128:129] op_sel:[0,1,0] op_sel_hi:[1,1,1]
	v_pk_fma_f32 v[132:133], v[124:125], v[46:47], v[132:133] op_sel:[0,0,0] op_sel_hi:[1,0,1]
	v_pk_fma_f32 v[128:129], v[124:125], v[14:15], v[128:129] op_sel:[0,0,0] op_sel_hi:[1,0,1]
	v_pk_fma_f32 v[132:133], v[126:127], v[46:47], v[132:133] op_sel:[0,1,0] op_sel_hi:[1,1,1]
	v_pk_fma_f32 v[128:129], v[126:127], v[14:15], v[128:129] op_sel:[0,1,0] op_sel_hi:[1,1,1]
	ds_read_b64 v[100:101], v197 offset:36608
	s_waitcnt lgkmcnt(6)
	v_cndmask_b32_e64 v134, v133, v132, s[2:3]
	v_cndmask_b32_e64 v135, v132, v133, s[2:3]
	v_cndmask_b32_e64 v136, v129, v128, s[2:3]
	v_cndmask_b32_e64 v137, v128, v129, s[2:3]
	v_add_f32_dpp v138, v135, v134 quad_perm:[1,0,3,2] row_mask:0xf bank_mask:0xf bound_ctrl:1
	v_pk_mul_f32 v[150:151], v[40:41], v[52:53] op_sel:[0,0] op_sel_hi:[0,1]
	v_add_f32_dpp v139, v137, v136 quad_perm:[1,0,3,2] row_mask:0xf bank_mask:0xf bound_ctrl:1
	v_cndmask_b32_e64 v140, v139, v138, s[4:5]
	v_cndmask_b32_e64 v141, v138, v139, s[4:5]
	v_pk_mul_f32 v[152:153], v[40:41], v[52:53] op_sel:[1,0] op_sel_hi:[1,1]
	v_pk_mul_f32 v[154:155], v[42:43], v[52:53] op_sel:[0,0] op_sel_hi:[0,1]
	v_add_f32_dpp v142, v141, v140 quad_perm:[2,3,0,1] row_mask:0xf bank_mask:0xf bound_ctrl:1
	v_pk_mul_f32 v[156:157], v[42:43], v[52:53] op_sel:[1,0] op_sel_hi:[1,1]
	v_pk_fma_f32 v[150:151], v[120:121], v[32:33], v[150:151] op_sel:[0,0,0] op_sel_hi:[1,0,1]
	v_add_f32_dpp v142, v142, v142 row_ror:4 row_mask:0xf bank_mask:0xf bound_ctrl:1
	v_pk_fma_f32 v[152:153], v[122:123], v[32:33], v[152:153] op_sel:[0,1,0] op_sel_hi:[1,1,1]
	v_pk_fma_f32 v[154:155], v[124:125], v[34:35], v[154:155] op_sel:[0,0,0] op_sel_hi:[1,0,1]
	v_add_f32_dpp v145, v142, v142 row_ror:8 row_mask:0xf bank_mask:0xf bound_ctrl:1
	v_pk_fma_f32 v[156:157], v[126:127], v[34:35], v[156:157] op_sel:[0,1,0] op_sel_hi:[1,1,1]
	ds_read_b128 v[8:11], v196 offset:36864
	v_mov_b32_dpp v148, v145 quad_perm:[0,0,0,0] row_mask:0xf bank_mask:0xf
	v_mov_b32_dpp v149, v145 quad_perm:[1,1,1,1] row_mask:0xf bank_mask:0xf
	v_pk_fma_f32 v[120:121], v[48:49], v[148:149], v[150:151] op_sel:[0,0,0] op_sel_hi:[0,1,1]
	ds_read_b128 v[12:15], v196 offset:37120
	v_pk_fma_f32 v[122:123], v[48:49], v[148:149], v[152:153] op_sel:[1,0,0] op_sel_hi:[1,1,1]
	ds_read_b128 v[16:19], v196 offset:37376
	v_pk_fma_f32 v[124:125], v[50:51], v[148:149], v[154:155] op_sel:[0,0,0] op_sel_hi:[0,1,1]
	ds_read_b128 v[20:23], v196 offset:37632
	v_pk_fma_f32 v[126:127], v[50:51], v[148:149], v[156:157] op_sel:[1,0,0] op_sel_hi:[1,1,1]
	ds_read_b128 v[24:27], v196 offset:37888
	v_pk_mul_f32 v[132:133], v[120:121], v[68:69] op_sel:[0,0] op_sel_hi:[1,0]
	v_pk_mul_f32 v[128:129], v[120:121], v[36:37] op_sel:[0,0] op_sel_hi:[1,0]
	v_pk_fma_f32 v[132:133], v[122:123], v[68:69], v[132:133] op_sel:[0,1,0] op_sel_hi:[1,1,1]
	v_pk_fma_f32 v[128:129], v[122:123], v[36:37], v[128:129] op_sel:[0,1,0] op_sel_hi:[1,1,1]
	v_pk_fma_f32 v[132:133], v[124:125], v[70:71], v[132:133] op_sel:[0,0,0] op_sel_hi:[1,0,1]
	v_pk_fma_f32 v[128:129], v[124:125], v[38:39], v[128:129] op_sel:[0,0,0] op_sel_hi:[1,0,1]
	v_pk_fma_f32 v[132:133], v[126:127], v[70:71], v[132:133] op_sel:[0,1,0] op_sel_hi:[1,1,1]
	v_pk_fma_f32 v[128:129], v[126:127], v[38:39], v[128:129] op_sel:[0,1,0] op_sel_hi:[1,1,1]
	ds_read_b64 v[28:29], v197 offset:38144
	s_waitcnt lgkmcnt(6)
	v_cndmask_b32_e64 v134, v133, v132, s[2:3]
	v_cndmask_b32_e64 v135, v132, v133, s[2:3]
	v_cndmask_b32_e64 v136, v129, v128, s[2:3]
	v_cndmask_b32_e64 v137, v128, v129, s[2:3]
	v_add_f32_dpp v138, v135, v134 quad_perm:[1,0,3,2] row_mask:0xf bank_mask:0xf bound_ctrl:1
	v_pk_mul_f32 v[150:151], v[64:65], v[76:77] op_sel:[0,0] op_sel_hi:[0,1]
	v_add_f32_dpp v139, v137, v136 quad_perm:[1,0,3,2] row_mask:0xf bank_mask:0xf bound_ctrl:1
	v_cndmask_b32_e64 v140, v139, v138, s[4:5]
	v_cndmask_b32_e64 v141, v138, v139, s[4:5]
	v_pk_mul_f32 v[152:153], v[64:65], v[76:77] op_sel:[1,0] op_sel_hi:[1,1]
	v_pk_mul_f32 v[154:155], v[66:67], v[76:77] op_sel:[0,0] op_sel_hi:[0,1]
	v_add_f32_dpp v142, v141, v140 quad_perm:[2,3,0,1] row_mask:0xf bank_mask:0xf bound_ctrl:1
	v_pk_mul_f32 v[156:157], v[66:67], v[76:77] op_sel:[1,0] op_sel_hi:[1,1]
	v_pk_fma_f32 v[150:151], v[120:121], v[56:57], v[150:151] op_sel:[0,0,0] op_sel_hi:[1,0,1]
	v_add_f32_dpp v142, v142, v142 row_ror:4 row_mask:0xf bank_mask:0xf bound_ctrl:1
	v_pk_fma_f32 v[152:153], v[122:123], v[56:57], v[152:153] op_sel:[0,1,0] op_sel_hi:[1,1,1]
	v_pk_fma_f32 v[154:155], v[124:125], v[58:59], v[154:155] op_sel:[0,0,0] op_sel_hi:[1,0,1]
	v_add_f32_dpp v146, v142, v142 row_ror:8 row_mask:0xf bank_mask:0xf bound_ctrl:1
	v_pk_fma_f32 v[156:157], v[126:127], v[58:59], v[156:157] op_sel:[0,1,0] op_sel_hi:[1,1,1]
	ds_read_b128 v[32:35], v196 offset:38400
	v_mov_b32_dpp v148, v146 quad_perm:[0,0,0,0] row_mask:0xf bank_mask:0xf
	v_mov_b32_dpp v149, v146 quad_perm:[1,1,1,1] row_mask:0xf bank_mask:0xf
	v_pk_fma_f32 v[120:121], v[72:73], v[148:149], v[150:151] op_sel:[0,0,0] op_sel_hi:[0,1,1]
	ds_read_b128 v[36:39], v196 offset:38656
	v_pk_fma_f32 v[122:123], v[72:73], v[148:149], v[152:153] op_sel:[1,0,0] op_sel_hi:[1,1,1]
	ds_read_b128 v[40:43], v196 offset:38912
	v_pk_fma_f32 v[124:125], v[74:75], v[148:149], v[154:155] op_sel:[0,0,0] op_sel_hi:[0,1,1]
	ds_read_b128 v[44:47], v196 offset:39168
	v_pk_fma_f32 v[126:127], v[74:75], v[148:149], v[156:157] op_sel:[1,0,0] op_sel_hi:[1,1,1]
	ds_read_b128 v[48:51], v196 offset:39424
	v_pk_mul_f32 v[132:133], v[120:121], v[92:93] op_sel:[0,0] op_sel_hi:[1,0]
	v_pk_mul_f32 v[128:129], v[120:121], v[60:61] op_sel:[0,0] op_sel_hi:[1,0]
	v_pk_fma_f32 v[132:133], v[122:123], v[92:93], v[132:133] op_sel:[0,1,0] op_sel_hi:[1,1,1]
	v_pk_fma_f32 v[128:129], v[122:123], v[60:61], v[128:129] op_sel:[0,1,0] op_sel_hi:[1,1,1]
	v_pk_fma_f32 v[132:133], v[124:125], v[94:95], v[132:133] op_sel:[0,0,0] op_sel_hi:[1,0,1]
	v_pk_fma_f32 v[128:129], v[124:125], v[62:63], v[128:129] op_sel:[0,0,0] op_sel_hi:[1,0,1]
	v_pk_fma_f32 v[132:133], v[126:127], v[94:95], v[132:133] op_sel:[0,1,0] op_sel_hi:[1,1,1]
	v_pk_fma_f32 v[128:129], v[126:127], v[62:63], v[128:129] op_sel:[0,1,0] op_sel_hi:[1,1,1]
	ds_read_b64 v[52:53], v197 offset:39680
	s_waitcnt lgkmcnt(6)
	v_cndmask_b32_e64 v134, v133, v132, s[2:3]
	v_cndmask_b32_e64 v135, v132, v133, s[2:3]
	v_cndmask_b32_e64 v136, v129, v128, s[2:3]
	v_cndmask_b32_e64 v137, v128, v129, s[2:3]
	v_add_f32_dpp v138, v135, v134 quad_perm:[1,0,3,2] row_mask:0xf bank_mask:0xf bound_ctrl:1
	v_pk_mul_f32 v[150:151], v[88:89], v[100:101] op_sel:[0,0] op_sel_hi:[0,1]
	v_add_f32_dpp v139, v137, v136 quad_perm:[1,0,3,2] row_mask:0xf bank_mask:0xf bound_ctrl:1
	v_cndmask_b32_e64 v140, v139, v138, s[4:5]
	v_cndmask_b32_e64 v141, v138, v139, s[4:5]
	v_pk_mul_f32 v[152:153], v[88:89], v[100:101] op_sel:[1,0] op_sel_hi:[1,1]
	v_pk_mul_f32 v[154:155], v[90:91], v[100:101] op_sel:[0,0] op_sel_hi:[0,1]
	v_add_f32_dpp v142, v141, v140 quad_perm:[2,3,0,1] row_mask:0xf bank_mask:0xf bound_ctrl:1
	v_pk_mul_f32 v[156:157], v[90:91], v[100:101] op_sel:[1,0] op_sel_hi:[1,1]
	v_pk_fma_f32 v[150:151], v[120:121], v[80:81], v[150:151] op_sel:[0,0,0] op_sel_hi:[1,0,1]
	v_add_f32_dpp v142, v142, v142 row_ror:4 row_mask:0xf bank_mask:0xf bound_ctrl:1
	v_pk_fma_f32 v[152:153], v[122:123], v[80:81], v[152:153] op_sel:[0,1,0] op_sel_hi:[1,1,1]
	v_pk_fma_f32 v[154:155], v[124:125], v[82:83], v[154:155] op_sel:[0,0,0] op_sel_hi:[1,0,1]
	v_add_f32_dpp v147, v142, v142 row_ror:8 row_mask:0xf bank_mask:0xf bound_ctrl:1
	v_pk_fma_f32 v[156:157], v[126:127], v[82:83], v[156:157] op_sel:[0,1,0] op_sel_hi:[1,1,1]
	ds_read_b128 v[56:59], v196 offset:39936
	v_mov_b32_dpp v148, v147 quad_perm:[0,0,0,0] row_mask:0xf bank_mask:0xf
	v_mov_b32_dpp v149, v147 quad_perm:[1,1,1,1] row_mask:0xf bank_mask:0xf
	v_pk_fma_f32 v[120:121], v[96:97], v[148:149], v[150:151] op_sel:[0,0,0] op_sel_hi:[0,1,1]
	ds_read_b128 v[60:63], v196 offset:40192
	v_pk_fma_f32 v[122:123], v[96:97], v[148:149], v[152:153] op_sel:[1,0,0] op_sel_hi:[1,1,1]
	ds_read_b128 v[64:67], v196 offset:40448
	v_pk_fma_f32 v[124:125], v[98:99], v[148:149], v[154:155] op_sel:[0,0,0] op_sel_hi:[0,1,1]
	ds_read_b128 v[68:71], v196 offset:40704
	v_pk_fma_f32 v[126:127], v[98:99], v[148:149], v[156:157] op_sel:[1,0,0] op_sel_hi:[1,1,1]
	ds_read_b128 v[72:75], v196 offset:40960
	v_pk_mul_f32 v[132:133], v[120:121], v[20:21] op_sel:[0,0] op_sel_hi:[1,0]
	v_pk_mul_f32 v[128:129], v[120:121], v[84:85] op_sel:[0,0] op_sel_hi:[1,0]
	v_pk_fma_f32 v[132:133], v[122:123], v[20:21], v[132:133] op_sel:[0,1,0] op_sel_hi:[1,1,1]
	v_pk_fma_f32 v[128:129], v[122:123], v[84:85], v[128:129] op_sel:[0,1,0] op_sel_hi:[1,1,1]
	v_pk_fma_f32 v[132:133], v[124:125], v[22:23], v[132:133] op_sel:[0,0,0] op_sel_hi:[1,0,1]
	v_pk_fma_f32 v[128:129], v[124:125], v[86:87], v[128:129] op_sel:[0,0,0] op_sel_hi:[1,0,1]
	v_pk_fma_f32 v[132:133], v[126:127], v[22:23], v[132:133] op_sel:[0,1,0] op_sel_hi:[1,1,1]
	v_pk_fma_f32 v[128:129], v[126:127], v[86:87], v[128:129] op_sel:[0,1,0] op_sel_hi:[1,1,1]
	ds_read_b64 v[76:77], v197 offset:41216
	v_cndmask_b32_e64 v106, v147, v146, s[12:13]
	v_cndmask_b32_e64 v106, v106, v145, s[10:11]
	v_cndmask_b32_e64 v106, v106, v144, s[6:7]
	s_and_saveexec_b64 s[28:29], s[8:9]
	global_store_dword v[104:105], v106, off
	s_mov_b64 exec, s[28:29]
	v_lshl_add_u64 v[104:105], v[104:105], 0, s[26:27]
	s_waitcnt lgkmcnt(6)
	v_cndmask_b32_e64 v134, v133, v132, s[2:3]
	v_cndmask_b32_e64 v135, v132, v133, s[2:3]
	v_cndmask_b32_e64 v136, v129, v128, s[2:3]
	v_cndmask_b32_e64 v137, v128, v129, s[2:3]
	v_add_f32_dpp v138, v135, v134 quad_perm:[1,0,3,2] row_mask:0xf bank_mask:0xf bound_ctrl:1
	v_pk_mul_f32 v[150:151], v[16:17], v[28:29] op_sel:[0,0] op_sel_hi:[0,1]
	v_add_f32_dpp v139, v137, v136 quad_perm:[1,0,3,2] row_mask:0xf bank_mask:0xf bound_ctrl:1
	v_cndmask_b32_e64 v140, v139, v138, s[4:5]
	v_cndmask_b32_e64 v141, v138, v139, s[4:5]
	v_pk_mul_f32 v[152:153], v[16:17], v[28:29] op_sel:[1,0] op_sel_hi:[1,1]
	v_pk_mul_f32 v[154:155], v[18:19], v[28:29] op_sel:[0,0] op_sel_hi:[0,1]
	v_add_f32_dpp v142, v141, v140 quad_perm:[2,3,0,1] row_mask:0xf bank_mask:0xf bound_ctrl:1
	v_pk_mul_f32 v[156:157], v[18:19], v[28:29] op_sel:[1,0] op_sel_hi:[1,1]
	v_pk_fma_f32 v[150:151], v[120:121], v[8:9], v[150:151] op_sel:[0,0,0] op_sel_hi:[1,0,1]
	v_add_f32_dpp v142, v142, v142 row_ror:4 row_mask:0xf bank_mask:0xf bound_ctrl:1
	v_pk_fma_f32 v[152:153], v[122:123], v[8:9], v[152:153] op_sel:[0,1,0] op_sel_hi:[1,1,1]
	v_pk_fma_f32 v[154:155], v[124:125], v[10:11], v[154:155] op_sel:[0,0,0] op_sel_hi:[1,0,1]
	v_add_f32_dpp v144, v142, v142 row_ror:8 row_mask:0xf bank_mask:0xf bound_ctrl:1
	v_pk_fma_f32 v[156:157], v[126:127], v[10:11], v[156:157] op_sel:[0,1,0] op_sel_hi:[1,1,1]
	ds_read_b128 v[80:83], v196 offset:41472
	v_mov_b32_dpp v148, v144 quad_perm:[0,0,0,0] row_mask:0xf bank_mask:0xf
	v_mov_b32_dpp v149, v144 quad_perm:[1,1,1,1] row_mask:0xf bank_mask:0xf
	v_pk_fma_f32 v[120:121], v[24:25], v[148:149], v[150:151] op_sel:[0,0,0] op_sel_hi:[0,1,1]
	ds_read_b128 v[84:87], v196 offset:41728
	v_pk_fma_f32 v[122:123], v[24:25], v[148:149], v[152:153] op_sel:[1,0,0] op_sel_hi:[1,1,1]
	ds_read_b128 v[88:91], v196 offset:41984
	v_pk_fma_f32 v[124:125], v[26:27], v[148:149], v[154:155] op_sel:[0,0,0] op_sel_hi:[0,1,1]
	ds_read_b128 v[92:95], v196 offset:42240
	v_pk_fma_f32 v[126:127], v[26:27], v[148:149], v[156:157] op_sel:[1,0,0] op_sel_hi:[1,1,1]
	ds_read_b128 v[96:99], v196 offset:42496
	v_pk_mul_f32 v[132:133], v[120:121], v[44:45] op_sel:[0,0] op_sel_hi:[1,0]
	v_pk_mul_f32 v[128:129], v[120:121], v[12:13] op_sel:[0,0] op_sel_hi:[1,0]
	v_pk_fma_f32 v[132:133], v[122:123], v[44:45], v[132:133] op_sel:[0,1,0] op_sel_hi:[1,1,1]
	v_pk_fma_f32 v[128:129], v[122:123], v[12:13], v[128:129] op_sel:[0,1,0] op_sel_hi:[1,1,1]
	v_pk_fma_f32 v[132:133], v[124:125], v[46:47], v[132:133] op_sel:[0,0,0] op_sel_hi:[1,0,1]
	v_pk_fma_f32 v[128:129], v[124:125], v[14:15], v[128:129] op_sel:[0,0,0] op_sel_hi:[1,0,1]
	v_pk_fma_f32 v[132:133], v[126:127], v[46:47], v[132:133] op_sel:[0,1,0] op_sel_hi:[1,1,1]
	v_pk_fma_f32 v[128:129], v[126:127], v[14:15], v[128:129] op_sel:[0,1,0] op_sel_hi:[1,1,1]
	ds_read_b64 v[100:101], v197 offset:42752
	s_waitcnt lgkmcnt(6)
	v_cndmask_b32_e64 v134, v133, v132, s[2:3]
	v_cndmask_b32_e64 v135, v132, v133, s[2:3]
	v_cndmask_b32_e64 v136, v129, v128, s[2:3]
	v_cndmask_b32_e64 v137, v128, v129, s[2:3]
	v_add_f32_dpp v138, v135, v134 quad_perm:[1,0,3,2] row_mask:0xf bank_mask:0xf bound_ctrl:1
	v_pk_mul_f32 v[150:151], v[40:41], v[52:53] op_sel:[0,0] op_sel_hi:[0,1]
	v_add_f32_dpp v139, v137, v136 quad_perm:[1,0,3,2] row_mask:0xf bank_mask:0xf bound_ctrl:1
	v_cndmask_b32_e64 v140, v139, v138, s[4:5]
	v_cndmask_b32_e64 v141, v138, v139, s[4:5]
	v_pk_mul_f32 v[152:153], v[40:41], v[52:53] op_sel:[1,0] op_sel_hi:[1,1]
	v_pk_mul_f32 v[154:155], v[42:43], v[52:53] op_sel:[0,0] op_sel_hi:[0,1]
	v_add_f32_dpp v142, v141, v140 quad_perm:[2,3,0,1] row_mask:0xf bank_mask:0xf bound_ctrl:1
	v_pk_mul_f32 v[156:157], v[42:43], v[52:53] op_sel:[1,0] op_sel_hi:[1,1]
	v_pk_fma_f32 v[150:151], v[120:121], v[32:33], v[150:151] op_sel:[0,0,0] op_sel_hi:[1,0,1]
	v_add_f32_dpp v142, v142, v142 row_ror:4 row_mask:0xf bank_mask:0xf bound_ctrl:1
	v_pk_fma_f32 v[152:153], v[122:123], v[32:33], v[152:153] op_sel:[0,1,0] op_sel_hi:[1,1,1]
	v_pk_fma_f32 v[154:155], v[124:125], v[34:35], v[154:155] op_sel:[0,0,0] op_sel_hi:[1,0,1]
	v_add_f32_dpp v145, v142, v142 row_ror:8 row_mask:0xf bank_mask:0xf bound_ctrl:1
	v_pk_fma_f32 v[156:157], v[126:127], v[34:35], v[156:157] op_sel:[0,1,0] op_sel_hi:[1,1,1]
	ds_read_b128 v[8:11], v196 offset:43008
	v_mov_b32_dpp v148, v145 quad_perm:[0,0,0,0] row_mask:0xf bank_mask:0xf
	v_mov_b32_dpp v149, v145 quad_perm:[1,1,1,1] row_mask:0xf bank_mask:0xf
	v_pk_fma_f32 v[120:121], v[48:49], v[148:149], v[150:151] op_sel:[0,0,0] op_sel_hi:[0,1,1]
	ds_read_b128 v[12:15], v196 offset:43264
	v_pk_fma_f32 v[122:123], v[48:49], v[148:149], v[152:153] op_sel:[1,0,0] op_sel_hi:[1,1,1]
	ds_read_b128 v[16:19], v196 offset:43520
	v_pk_fma_f32 v[124:125], v[50:51], v[148:149], v[154:155] op_sel:[0,0,0] op_sel_hi:[0,1,1]
	ds_read_b128 v[20:23], v196 offset:43776
	v_pk_fma_f32 v[126:127], v[50:51], v[148:149], v[156:157] op_sel:[1,0,0] op_sel_hi:[1,1,1]
	ds_read_b128 v[24:27], v196 offset:44032
	v_pk_mul_f32 v[132:133], v[120:121], v[68:69] op_sel:[0,0] op_sel_hi:[1,0]
	v_pk_mul_f32 v[128:129], v[120:121], v[36:37] op_sel:[0,0] op_sel_hi:[1,0]
	v_pk_fma_f32 v[132:133], v[122:123], v[68:69], v[132:133] op_sel:[0,1,0] op_sel_hi:[1,1,1]
	v_pk_fma_f32 v[128:129], v[122:123], v[36:37], v[128:129] op_sel:[0,1,0] op_sel_hi:[1,1,1]
	v_pk_fma_f32 v[132:133], v[124:125], v[70:71], v[132:133] op_sel:[0,0,0] op_sel_hi:[1,0,1]
	v_pk_fma_f32 v[128:129], v[124:125], v[38:39], v[128:129] op_sel:[0,0,0] op_sel_hi:[1,0,1]
	v_pk_fma_f32 v[132:133], v[126:127], v[70:71], v[132:133] op_sel:[0,1,0] op_sel_hi:[1,1,1]
	v_pk_fma_f32 v[128:129], v[126:127], v[38:39], v[128:129] op_sel:[0,1,0] op_sel_hi:[1,1,1]
	ds_read_b64 v[28:29], v197 offset:44288
	s_waitcnt lgkmcnt(6)
	v_cndmask_b32_e64 v134, v133, v132, s[2:3]
	v_cndmask_b32_e64 v135, v132, v133, s[2:3]
	v_cndmask_b32_e64 v136, v129, v128, s[2:3]
	v_cndmask_b32_e64 v137, v128, v129, s[2:3]
	v_add_f32_dpp v138, v135, v134 quad_perm:[1,0,3,2] row_mask:0xf bank_mask:0xf bound_ctrl:1
	v_pk_mul_f32 v[150:151], v[64:65], v[76:77] op_sel:[0,0] op_sel_hi:[0,1]
	v_add_f32_dpp v139, v137, v136 quad_perm:[1,0,3,2] row_mask:0xf bank_mask:0xf bound_ctrl:1
	v_cndmask_b32_e64 v140, v139, v138, s[4:5]
	v_cndmask_b32_e64 v141, v138, v139, s[4:5]
	v_pk_mul_f32 v[152:153], v[64:65], v[76:77] op_sel:[1,0] op_sel_hi:[1,1]
	v_pk_mul_f32 v[154:155], v[66:67], v[76:77] op_sel:[0,0] op_sel_hi:[0,1]
	v_add_f32_dpp v142, v141, v140 quad_perm:[2,3,0,1] row_mask:0xf bank_mask:0xf bound_ctrl:1
	v_pk_mul_f32 v[156:157], v[66:67], v[76:77] op_sel:[1,0] op_sel_hi:[1,1]
	v_pk_fma_f32 v[150:151], v[120:121], v[56:57], v[150:151] op_sel:[0,0,0] op_sel_hi:[1,0,1]
	v_add_f32_dpp v142, v142, v142 row_ror:4 row_mask:0xf bank_mask:0xf bound_ctrl:1
	v_pk_fma_f32 v[152:153], v[122:123], v[56:57], v[152:153] op_sel:[0,1,0] op_sel_hi:[1,1,1]
	v_pk_fma_f32 v[154:155], v[124:125], v[58:59], v[154:155] op_sel:[0,0,0] op_sel_hi:[1,0,1]
	v_add_f32_dpp v146, v142, v142 row_ror:8 row_mask:0xf bank_mask:0xf bound_ctrl:1
	v_pk_fma_f32 v[156:157], v[126:127], v[58:59], v[156:157] op_sel:[0,1,0] op_sel_hi:[1,1,1]
	ds_read_b128 v[32:35], v196 offset:44544
	v_mov_b32_dpp v148, v146 quad_perm:[0,0,0,0] row_mask:0xf bank_mask:0xf
	v_mov_b32_dpp v149, v146 quad_perm:[1,1,1,1] row_mask:0xf bank_mask:0xf
	v_pk_fma_f32 v[120:121], v[72:73], v[148:149], v[150:151] op_sel:[0,0,0] op_sel_hi:[0,1,1]
	ds_read_b128 v[36:39], v196 offset:44800
	v_pk_fma_f32 v[122:123], v[72:73], v[148:149], v[152:153] op_sel:[1,0,0] op_sel_hi:[1,1,1]
	ds_read_b128 v[40:43], v196 offset:45056
	v_pk_fma_f32 v[124:125], v[74:75], v[148:149], v[154:155] op_sel:[0,0,0] op_sel_hi:[0,1,1]
	ds_read_b128 v[44:47], v196 offset:45312
	v_pk_fma_f32 v[126:127], v[74:75], v[148:149], v[156:157] op_sel:[1,0,0] op_sel_hi:[1,1,1]
	ds_read_b128 v[48:51], v196 offset:45568
	v_pk_mul_f32 v[132:133], v[120:121], v[92:93] op_sel:[0,0] op_sel_hi:[1,0]
	v_pk_mul_f32 v[128:129], v[120:121], v[60:61] op_sel:[0,0] op_sel_hi:[1,0]
	v_pk_fma_f32 v[132:133], v[122:123], v[92:93], v[132:133] op_sel:[0,1,0] op_sel_hi:[1,1,1]
	v_pk_fma_f32 v[128:129], v[122:123], v[60:61], v[128:129] op_sel:[0,1,0] op_sel_hi:[1,1,1]
	v_pk_fma_f32 v[132:133], v[124:125], v[94:95], v[132:133] op_sel:[0,0,0] op_sel_hi:[1,0,1]
	v_pk_fma_f32 v[128:129], v[124:125], v[62:63], v[128:129] op_sel:[0,0,0] op_sel_hi:[1,0,1]
	v_pk_fma_f32 v[132:133], v[126:127], v[94:95], v[132:133] op_sel:[0,1,0] op_sel_hi:[1,1,1]
	v_pk_fma_f32 v[128:129], v[126:127], v[62:63], v[128:129] op_sel:[0,1,0] op_sel_hi:[1,1,1]
	ds_read_b64 v[52:53], v197 offset:45824
	s_waitcnt lgkmcnt(6)
	v_cndmask_b32_e64 v134, v133, v132, s[2:3]
	v_cndmask_b32_e64 v135, v132, v133, s[2:3]
	v_cndmask_b32_e64 v136, v129, v128, s[2:3]
	v_cndmask_b32_e64 v137, v128, v129, s[2:3]
	v_add_f32_dpp v138, v135, v134 quad_perm:[1,0,3,2] row_mask:0xf bank_mask:0xf bound_ctrl:1
	v_pk_mul_f32 v[150:151], v[88:89], v[100:101] op_sel:[0,0] op_sel_hi:[0,1]
	v_add_f32_dpp v139, v137, v136 quad_perm:[1,0,3,2] row_mask:0xf bank_mask:0xf bound_ctrl:1
	v_cndmask_b32_e64 v140, v139, v138, s[4:5]
	v_cndmask_b32_e64 v141, v138, v139, s[4:5]
	v_pk_mul_f32 v[152:153], v[88:89], v[100:101] op_sel:[1,0] op_sel_hi:[1,1]
	v_pk_mul_f32 v[154:155], v[90:91], v[100:101] op_sel:[0,0] op_sel_hi:[0,1]
	v_add_f32_dpp v142, v141, v140 quad_perm:[2,3,0,1] row_mask:0xf bank_mask:0xf bound_ctrl:1
	v_pk_mul_f32 v[156:157], v[90:91], v[100:101] op_sel:[1,0] op_sel_hi:[1,1]
	v_pk_fma_f32 v[150:151], v[120:121], v[80:81], v[150:151] op_sel:[0,0,0] op_sel_hi:[1,0,1]
	v_add_f32_dpp v142, v142, v142 row_ror:4 row_mask:0xf bank_mask:0xf bound_ctrl:1
	v_pk_fma_f32 v[152:153], v[122:123], v[80:81], v[152:153] op_sel:[0,1,0] op_sel_hi:[1,1,1]
	v_pk_fma_f32 v[154:155], v[124:125], v[82:83], v[154:155] op_sel:[0,0,0] op_sel_hi:[1,0,1]
	v_add_f32_dpp v147, v142, v142 row_ror:8 row_mask:0xf bank_mask:0xf bound_ctrl:1
	v_pk_fma_f32 v[156:157], v[126:127], v[82:83], v[156:157] op_sel:[0,1,0] op_sel_hi:[1,1,1]
	ds_read_b128 v[56:59], v196 offset:46080
	v_mov_b32_dpp v148, v147 quad_perm:[0,0,0,0] row_mask:0xf bank_mask:0xf
	v_mov_b32_dpp v149, v147 quad_perm:[1,1,1,1] row_mask:0xf bank_mask:0xf
	v_pk_fma_f32 v[120:121], v[96:97], v[148:149], v[150:151] op_sel:[0,0,0] op_sel_hi:[0,1,1]
	ds_read_b128 v[60:63], v196 offset:46336
	v_pk_fma_f32 v[122:123], v[96:97], v[148:149], v[152:153] op_sel:[1,0,0] op_sel_hi:[1,1,1]
	ds_read_b128 v[64:67], v196 offset:46592
	v_pk_fma_f32 v[124:125], v[98:99], v[148:149], v[154:155] op_sel:[0,0,0] op_sel_hi:[0,1,1]
	ds_read_b128 v[68:71], v196 offset:46848
	v_pk_fma_f32 v[126:127], v[98:99], v[148:149], v[156:157] op_sel:[1,0,0] op_sel_hi:[1,1,1]
	ds_read_b128 v[72:75], v196 offset:47104
	v_pk_mul_f32 v[132:133], v[120:121], v[20:21] op_sel:[0,0] op_sel_hi:[1,0]
	v_pk_mul_f32 v[128:129], v[120:121], v[84:85] op_sel:[0,0] op_sel_hi:[1,0]
	v_pk_fma_f32 v[132:133], v[122:123], v[20:21], v[132:133] op_sel:[0,1,0] op_sel_hi:[1,1,1]
	v_pk_fma_f32 v[128:129], v[122:123], v[84:85], v[128:129] op_sel:[0,1,0] op_sel_hi:[1,1,1]
	v_pk_fma_f32 v[132:133], v[124:125], v[22:23], v[132:133] op_sel:[0,0,0] op_sel_hi:[1,0,1]
	v_pk_fma_f32 v[128:129], v[124:125], v[86:87], v[128:129] op_sel:[0,0,0] op_sel_hi:[1,0,1]
	v_pk_fma_f32 v[132:133], v[126:127], v[22:23], v[132:133] op_sel:[0,1,0] op_sel_hi:[1,1,1]
	v_pk_fma_f32 v[128:129], v[126:127], v[86:87], v[128:129] op_sel:[0,1,0] op_sel_hi:[1,1,1]
	ds_read_b64 v[76:77], v197 offset:47360
	v_cndmask_b32_e64 v106, v147, v146, s[12:13]
	v_cndmask_b32_e64 v106, v106, v145, s[10:11]
	v_cndmask_b32_e64 v106, v106, v144, s[6:7]
	s_and_saveexec_b64 s[28:29], s[8:9]
	global_store_dword v[104:105], v106, off
	s_mov_b64 exec, s[28:29]
	v_lshl_add_u64 v[104:105], v[104:105], 0, s[26:27]
	s_waitcnt lgkmcnt(6)
	v_cndmask_b32_e64 v134, v133, v132, s[2:3]
	v_cndmask_b32_e64 v135, v132, v133, s[2:3]
	v_cndmask_b32_e64 v136, v129, v128, s[2:3]
	v_cndmask_b32_e64 v137, v128, v129, s[2:3]
	v_add_f32_dpp v138, v135, v134 quad_perm:[1,0,3,2] row_mask:0xf bank_mask:0xf bound_ctrl:1
	v_pk_mul_f32 v[150:151], v[16:17], v[28:29] op_sel:[0,0] op_sel_hi:[0,1]
	v_add_f32_dpp v139, v137, v136 quad_perm:[1,0,3,2] row_mask:0xf bank_mask:0xf bound_ctrl:1
	v_cndmask_b32_e64 v140, v139, v138, s[4:5]
	v_cndmask_b32_e64 v141, v138, v139, s[4:5]
	v_pk_mul_f32 v[152:153], v[16:17], v[28:29] op_sel:[1,0] op_sel_hi:[1,1]
	v_pk_mul_f32 v[154:155], v[18:19], v[28:29] op_sel:[0,0] op_sel_hi:[0,1]
	v_add_f32_dpp v142, v141, v140 quad_perm:[2,3,0,1] row_mask:0xf bank_mask:0xf bound_ctrl:1
	v_pk_mul_f32 v[156:157], v[18:19], v[28:29] op_sel:[1,0] op_sel_hi:[1,1]
	v_pk_fma_f32 v[150:151], v[120:121], v[8:9], v[150:151] op_sel:[0,0,0] op_sel_hi:[1,0,1]
	v_add_f32_dpp v142, v142, v142 row_ror:4 row_mask:0xf bank_mask:0xf bound_ctrl:1
	v_pk_fma_f32 v[152:153], v[122:123], v[8:9], v[152:153] op_sel:[0,1,0] op_sel_hi:[1,1,1]
	v_pk_fma_f32 v[154:155], v[124:125], v[10:11], v[154:155] op_sel:[0,0,0] op_sel_hi:[1,0,1]
	v_add_f32_dpp v144, v142, v142 row_ror:8 row_mask:0xf bank_mask:0xf bound_ctrl:1
	v_pk_fma_f32 v[156:157], v[126:127], v[10:11], v[156:157] op_sel:[0,1,0] op_sel_hi:[1,1,1]
	ds_read_b128 v[80:83], v196 offset:47616
	v_mov_b32_dpp v148, v144 quad_perm:[0,0,0,0] row_mask:0xf bank_mask:0xf
	v_mov_b32_dpp v149, v144 quad_perm:[1,1,1,1] row_mask:0xf bank_mask:0xf
	v_pk_fma_f32 v[120:121], v[24:25], v[148:149], v[150:151] op_sel:[0,0,0] op_sel_hi:[0,1,1]
	ds_read_b128 v[84:87], v196 offset:47872
	v_pk_fma_f32 v[122:123], v[24:25], v[148:149], v[152:153] op_sel:[1,0,0] op_sel_hi:[1,1,1]
	ds_read_b128 v[88:91], v196 offset:48128
	v_pk_fma_f32 v[124:125], v[26:27], v[148:149], v[154:155] op_sel:[0,0,0] op_sel_hi:[0,1,1]
	ds_read_b128 v[92:95], v196 offset:48384
	v_pk_fma_f32 v[126:127], v[26:27], v[148:149], v[156:157] op_sel:[1,0,0] op_sel_hi:[1,1,1]
	ds_read_b128 v[96:99], v196 offset:48640
	v_pk_mul_f32 v[132:133], v[120:121], v[44:45] op_sel:[0,0] op_sel_hi:[1,0]
	v_pk_mul_f32 v[128:129], v[120:121], v[12:13] op_sel:[0,0] op_sel_hi:[1,0]
	v_pk_fma_f32 v[132:133], v[122:123], v[44:45], v[132:133] op_sel:[0,1,0] op_sel_hi:[1,1,1]
	v_pk_fma_f32 v[128:129], v[122:123], v[12:13], v[128:129] op_sel:[0,1,0] op_sel_hi:[1,1,1]
	v_pk_fma_f32 v[132:133], v[124:125], v[46:47], v[132:133] op_sel:[0,0,0] op_sel_hi:[1,0,1]
	v_pk_fma_f32 v[128:129], v[124:125], v[14:15], v[128:129] op_sel:[0,0,0] op_sel_hi:[1,0,1]
	v_pk_fma_f32 v[132:133], v[126:127], v[46:47], v[132:133] op_sel:[0,1,0] op_sel_hi:[1,1,1]
	v_pk_fma_f32 v[128:129], v[126:127], v[14:15], v[128:129] op_sel:[0,1,0] op_sel_hi:[1,1,1]
	ds_read_b64 v[100:101], v197 offset:48896
	s_waitcnt lgkmcnt(6)
	v_cndmask_b32_e64 v134, v133, v132, s[2:3]
	v_cndmask_b32_e64 v135, v132, v133, s[2:3]
	v_cndmask_b32_e64 v136, v129, v128, s[2:3]
	v_cndmask_b32_e64 v137, v128, v129, s[2:3]
	v_add_f32_dpp v138, v135, v134 quad_perm:[1,0,3,2] row_mask:0xf bank_mask:0xf bound_ctrl:1
	v_pk_mul_f32 v[150:151], v[40:41], v[52:53] op_sel:[0,0] op_sel_hi:[0,1]
	v_add_f32_dpp v139, v137, v136 quad_perm:[1,0,3,2] row_mask:0xf bank_mask:0xf bound_ctrl:1
	v_cndmask_b32_e64 v140, v139, v138, s[4:5]
	v_cndmask_b32_e64 v141, v138, v139, s[4:5]
	v_pk_mul_f32 v[152:153], v[40:41], v[52:53] op_sel:[1,0] op_sel_hi:[1,1]
	v_pk_mul_f32 v[154:155], v[42:43], v[52:53] op_sel:[0,0] op_sel_hi:[0,1]
	v_add_f32_dpp v142, v141, v140 quad_perm:[2,3,0,1] row_mask:0xf bank_mask:0xf bound_ctrl:1
	v_pk_mul_f32 v[156:157], v[42:43], v[52:53] op_sel:[1,0] op_sel_hi:[1,1]
	v_pk_fma_f32 v[150:151], v[120:121], v[32:33], v[150:151] op_sel:[0,0,0] op_sel_hi:[1,0,1]
	v_add_f32_dpp v142, v142, v142 row_ror:4 row_mask:0xf bank_mask:0xf bound_ctrl:1
	v_pk_fma_f32 v[152:153], v[122:123], v[32:33], v[152:153] op_sel:[0,1,0] op_sel_hi:[1,1,1]
	v_pk_fma_f32 v[154:155], v[124:125], v[34:35], v[154:155] op_sel:[0,0,0] op_sel_hi:[1,0,1]
	v_add_f32_dpp v145, v142, v142 row_ror:8 row_mask:0xf bank_mask:0xf bound_ctrl:1
	v_pk_fma_f32 v[156:157], v[126:127], v[34:35], v[156:157] op_sel:[0,1,0] op_sel_hi:[1,1,1]
	s_nop 0
	v_mov_b32_dpp v148, v145 quad_perm:[0,0,0,0] row_mask:0xf bank_mask:0xf
	v_mov_b32_dpp v149, v145 quad_perm:[1,1,1,1] row_mask:0xf bank_mask:0xf
	v_pk_fma_f32 v[120:121], v[48:49], v[148:149], v[150:151] op_sel:[0,0,0] op_sel_hi:[0,1,1]
	v_pk_fma_f32 v[122:123], v[48:49], v[148:149], v[152:153] op_sel:[1,0,0] op_sel_hi:[1,1,1]
	v_pk_fma_f32 v[124:125], v[50:51], v[148:149], v[154:155] op_sel:[0,0,0] op_sel_hi:[0,1,1]
	v_pk_fma_f32 v[126:127], v[50:51], v[148:149], v[156:157] op_sel:[1,0,0] op_sel_hi:[1,1,1]
	v_pk_mul_f32 v[132:133], v[120:121], v[68:69] op_sel:[0,0] op_sel_hi:[1,0]
	v_pk_mul_f32 v[128:129], v[120:121], v[36:37] op_sel:[0,0] op_sel_hi:[1,0]
	v_pk_fma_f32 v[132:133], v[122:123], v[68:69], v[132:133] op_sel:[0,1,0] op_sel_hi:[1,1,1]
	v_pk_fma_f32 v[128:129], v[122:123], v[36:37], v[128:129] op_sel:[0,1,0] op_sel_hi:[1,1,1]
	v_pk_fma_f32 v[132:133], v[124:125], v[70:71], v[132:133] op_sel:[0,0,0] op_sel_hi:[1,0,1]
	v_pk_fma_f32 v[128:129], v[124:125], v[38:39], v[128:129] op_sel:[0,0,0] op_sel_hi:[1,0,1]
	v_pk_fma_f32 v[132:133], v[126:127], v[70:71], v[132:133] op_sel:[0,1,0] op_sel_hi:[1,1,1]
	v_pk_fma_f32 v[128:129], v[126:127], v[38:39], v[128:129] op_sel:[0,1,0] op_sel_hi:[1,1,1]
	s_waitcnt lgkmcnt(0)
	v_cndmask_b32_e64 v134, v133, v132, s[2:3]
	v_cndmask_b32_e64 v135, v132, v133, s[2:3]
	v_cndmask_b32_e64 v136, v129, v128, s[2:3]
	v_cndmask_b32_e64 v137, v128, v129, s[2:3]
	v_add_f32_dpp v138, v135, v134 quad_perm:[1,0,3,2] row_mask:0xf bank_mask:0xf bound_ctrl:1
	v_pk_mul_f32 v[150:151], v[64:65], v[76:77] op_sel:[0,0] op_sel_hi:[0,1]
	v_add_f32_dpp v139, v137, v136 quad_perm:[1,0,3,2] row_mask:0xf bank_mask:0xf bound_ctrl:1
	v_cndmask_b32_e64 v140, v139, v138, s[4:5]
	v_cndmask_b32_e64 v141, v138, v139, s[4:5]
	v_pk_mul_f32 v[152:153], v[64:65], v[76:77] op_sel:[1,0] op_sel_hi:[1,1]
	v_pk_mul_f32 v[154:155], v[66:67], v[76:77] op_sel:[0,0] op_sel_hi:[0,1]
	v_add_f32_dpp v142, v141, v140 quad_perm:[2,3,0,1] row_mask:0xf bank_mask:0xf bound_ctrl:1
	v_pk_mul_f32 v[156:157], v[66:67], v[76:77] op_sel:[1,0] op_sel_hi:[1,1]
	v_pk_fma_f32 v[150:151], v[120:121], v[56:57], v[150:151] op_sel:[0,0,0] op_sel_hi:[1,0,1]
	v_add_f32_dpp v142, v142, v142 row_ror:4 row_mask:0xf bank_mask:0xf bound_ctrl:1
	v_pk_fma_f32 v[152:153], v[122:123], v[56:57], v[152:153] op_sel:[0,1,0] op_sel_hi:[1,1,1]
	v_pk_fma_f32 v[154:155], v[124:125], v[58:59], v[154:155] op_sel:[0,0,0] op_sel_hi:[1,0,1]
	v_add_f32_dpp v146, v142, v142 row_ror:8 row_mask:0xf bank_mask:0xf bound_ctrl:1
	v_pk_fma_f32 v[156:157], v[126:127], v[58:59], v[156:157] op_sel:[0,1,0] op_sel_hi:[1,1,1]
	s_nop 0
	v_mov_b32_dpp v148, v146 quad_perm:[0,0,0,0] row_mask:0xf bank_mask:0xf
	v_mov_b32_dpp v149, v146 quad_perm:[1,1,1,1] row_mask:0xf bank_mask:0xf
	v_pk_fma_f32 v[120:121], v[72:73], v[148:149], v[150:151] op_sel:[0,0,0] op_sel_hi:[0,1,1]
	v_pk_fma_f32 v[122:123], v[72:73], v[148:149], v[152:153] op_sel:[1,0,0] op_sel_hi:[1,1,1]
	v_pk_fma_f32 v[124:125], v[74:75], v[148:149], v[154:155] op_sel:[0,0,0] op_sel_hi:[0,1,1]
	v_pk_fma_f32 v[126:127], v[74:75], v[148:149], v[156:157] op_sel:[1,0,0] op_sel_hi:[1,1,1]
	v_pk_mul_f32 v[132:133], v[120:121], v[92:93] op_sel:[0,0] op_sel_hi:[1,0]
	v_pk_mul_f32 v[128:129], v[120:121], v[60:61] op_sel:[0,0] op_sel_hi:[1,0]
	v_pk_fma_f32 v[132:133], v[122:123], v[92:93], v[132:133] op_sel:[0,1,0] op_sel_hi:[1,1,1]
	v_pk_fma_f32 v[128:129], v[122:123], v[60:61], v[128:129] op_sel:[0,1,0] op_sel_hi:[1,1,1]
	v_pk_fma_f32 v[132:133], v[124:125], v[94:95], v[132:133] op_sel:[0,0,0] op_sel_hi:[1,0,1]
	v_pk_fma_f32 v[128:129], v[124:125], v[62:63], v[128:129] op_sel:[0,0,0] op_sel_hi:[1,0,1]
	v_pk_fma_f32 v[132:133], v[126:127], v[94:95], v[132:133] op_sel:[0,1,0] op_sel_hi:[1,1,1]
	v_pk_fma_f32 v[128:129], v[126:127], v[62:63], v[128:129] op_sel:[0,1,0] op_sel_hi:[1,1,1]
	v_cndmask_b32_e64 v134, v133, v132, s[2:3]
	v_cndmask_b32_e64 v135, v132, v133, s[2:3]
	v_cndmask_b32_e64 v136, v129, v128, s[2:3]
	v_cndmask_b32_e64 v137, v128, v129, s[2:3]
	v_add_f32_dpp v138, v135, v134 quad_perm:[1,0,3,2] row_mask:0xf bank_mask:0xf bound_ctrl:1
	v_pk_mul_f32 v[150:151], v[88:89], v[100:101] op_sel:[0,0] op_sel_hi:[0,1]
	v_add_f32_dpp v139, v137, v136 quad_perm:[1,0,3,2] row_mask:0xf bank_mask:0xf bound_ctrl:1
	v_cndmask_b32_e64 v140, v139, v138, s[4:5]
	v_cndmask_b32_e64 v141, v138, v139, s[4:5]
	v_pk_mul_f32 v[152:153], v[88:89], v[100:101] op_sel:[1,0] op_sel_hi:[1,1]
	v_pk_mul_f32 v[154:155], v[90:91], v[100:101] op_sel:[0,0] op_sel_hi:[0,1]
	v_add_f32_dpp v142, v141, v140 quad_perm:[2,3,0,1] row_mask:0xf bank_mask:0xf bound_ctrl:1
	v_pk_mul_f32 v[156:157], v[90:91], v[100:101] op_sel:[1,0] op_sel_hi:[1,1]
	v_pk_fma_f32 v[150:151], v[120:121], v[80:81], v[150:151] op_sel:[0,0,0] op_sel_hi:[1,0,1]
	v_add_f32_dpp v142, v142, v142 row_ror:4 row_mask:0xf bank_mask:0xf bound_ctrl:1
	v_pk_fma_f32 v[152:153], v[122:123], v[80:81], v[152:153] op_sel:[0,1,0] op_sel_hi:[1,1,1]
	v_pk_fma_f32 v[154:155], v[124:125], v[82:83], v[154:155] op_sel:[0,0,0] op_sel_hi:[1,0,1]
	v_add_f32_dpp v147, v142, v142 row_ror:8 row_mask:0xf bank_mask:0xf bound_ctrl:1
	v_pk_fma_f32 v[156:157], v[126:127], v[82:83], v[156:157] op_sel:[0,1,0] op_sel_hi:[1,1,1]
	s_nop 0
	v_mov_b32_dpp v148, v147 quad_perm:[0,0,0,0] row_mask:0xf bank_mask:0xf
	v_mov_b32_dpp v149, v147 quad_perm:[1,1,1,1] row_mask:0xf bank_mask:0xf
	v_pk_fma_f32 v[120:121], v[96:97], v[148:149], v[150:151] op_sel:[0,0,0] op_sel_hi:[0,1,1]
	v_pk_fma_f32 v[122:123], v[96:97], v[148:149], v[152:153] op_sel:[1,0,0] op_sel_hi:[1,1,1]
	v_pk_fma_f32 v[124:125], v[98:99], v[148:149], v[154:155] op_sel:[0,0,0] op_sel_hi:[0,1,1]
	v_pk_fma_f32 v[126:127], v[98:99], v[148:149], v[156:157] op_sel:[1,0,0] op_sel_hi:[1,1,1]
	v_pk_mul_f32 v[128:129], v[120:121], v[84:85] op_sel:[0,0] op_sel_hi:[1,0]
	v_pk_fma_f32 v[128:129], v[122:123], v[84:85], v[128:129] op_sel:[0,1,0] op_sel_hi:[1,1,1]
	v_pk_fma_f32 v[128:129], v[124:125], v[86:87], v[128:129] op_sel:[0,0,0] op_sel_hi:[1,0,1]
	v_pk_fma_f32 v[128:129], v[126:127], v[86:87], v[128:129] op_sel:[0,1,0] op_sel_hi:[1,1,1]
	v_cndmask_b32_e64 v106, v147, v146, s[12:13]
	v_cndmask_b32_e64 v106, v106, v145, s[10:11]
	v_cndmask_b32_e64 v106, v106, v144, s[6:7]
	s_and_saveexec_b64 s[28:29], s[8:9]
	global_store_dword v[104:105], v106, off
	s_mov_b64 exec, s[28:29]
	v_mov_b32_e32 v16, v128
	v_mov_b32_e32 v17, v129
	s_mov_b64 s[22:23], -1
	s_and_b64 vcc, exec, s[18:19]
	s_cbranch_vccnz .LBB0_1194

.LBB0_2807:
	s_sleep 1
	global_load_dword v2, v1, s[14:15] sc1
	s_add_i32 s5, s4, 1
	s_cmp_lt_u32 s4, 0x1000000
	s_mov_b32 s4, s5
	s_cselect_b64 s[6:7], -1, 0
	s_waitcnt vmcnt(0)
	v_readfirstlane_b32 s5, v2
	s_cmp_eq_u32 s5, 0
	s_cselect_b64 s[8:9], -1, 0
	s_and_b64 s[6:7], s[6:7], s[8:9]
	s_and_b64 vcc, exec, s[6:7]
	s_cbranch_vccnz .LBB0_2807
	s_ashr_i32 s6, s1, 1
	s_lshl_b32 s1, s1, 5
	s_lshl_b32 s4, s0, 3
	s_and_b32 s1, s1, 32
	s_and_b32 s4, s4, 24
	s_or_b32 s7, s4, s1
	s_lshl_b32 s4, s6, 6
	s_ashr_i32 s5, s4, 31
	s_lshl_b64 s[4:5], s[4:5], 2
	s_add_u32 s4, s2, s4
	s_addc_u32 s5, s3, s5
	s_mul_hi_i32 s1, s6, 0xc00000
	s_mul_i32 s6, s6, 0xc00000
	s_add_u32 s2, s2, s6
	s_mul_i32 s9, s0, 0x1800
	s_addc_u32 s1, s3, s1
	v_lshlrev_b32_e32 v2, 4, v0
	s_mul_hi_i32 s8, s0, 0x1800
	s_add_u32 s2, s2, s9
	v_ashrrev_i32_e32 v3, 31, v2
	s_addc_u32 s3, s1, s8
	v_lshl_add_u64 v[2:3], s[2:3], 0, v[2:3]
	s_add_i32 s1, s9, 0
	v_lshl_add_u64 v[184:185], v[2:3], 0, s[60:61]
	s_mov_b32 m0, s1
	v_lshl_add_u64 v[4:5], v[2:3], 0, s[68:69]
	global_load_lds_dwordx4 v[184:185], off sc1
	s_add_i32 m0, s1, 0x400
	s_mov_b64 s[2:3], 0x44c00800
	global_load_lds_dwordx4 v[4:5], off sc1
	v_lshl_add_u64 v[4:5], v[2:3], 0, s[2:3]
	s_add_i32 m0, s1, 0x800
	s_mov_b64 s[2:3], 0x44c00c00
	global_load_lds_dwordx4 v[4:5], off sc1
	v_lshl_add_u64 v[4:5], v[2:3], 0, s[2:3]
	s_add_i32 m0, s1, 0xc00
	s_mov_b64 s[2:3], 0x44c01000
	global_load_lds_dwordx4 v[4:5], off sc1
	v_lshl_add_u64 v[4:5], v[2:3], 0, s[2:3]
	s_add_i32 m0, s1, 0x1000
	s_mov_b64 s[2:3], 0x44c01400
	global_load_lds_dwordx4 v[4:5], off sc1
	v_lshl_add_u64 v[2:3], v[2:3], 0, s[2:3]
	s_add_i32 m0, s1, 0x1400
	s_mov_b64 s[2:3], 0x5cd00000
	global_load_lds_dwordx4 v[2:3], off sc1
	global_load_dword v195, v1, s[14:15] offset:16 sc1
	v_ashrrev_i32_e32 v2, 3, v0
	v_and_b32_e32 v2, -2, v2
	v_add_u32_e32 v2, s7, v2
	v_ashrrev_i32_e32 v3, 31, v2
	v_lshl_add_u64 v[4:5], v[2:3], 2, s[4:5]
	v_and_b32_e32 v189, 1, v0
	v_lshl_add_u64 v[182:183], v[4:5], 0, s[2:3]
	v_and_b32_e32 v188, 15, v0
	v_lshlrev_b32_e32 v190, 2, v2
	v_and_b32_e32 v2, 2, v0
	s_cmp_lt_i32 s0, 4
	v_bfe_u32 v3, v0, 2, 2
	v_lshlrev_b32_e32 v0, 2, v189
	v_lshlrev_b32_e32 v191, 4, v188
	s_cselect_b64 s[16:17], -1, 0
	s_cmp_gt_i32 s0, 3
	v_lshl_add_u64 v[186:187], v[182:183], 0, v[0:1]
	v_mov_b32_e32 v0, v1
	s_mov_b32 s25, 0
	v_cmp_eq_u32_e64 s[2:3], 0, v189
	v_cmp_eq_u32_e64 s[4:5], 0, v2
	s_cselect_b64 s[18:19], -1, 0
	v_add_u32_e32 v192, 0, v191
	v_cmp_gt_u32_e64 s[6:7], 4, v188
	v_add_u32_e32 v193, -1, v3
	v_cmp_ne_u32_e64 s[8:9], 0, v2
	v_cmp_eq_u32_e64 s[10:11], 1, v3
	v_cmp_eq_u32_e64 s[12:13], 2, v3
	v_add_u32_e32 v194, 3, v3
	v_mov_b64_e32 v[58:59], v[0:1]
	v_mov_b64_e32 v[60:61], v[0:1]
	v_mov_b64_e32 v[66:67], v[0:1]
	v_mov_b64_e32 v[68:69], v[0:1]
	v_mov_b64_e32 v[74:75], v[0:1]
	v_mov_b64_e32 v[76:77], v[0:1]
	v_mov_b64_e32 v[120:121], v[0:1]
	v_mov_b64_e32 v[122:123], v[0:1]
	v_mov_b64_e32 v[124:125], v[0:1]
	v_mov_b64_e32 v[126:127], v[0:1]
	v_mov_b64_e32 v[128:129], v[0:1]
	s_waitcnt vmcnt(0) lgkmcnt(0)
	s_barrier

.LBB0_2817:
	s_cmpk_eq_i32 s0, 0x100
	s_cbranch_scc0 .LBB0_2839
	s_branch .LBB0_2840

.LBB0_2819:
	s_mul_i32 s22, s24, 0xc000
	s_lshl_b32 s23, s25, 5
	v_add_u32_e32 v196, s22, v191
	v_add_u32_e32 v197, s22, v190
	v_add_u32_e32 v104, s23, v193
	s_mov_b64 s[26:27], 0x8000
	s_andn2_b64 s[30:31], s[8:9], s[6:7]
	s_cmp_eq_u32 s25, 0
	s_cselect_b64 s[30:31], s[30:31], s[8:9]
	ds_read_b128 v[8:11], v196 offset:0
	ds_read_b128 v[12:15], v196 offset:256
	ds_read_b128 v[16:19], v196 offset:512
	ds_read_b128 v[20:23], v196 offset:768
	ds_read_b128 v[24:27], v196 offset:1024
	ds_read_b64 v[28:29], v197 offset:1280
	ds_read_b128 v[32:35], v196 offset:1536
	ds_read_b128 v[36:39], v196 offset:1792
	ds_read_b128 v[40:43], v196 offset:2048
	ds_read_b128 v[44:47], v196 offset:2304
	ds_read_b128 v[48:51], v196 offset:2560
	ds_read_b64 v[52:53], v197 offset:2816
	v_ashrrev_i32_e32 v105, 31, v104
	v_lshlrev_b64 v[104:105], 13, v[104:105]
	v_lshl_add_u64 v[104:105], v[104:105], 0, v[186:187]
	s_waitcnt lgkmcnt(6)
	ds_read_b128 v[56:59], v196 offset:3072
	ds_read_b128 v[60:63], v196 offset:3328
	ds_read_b128 v[64:67], v196 offset:3584
	ds_read_b128 v[68:71], v196 offset:3840
	ds_read_b128 v[72:75], v196 offset:4096
	ds_read_b64 v[76:77], v197 offset:4352
	v_pk_mul_f32 v[132:133], v[120:121], v[20:21] op_sel:[0,0] op_sel_hi:[1,0]
	v_pk_fma_f32 v[132:133], v[122:123], v[20:21], v[132:133] op_sel:[0,1,0] op_sel_hi:[1,1,1]
	v_pk_fma_f32 v[132:133], v[124:125], v[22:23], v[132:133] op_sel:[0,0,0] op_sel_hi:[1,0,1]
	v_pk_fma_f32 v[132:133], v[126:127], v[22:23], v[132:133] op_sel:[0,1,0] op_sel_hi:[1,1,1]
	s_waitcnt lgkmcnt(6)
	v_cndmask_b32_e64 v134, v133, v132, s[2:3]
	v_cndmask_b32_e64 v135, v132, v133, s[2:3]
	v_cndmask_b32_e64 v136, v129, v128, s[2:3]
	v_cndmask_b32_e64 v137, v128, v129, s[2:3]
	v_add_f32_dpp v138, v135, v134 quad_perm:[1,0,3,2] row_mask:0xf bank_mask:0xf bound_ctrl:1
	v_pk_mul_f32 v[150:151], v[16:17], v[28:29] op_sel:[0,0] op_sel_hi:[0,1]
	v_add_f32_dpp v139, v137, v136 quad_perm:[1,0,3,2] row_mask:0xf bank_mask:0xf bound_ctrl:1
	v_cndmask_b32_e64 v140, v139, v138, s[4:5]
	v_cndmask_b32_e64 v141, v138, v139, s[4:5]
	v_pk_mul_f32 v[152:153], v[16:17], v[28:29] op_sel:[1,0] op_sel_hi:[1,1]
	v_pk_mul_f32 v[154:155], v[18:19], v[28:29] op_sel:[0,0] op_sel_hi:[0,1]
	v_add_f32_dpp v142, v141, v140 quad_perm:[2,3,0,1] row_mask:0xf bank_mask:0xf bound_ctrl:1
	v_pk_mul_f32 v[156:157], v[18:19], v[28:29] op_sel:[1,0] op_sel_hi:[1,1]
	v_pk_fma_f32 v[150:151], v[120:121], v[8:9], v[150:151] op_sel:[0,0,0] op_sel_hi:[1,0,1]
	v_add_f32_dpp v142, v142, v142 row_ror:4 row_mask:0xf bank_mask:0xf bound_ctrl:1
	v_pk_fma_f32 v[152:153], v[122:123], v[8:9], v[152:153] op_sel:[0,1,0] op_sel_hi:[1,1,1]
	v_pk_fma_f32 v[154:155], v[124:125], v[10:11], v[154:155] op_sel:[0,0,0] op_sel_hi:[1,0,1]
	v_add_f32_dpp v144, v142, v142 row_ror:8 row_mask:0xf bank_mask:0xf bound_ctrl:1
	v_pk_fma_f32 v[156:157], v[126:127], v[10:11], v[156:157] op_sel:[0,1,0] op_sel_hi:[1,1,1]
	ds_read_b128 v[80:83], v196 offset:4608
	v_mov_b32_dpp v148, v144 quad_perm:[0,0,0,0] row_mask:0xf bank_mask:0xf
	v_mov_b32_dpp v149, v144 quad_perm:[1,1,1,1] row_mask:0xf bank_mask:0xf
	v_pk_fma_f32 v[120:121], v[24:25], v[148:149], v[150:151] op_sel:[0,0,0] op_sel_hi:[0,1,1]
	ds_read_b128 v[84:87], v196 offset:4864
	v_pk_fma_f32 v[122:123], v[24:25], v[148:149], v[152:153] op_sel:[1,0,0] op_sel_hi:[1,1,1]
	ds_read_b128 v[88:91], v196 offset:5120
	v_pk_fma_f32 v[124:125], v[26:27], v[148:149], v[154:155] op_sel:[0,0,0] op_sel_hi:[0,1,1]
	ds_read_b128 v[92:95], v196 offset:5376
	v_pk_fma_f32 v[126:127], v[26:27], v[148:149], v[156:157] op_sel:[1,0,0] op_sel_hi:[1,1,1]
	ds_read_b128 v[96:99], v196 offset:5632
	v_pk_mul_f32 v[132:133], v[120:121], v[44:45] op_sel:[0,0] op_sel_hi:[1,0]
	v_pk_mul_f32 v[128:129], v[120:121], v[12:13] op_sel:[0,0] op_sel_hi:[1,0]
	v_pk_fma_f32 v[132:133], v[122:123], v[44:45], v[132:133] op_sel:[0,1,0] op_sel_hi:[1,1,1]
	v_pk_fma_f32 v[128:129], v[122:123], v[12:13], v[128:129] op_sel:[0,1,0] op_sel_hi:[1,1,1]
	v_pk_fma_f32 v[132:133], v[124:125], v[46:47], v[132:133] op_sel:[0,0,0] op_sel_hi:[1,0,1]
	v_pk_fma_f32 v[128:129], v[124:125], v[14:15], v[128:129] op_sel:[0,0,0] op_sel_hi:[1,0,1]
	v_pk_fma_f32 v[132:133], v[126:127], v[46:47], v[132:133] op_sel:[0,1,0] op_sel_hi:[1,1,1]
	v_pk_fma_f32 v[128:129], v[126:127], v[14:15], v[128:129] op_sel:[0,1,0] op_sel_hi:[1,1,1]
	ds_read_b64 v[100:101], v197 offset:5888
	s_waitcnt lgkmcnt(6)
	v_cndmask_b32_e64 v134, v133, v132, s[2:3]
	v_cndmask_b32_e64 v135, v132, v133, s[2:3]
	v_cndmask_b32_e64 v136, v129, v128, s[2:3]
	v_cndmask_b32_e64 v137, v128, v129, s[2:3]
	v_add_f32_dpp v138, v135, v134 quad_perm:[1,0,3,2] row_mask:0xf bank_mask:0xf bound_ctrl:1
	v_pk_mul_f32 v[150:151], v[40:41], v[52:53] op_sel:[0,0] op_sel_hi:[0,1]
	v_add_f32_dpp v139, v137, v136 quad_perm:[1,0,3,2] row_mask:0xf bank_mask:0xf bound_ctrl:1
	v_cndmask_b32_e64 v140, v139, v138, s[4:5]
	v_cndmask_b32_e64 v141, v138, v139, s[4:5]
	v_pk_mul_f32 v[152:153], v[40:41], v[52:53] op_sel:[1,0] op_sel_hi:[1,1]
	v_pk_mul_f32 v[154:155], v[42:43], v[52:53] op_sel:[0,0] op_sel_hi:[0,1]
	v_add_f32_dpp v142, v141, v140 quad_perm:[2,3,0,1] row_mask:0xf bank_mask:0xf bound_ctrl:1
	v_pk_mul_f32 v[156:157], v[42:43], v[52:53] op_sel:[1,0] op_sel_hi:[1,1]
	v_pk_fma_f32 v[150:151], v[120:121], v[32:33], v[150:151] op_sel:[0,0,0] op_sel_hi:[1,0,1]
	v_add_f32_dpp v142, v142, v142 row_ror:4 row_mask:0xf bank_mask:0xf bound_ctrl:1
	v_pk_fma_f32 v[152:153], v[122:123], v[32:33], v[152:153] op_sel:[0,1,0] op_sel_hi:[1,1,1]
	v_pk_fma_f32 v[154:155], v[124:125], v[34:35], v[154:155] op_sel:[0,0,0] op_sel_hi:[1,0,1]
	v_add_f32_dpp v145, v142, v142 row_ror:8 row_mask:0xf bank_mask:0xf bound_ctrl:1
	v_pk_fma_f32 v[156:157], v[126:127], v[34:35], v[156:157] op_sel:[0,1,0] op_sel_hi:[1,1,1]
	ds_read_b128 v[8:11], v196 offset:6144
	v_mov_b32_dpp v148, v145 quad_perm:[0,0,0,0] row_mask:0xf bank_mask:0xf
	v_mov_b32_dpp v149, v145 quad_perm:[1,1,1,1] row_mask:0xf bank_mask:0xf
	v_pk_fma_f32 v[120:121], v[48:49], v[148:149], v[150:151] op_sel:[0,0,0] op_sel_hi:[0,1,1]
	ds_read_b128 v[12:15], v196 offset:6400
	v_pk_fma_f32 v[122:123], v[48:49], v[148:149], v[152:153] op_sel:[1,0,0] op_sel_hi:[1,1,1]
	ds_read_b128 v[16:19], v196 offset:6656
	v_pk_fma_f32 v[124:125], v[50:51], v[148:149], v[154:155] op_sel:[0,0,0] op_sel_hi:[0,1,1]
	ds_read_b128 v[20:23], v196 offset:6912
	v_pk_fma_f32 v[126:127], v[50:51], v[148:149], v[156:157] op_sel:[1,0,0] op_sel_hi:[1,1,1]
	ds_read_b128 v[24:27], v196 offset:7168
	v_pk_mul_f32 v[132:133], v[120:121], v[68:69] op_sel:[0,0] op_sel_hi:[1,0]
	v_pk_mul_f32 v[128:129], v[120:121], v[36:37] op_sel:[0,0] op_sel_hi:[1,0]
	v_pk_fma_f32 v[132:133], v[122:123], v[68:69], v[132:133] op_sel:[0,1,0] op_sel_hi:[1,1,1]
	v_pk_fma_f32 v[128:129], v[122:123], v[36:37], v[128:129] op_sel:[0,1,0] op_sel_hi:[1,1,1]
	v_pk_fma_f32 v[132:133], v[124:125], v[70:71], v[132:133] op_sel:[0,0,0] op_sel_hi:[1,0,1]
	v_pk_fma_f32 v[128:129], v[124:125], v[38:39], v[128:129] op_sel:[0,0,0] op_sel_hi:[1,0,1]
	v_pk_fma_f32 v[132:133], v[126:127], v[70:71], v[132:133] op_sel:[0,1,0] op_sel_hi:[1,1,1]
	v_pk_fma_f32 v[128:129], v[126:127], v[38:39], v[128:129] op_sel:[0,1,0] op_sel_hi:[1,1,1]
	ds_read_b64 v[28:29], v197 offset:7424
	s_waitcnt lgkmcnt(6)
	v_cndmask_b32_e64 v134, v133, v132, s[2:3]
	v_cndmask_b32_e64 v135, v132, v133, s[2:3]
	v_cndmask_b32_e64 v136, v129, v128, s[2:3]
	v_cndmask_b32_e64 v137, v128, v129, s[2:3]
	v_add_f32_dpp v138, v135, v134 quad_perm:[1,0,3,2] row_mask:0xf bank_mask:0xf bound_ctrl:1
	v_pk_mul_f32 v[150:151], v[64:65], v[76:77] op_sel:[0,0] op_sel_hi:[0,1]
	v_add_f32_dpp v139, v137, v136 quad_perm:[1,0,3,2] row_mask:0xf bank_mask:0xf bound_ctrl:1
	v_cndmask_b32_e64 v140, v139, v138, s[4:5]
	v_cndmask_b32_e64 v141, v138, v139, s[4:5]
	v_pk_mul_f32 v[152:153], v[64:65], v[76:77] op_sel:[1,0] op_sel_hi:[1,1]
	v_pk_mul_f32 v[154:155], v[66:67], v[76:77] op_sel:[0,0] op_sel_hi:[0,1]
	v_add_f32_dpp v142, v141, v140 quad_perm:[2,3,0,1] row_mask:0xf bank_mask:0xf bound_ctrl:1
	v_pk_mul_f32 v[156:157], v[66:67], v[76:77] op_sel:[1,0] op_sel_hi:[1,1]
	v_pk_fma_f32 v[150:151], v[120:121], v[56:57], v[150:151] op_sel:[0,0,0] op_sel_hi:[1,0,1]
	v_add_f32_dpp v142, v142, v142 row_ror:4 row_mask:0xf bank_mask:0xf bound_ctrl:1
	v_pk_fma_f32 v[152:153], v[122:123], v[56:57], v[152:153] op_sel:[0,1,0] op_sel_hi:[1,1,1]
	v_pk_fma_f32 v[154:155], v[124:125], v[58:59], v[154:155] op_sel:[0,0,0] op_sel_hi:[1,0,1]
	v_add_f32_dpp v146, v142, v142 row_ror:8 row_mask:0xf bank_mask:0xf bound_ctrl:1
	v_pk_fma_f32 v[156:157], v[126:127], v[58:59], v[156:157] op_sel:[0,1,0] op_sel_hi:[1,1,1]
	ds_read_b128 v[32:35], v196 offset:7680
	v_mov_b32_dpp v148, v146 quad_perm:[0,0,0,0] row_mask:0xf bank_mask:0xf
	v_mov_b32_dpp v149, v146 quad_perm:[1,1,1,1] row_mask:0xf bank_mask:0xf
	v_pk_fma_f32 v[120:121], v[72:73], v[148:149], v[150:151] op_sel:[0,0,0] op_sel_hi:[0,1,1]
	ds_read_b128 v[36:39], v196 offset:7936
	v_pk_fma_f32 v[122:123], v[72:73], v[148:149], v[152:153] op_sel:[1,0,0] op_sel_hi:[1,1,1]
	ds_read_b128 v[40:43], v196 offset:8192
	v_pk_fma_f32 v[124:125], v[74:75], v[148:149], v[154:155] op_sel:[0,0,0] op_sel_hi:[0,1,1]
	ds_read_b128 v[44:47], v196 offset:8448
	v_pk_fma_f32 v[126:127], v[74:75], v[148:149], v[156:157] op_sel:[1,0,0] op_sel_hi:[1,1,1]
	ds_read_b128 v[48:51], v196 offset:8704
	v_pk_mul_f32 v[132:133], v[120:121], v[92:93] op_sel:[0,0] op_sel_hi:[1,0]
	v_pk_mul_f32 v[128:129], v[120:121], v[60:61] op_sel:[0,0] op_sel_hi:[1,0]
	v_pk_fma_f32 v[132:133], v[122:123], v[92:93], v[132:133] op_sel:[0,1,0] op_sel_hi:[1,1,1]
	v_pk_fma_f32 v[128:129], v[122:123], v[60:61], v[128:129] op_sel:[0,1,0] op_sel_hi:[1,1,1]
	v_pk_fma_f32 v[132:133], v[124:125], v[94:95], v[132:133] op_sel:[0,0,0] op_sel_hi:[1,0,1]
	v_pk_fma_f32 v[128:129], v[124:125], v[62:63], v[128:129] op_sel:[0,0,0] op_sel_hi:[1,0,1]
	v_pk_fma_f32 v[132:133], v[126:127], v[94:95], v[132:133] op_sel:[0,1,0] op_sel_hi:[1,1,1]
	v_pk_fma_f32 v[128:129], v[126:127], v[62:63], v[128:129] op_sel:[0,1,0] op_sel_hi:[1,1,1]
	ds_read_b64 v[52:53], v197 offset:8960
	s_waitcnt lgkmcnt(6)
	v_cndmask_b32_e64 v134, v133, v132, s[2:3]
	v_cndmask_b32_e64 v135, v132, v133, s[2:3]
	v_cndmask_b32_e64 v136, v129, v128, s[2:3]
	v_cndmask_b32_e64 v137, v128, v129, s[2:3]
	v_add_f32_dpp v138, v135, v134 quad_perm:[1,0,3,2] row_mask:0xf bank_mask:0xf bound_ctrl:1
	v_pk_mul_f32 v[150:151], v[88:89], v[100:101] op_sel:[0,0] op_sel_hi:[0,1]
	v_add_f32_dpp v139, v137, v136 quad_perm:[1,0,3,2] row_mask:0xf bank_mask:0xf bound_ctrl:1
	v_cndmask_b32_e64 v140, v139, v138, s[4:5]
	v_cndmask_b32_e64 v141, v138, v139, s[4:5]
	v_pk_mul_f32 v[152:153], v[88:89], v[100:101] op_sel:[1,0] op_sel_hi:[1,1]
	v_pk_mul_f32 v[154:155], v[90:91], v[100:101] op_sel:[0,0] op_sel_hi:[0,1]
	v_add_f32_dpp v142, v141, v140 quad_perm:[2,3,0,1] row_mask:0xf bank_mask:0xf bound_ctrl:1
	v_pk_mul_f32 v[156:157], v[90:91], v[100:101] op_sel:[1,0] op_sel_hi:[1,1]
	v_pk_fma_f32 v[150:151], v[120:121], v[80:81], v[150:151] op_sel:[0,0,0] op_sel_hi:[1,0,1]
	v_add_f32_dpp v142, v142, v142 row_ror:4 row_mask:0xf bank_mask:0xf bound_ctrl:1
	v_pk_fma_f32 v[152:153], v[122:123], v[80:81], v[152:153] op_sel:[0,1,0] op_sel_hi:[1,1,1]
	v_pk_fma_f32 v[154:155], v[124:125], v[82:83], v[154:155] op_sel:[0,0,0] op_sel_hi:[1,0,1]
	v_add_f32_dpp v147, v142, v142 row_ror:8 row_mask:0xf bank_mask:0xf bound_ctrl:1
	v_pk_fma_f32 v[156:157], v[126:127], v[82:83], v[156:157] op_sel:[0,1,0] op_sel_hi:[1,1,1]
	ds_read_b128 v[56:59], v196 offset:9216
	v_mov_b32_dpp v148, v147 quad_perm:[0,0,0,0] row_mask:0xf bank_mask:0xf
	v_mov_b32_dpp v149, v147 quad_perm:[1,1,1,1] row_mask:0xf bank_mask:0xf
	v_pk_fma_f32 v[120:121], v[96:97], v[148:149], v[150:151] op_sel:[0,0,0] op_sel_hi:[0,1,1]
	ds_read_b128 v[60:63], v196 offset:9472
	v_pk_fma_f32 v[122:123], v[96:97], v[148:149], v[152:153] op_sel:[1,0,0] op_sel_hi:[1,1,1]
	ds_read_b128 v[64:67], v196 offset:9728
	v_pk_fma_f32 v[124:125], v[98:99], v[148:149], v[154:155] op_sel:[0,0,0] op_sel_hi:[0,1,1]
	ds_read_b128 v[68:71], v196 offset:9984
	v_pk_fma_f32 v[126:127], v[98:99], v[148:149], v[156:157] op_sel:[1,0,0] op_sel_hi:[1,1,1]
	ds_read_b128 v[72:75], v196 offset:10240
	v_pk_mul_f32 v[132:133], v[120:121], v[20:21] op_sel:[0,0] op_sel_hi:[1,0]
	v_pk_mul_f32 v[128:129], v[120:121], v[84:85] op_sel:[0,0] op_sel_hi:[1,0]
	v_pk_fma_f32 v[132:133], v[122:123], v[20:21], v[132:133] op_sel:[0,1,0] op_sel_hi:[1,1,1]
	v_pk_fma_f32 v[128:129], v[122:123], v[84:85], v[128:129] op_sel:[0,1,0] op_sel_hi:[1,1,1]
	v_pk_fma_f32 v[132:133], v[124:125], v[22:23], v[132:133] op_sel:[0,0,0] op_sel_hi:[1,0,1]
	v_pk_fma_f32 v[128:129], v[124:125], v[86:87], v[128:129] op_sel:[0,0,0] op_sel_hi:[1,0,1]
	v_pk_fma_f32 v[132:133], v[126:127], v[22:23], v[132:133] op_sel:[0,1,0] op_sel_hi:[1,1,1]
	v_pk_fma_f32 v[128:129], v[126:127], v[86:87], v[128:129] op_sel:[0,1,0] op_sel_hi:[1,1,1]
	ds_read_b64 v[76:77], v197 offset:10496
	v_cndmask_b32_e64 v106, v147, v146, s[12:13]
	v_cndmask_b32_e64 v106, v106, v145, s[10:11]
	v_cndmask_b32_e64 v106, v106, v144, s[6:7]
	s_and_saveexec_b64 s[28:29], s[30:31]
	global_store_dword v[104:105], v106, off
	s_mov_b64 exec, s[28:29]
	v_lshl_add_u64 v[104:105], v[104:105], 0, s[26:27]
	s_waitcnt lgkmcnt(6)
	v_cndmask_b32_e64 v134, v133, v132, s[2:3]
	v_cndmask_b32_e64 v135, v132, v133, s[2:3]
	v_cndmask_b32_e64 v136, v129, v128, s[2:3]
	v_cndmask_b32_e64 v137, v128, v129, s[2:3]
	v_add_f32_dpp v138, v135, v134 quad_perm:[1,0,3,2] row_mask:0xf bank_mask:0xf bound_ctrl:1
	v_pk_mul_f32 v[150:151], v[16:17], v[28:29] op_sel:[0,0] op_sel_hi:[0,1]
	v_add_f32_dpp v139, v137, v136 quad_perm:[1,0,3,2] row_mask:0xf bank_mask:0xf bound_ctrl:1
	v_cndmask_b32_e64 v140, v139, v138, s[4:5]
	v_cndmask_b32_e64 v141, v138, v139, s[4:5]
	v_pk_mul_f32 v[152:153], v[16:17], v[28:29] op_sel:[1,0] op_sel_hi:[1,1]
	v_pk_mul_f32 v[154:155], v[18:19], v[28:29] op_sel:[0,0] op_sel_hi:[0,1]
	v_add_f32_dpp v142, v141, v140 quad_perm:[2,3,0,1] row_mask:0xf bank_mask:0xf bound_ctrl:1
	v_pk_mul_f32 v[156:157], v[18:19], v[28:29] op_sel:[1,0] op_sel_hi:[1,1]
	v_pk_fma_f32 v[150:151], v[120:121], v[8:9], v[150:151] op_sel:[0,0,0] op_sel_hi:[1,0,1]
	v_add_f32_dpp v142, v142, v142 row_ror:4 row_mask:0xf bank_mask:0xf bound_ctrl:1
	v_pk_fma_f32 v[152:153], v[122:123], v[8:9], v[152:153] op_sel:[0,1,0] op_sel_hi:[1,1,1]
	v_pk_fma_f32 v[154:155], v[124:125], v[10:11], v[154:155] op_sel:[0,0,0] op_sel_hi:[1,0,1]
	v_add_f32_dpp v144, v142, v142 row_ror:8 row_mask:0xf bank_mask:0xf bound_ctrl:1
	v_pk_fma_f32 v[156:157], v[126:127], v[10:11], v[156:157] op_sel:[0,1,0] op_sel_hi:[1,1,1]
	ds_read_b128 v[80:83], v196 offset:10752
	v_mov_b32_dpp v148, v144 quad_perm:[0,0,0,0] row_mask:0xf bank_mask:0xf
	v_mov_b32_dpp v149, v144 quad_perm:[1,1,1,1] row_mask:0xf bank_mask:0xf
	v_pk_fma_f32 v[120:121], v[24:25], v[148:149], v[150:151] op_sel:[0,0,0] op_sel_hi:[0,1,1]
	ds_read_b128 v[84:87], v196 offset:11008
	v_pk_fma_f32 v[122:123], v[24:25], v[148:149], v[152:153] op_sel:[1,0,0] op_sel_hi:[1,1,1]
	ds_read_b128 v[88:91], v196 offset:11264
	v_pk_fma_f32 v[124:125], v[26:27], v[148:149], v[154:155] op_sel:[0,0,0] op_sel_hi:[0,1,1]
	ds_read_b128 v[92:95], v196 offset:11520
	v_pk_fma_f32 v[126:127], v[26:27], v[148:149], v[156:157] op_sel:[1,0,0] op_sel_hi:[1,1,1]
	ds_read_b128 v[96:99], v196 offset:11776
	v_pk_mul_f32 v[132:133], v[120:121], v[44:45] op_sel:[0,0] op_sel_hi:[1,0]
	v_pk_mul_f32 v[128:129], v[120:121], v[12:13] op_sel:[0,0] op_sel_hi:[1,0]
	v_pk_fma_f32 v[132:133], v[122:123], v[44:45], v[132:133] op_sel:[0,1,0] op_sel_hi:[1,1,1]
	v_pk_fma_f32 v[128:129], v[122:123], v[12:13], v[128:129] op_sel:[0,1,0] op_sel_hi:[1,1,1]
	v_pk_fma_f32 v[132:133], v[124:125], v[46:47], v[132:133] op_sel:[0,0,0] op_sel_hi:[1,0,1]
	v_pk_fma_f32 v[128:129], v[124:125], v[14:15], v[128:129] op_sel:[0,0,0] op_sel_hi:[1,0,1]
	v_pk_fma_f32 v[132:133], v[126:127], v[46:47], v[132:133] op_sel:[0,1,0] op_sel_hi:[1,1,1]
	v_pk_fma_f32 v[128:129], v[126:127], v[14:15], v[128:129] op_sel:[0,1,0] op_sel_hi:[1,1,1]
	ds_read_b64 v[100:101], v197 offset:12032
	s_waitcnt lgkmcnt(6)
	v_cndmask_b32_e64 v134, v133, v132, s[2:3]
	v_cndmask_b32_e64 v135, v132, v133, s[2:3]
	v_cndmask_b32_e64 v136, v129, v128, s[2:3]
	v_cndmask_b32_e64 v137, v128, v129, s[2:3]
	v_add_f32_dpp v138, v135, v134 quad_perm:[1,0,3,2] row_mask:0xf bank_mask:0xf bound_ctrl:1
	v_pk_mul_f32 v[150:151], v[40:41], v[52:53] op_sel:[0,0] op_sel_hi:[0,1]
	v_add_f32_dpp v139, v137, v136 quad_perm:[1,0,3,2] row_mask:0xf bank_mask:0xf bound_ctrl:1
	v_cndmask_b32_e64 v140, v139, v138, s[4:5]
	v_cndmask_b32_e64 v141, v138, v139, s[4:5]
	v_pk_mul_f32 v[152:153], v[40:41], v[52:53] op_sel:[1,0] op_sel_hi:[1,1]
	v_pk_mul_f32 v[154:155], v[42:43], v[52:53] op_sel:[0,0] op_sel_hi:[0,1]
	v_add_f32_dpp v142, v141, v140 quad_perm:[2,3,0,1] row_mask:0xf bank_mask:0xf bound_ctrl:1
	v_pk_mul_f32 v[156:157], v[42:43], v[52:53] op_sel:[1,0] op_sel_hi:[1,1]
	v_pk_fma_f32 v[150:151], v[120:121], v[32:33], v[150:151] op_sel:[0,0,0] op_sel_hi:[1,0,1]
	v_add_f32_dpp v142, v142, v142 row_ror:4 row_mask:0xf bank_mask:0xf bound_ctrl:1
	v_pk_fma_f32 v[152:153], v[122:123], v[32:33], v[152:153] op_sel:[0,1,0] op_sel_hi:[1,1,1]
	v_pk_fma_f32 v[154:155], v[124:125], v[34:35], v[154:155] op_sel:[0,0,0] op_sel_hi:[1,0,1]
	v_add_f32_dpp v145, v142, v142 row_ror:8 row_mask:0xf bank_mask:0xf bound_ctrl:1
	v_pk_fma_f32 v[156:157], v[126:127], v[34:35], v[156:157] op_sel:[0,1,0] op_sel_hi:[1,1,1]
	ds_read_b128 v[8:11], v196 offset:12288
	v_mov_b32_dpp v148, v145 quad_perm:[0,0,0,0] row_mask:0xf bank_mask:0xf
	v_mov_b32_dpp v149, v145 quad_perm:[1,1,1,1] row_mask:0xf bank_mask:0xf
	v_pk_fma_f32 v[120:121], v[48:49], v[148:149], v[150:151] op_sel:[0,0,0] op_sel_hi:[0,1,1]
	ds_read_b128 v[12:15], v196 offset:12544
	v_pk_fma_f32 v[122:123], v[48:49], v[148:149], v[152:153] op_sel:[1,0,0] op_sel_hi:[1,1,1]
	ds_read_b128 v[16:19], v196 offset:12800
	v_pk_fma_f32 v[124:125], v[50:51], v[148:149], v[154:155] op_sel:[0,0,0] op_sel_hi:[0,1,1]
	ds_read_b128 v[20:23], v196 offset:13056
	v_pk_fma_f32 v[126:127], v[50:51], v[148:149], v[156:157] op_sel:[1,0,0] op_sel_hi:[1,1,1]
	ds_read_b128 v[24:27], v196 offset:13312
	v_pk_mul_f32 v[132:133], v[120:121], v[68:69] op_sel:[0,0] op_sel_hi:[1,0]
	v_pk_mul_f32 v[128:129], v[120:121], v[36:37] op_sel:[0,0] op_sel_hi:[1,0]
	v_pk_fma_f32 v[132:133], v[122:123], v[68:69], v[132:133] op_sel:[0,1,0] op_sel_hi:[1,1,1]
	v_pk_fma_f32 v[128:129], v[122:123], v[36:37], v[128:129] op_sel:[0,1,0] op_sel_hi:[1,1,1]
	v_pk_fma_f32 v[132:133], v[124:125], v[70:71], v[132:133] op_sel:[0,0,0] op_sel_hi:[1,0,1]
	v_pk_fma_f32 v[128:129], v[124:125], v[38:39], v[128:129] op_sel:[0,0,0] op_sel_hi:[1,0,1]
	v_pk_fma_f32 v[132:133], v[126:127], v[70:71], v[132:133] op_sel:[0,1,0] op_sel_hi:[1,1,1]
	v_pk_fma_f32 v[128:129], v[126:127], v[38:39], v[128:129] op_sel:[0,1,0] op_sel_hi:[1,1,1]
	ds_read_b64 v[28:29], v197 offset:13568
	s_waitcnt lgkmcnt(6)
	v_cndmask_b32_e64 v134, v133, v132, s[2:3]
	v_cndmask_b32_e64 v135, v132, v133, s[2:3]
	v_cndmask_b32_e64 v136, v129, v128, s[2:3]
	v_cndmask_b32_e64 v137, v128, v129, s[2:3]
	v_add_f32_dpp v138, v135, v134 quad_perm:[1,0,3,2] row_mask:0xf bank_mask:0xf bound_ctrl:1
	v_pk_mul_f32 v[150:151], v[64:65], v[76:77] op_sel:[0,0] op_sel_hi:[0,1]
	v_add_f32_dpp v139, v137, v136 quad_perm:[1,0,3,2] row_mask:0xf bank_mask:0xf bound_ctrl:1
	v_cndmask_b32_e64 v140, v139, v138, s[4:5]
	v_cndmask_b32_e64 v141, v138, v139, s[4:5]
	v_pk_mul_f32 v[152:153], v[64:65], v[76:77] op_sel:[1,0] op_sel_hi:[1,1]
	v_pk_mul_f32 v[154:155], v[66:67], v[76:77] op_sel:[0,0] op_sel_hi:[0,1]
	v_add_f32_dpp v142, v141, v140 quad_perm:[2,3,0,1] row_mask:0xf bank_mask:0xf bound_ctrl:1
	v_pk_mul_f32 v[156:157], v[66:67], v[76:77] op_sel:[1,0] op_sel_hi:[1,1]
	v_pk_fma_f32 v[150:151], v[120:121], v[56:57], v[150:151] op_sel:[0,0,0] op_sel_hi:[1,0,1]
	v_add_f32_dpp v142, v142, v142 row_ror:4 row_mask:0xf bank_mask:0xf bound_ctrl:1
	v_pk_fma_f32 v[152:153], v[122:123], v[56:57], v[152:153] op_sel:[0,1,0] op_sel_hi:[1,1,1]
	v_pk_fma_f32 v[154:155], v[124:125], v[58:59], v[154:155] op_sel:[0,0,0] op_sel_hi:[1,0,1]
	v_add_f32_dpp v146, v142, v142 row_ror:8 row_mask:0xf bank_mask:0xf bound_ctrl:1
	v_pk_fma_f32 v[156:157], v[126:127], v[58:59], v[156:157] op_sel:[0,1,0] op_sel_hi:[1,1,1]
	ds_read_b128 v[32:35], v196 offset:13824
	v_mov_b32_dpp v148, v146 quad_perm:[0,0,0,0] row_mask:0xf bank_mask:0xf
	v_mov_b32_dpp v149, v146 quad_perm:[1,1,1,1] row_mask:0xf bank_mask:0xf
	v_pk_fma_f32 v[120:121], v[72:73], v[148:149], v[150:151] op_sel:[0,0,0] op_sel_hi:[0,1,1]
	ds_read_b128 v[36:39], v196 offset:14080
	v_pk_fma_f32 v[122:123], v[72:73], v[148:149], v[152:153] op_sel:[1,0,0] op_sel_hi:[1,1,1]
	ds_read_b128 v[40:43], v196 offset:14336
	v_pk_fma_f32 v[124:125], v[74:75], v[148:149], v[154:155] op_sel:[0,0,0] op_sel_hi:[0,1,1]
	ds_read_b128 v[44:47], v196 offset:14592
	v_pk_fma_f32 v[126:127], v[74:75], v[148:149], v[156:157] op_sel:[1,0,0] op_sel_hi:[1,1,1]
	ds_read_b128 v[48:51], v196 offset:14848
	v_pk_mul_f32 v[132:133], v[120:121], v[92:93] op_sel:[0,0] op_sel_hi:[1,0]
	v_pk_mul_f32 v[128:129], v[120:121], v[60:61] op_sel:[0,0] op_sel_hi:[1,0]
	v_pk_fma_f32 v[132:133], v[122:123], v[92:93], v[132:133] op_sel:[0,1,0] op_sel_hi:[1,1,1]
	v_pk_fma_f32 v[128:129], v[122:123], v[60:61], v[128:129] op_sel:[0,1,0] op_sel_hi:[1,1,1]
	v_pk_fma_f32 v[132:133], v[124:125], v[94:95], v[132:133] op_sel:[0,0,0] op_sel_hi:[1,0,1]
	v_pk_fma_f32 v[128:129], v[124:125], v[62:63], v[128:129] op_sel:[0,0,0] op_sel_hi:[1,0,1]
	v_pk_fma_f32 v[132:133], v[126:127], v[94:95], v[132:133] op_sel:[0,1,0] op_sel_hi:[1,1,1]
	v_pk_fma_f32 v[128:129], v[126:127], v[62:63], v[128:129] op_sel:[0,1,0] op_sel_hi:[1,1,1]
	ds_read_b64 v[52:53], v197 offset:15104
	s_waitcnt lgkmcnt(6)
	v_cndmask_b32_e64 v134, v133, v132, s[2:3]
	v_cndmask_b32_e64 v135, v132, v133, s[2:3]
	v_cndmask_b32_e64 v136, v129, v128, s[2:3]
	v_cndmask_b32_e64 v137, v128, v129, s[2:3]
	v_add_f32_dpp v138, v135, v134 quad_perm:[1,0,3,2] row_mask:0xf bank_mask:0xf bound_ctrl:1
	v_pk_mul_f32 v[150:151], v[88:89], v[100:101] op_sel:[0,0] op_sel_hi:[0,1]
	v_add_f32_dpp v139, v137, v136 quad_perm:[1,0,3,2] row_mask:0xf bank_mask:0xf bound_ctrl:1
	v_cndmask_b32_e64 v140, v139, v138, s[4:5]
	v_cndmask_b32_e64 v141, v138, v139, s[4:5]
	v_pk_mul_f32 v[152:153], v[88:89], v[100:101] op_sel:[1,0] op_sel_hi:[1,1]
	v_pk_mul_f32 v[154:155], v[90:91], v[100:101] op_sel:[0,0] op_sel_hi:[0,1]
	v_add_f32_dpp v142, v141, v140 quad_perm:[2,3,0,1] row_mask:0xf bank_mask:0xf bound_ctrl:1
	v_pk_mul_f32 v[156:157], v[90:91], v[100:101] op_sel:[1,0] op_sel_hi:[1,1]
	v_pk_fma_f32 v[150:151], v[120:121], v[80:81], v[150:151] op_sel:[0,0,0] op_sel_hi:[1,0,1]
	v_add_f32_dpp v142, v142, v142 row_ror:4 row_mask:0xf bank_mask:0xf bound_ctrl:1
	v_pk_fma_f32 v[152:153], v[122:123], v[80:81], v[152:153] op_sel:[0,1,0] op_sel_hi:[1,1,1]
	v_pk_fma_f32 v[154:155], v[124:125], v[82:83], v[154:155] op_sel:[0,0,0] op_sel_hi:[1,0,1]
	v_add_f32_dpp v147, v142, v142 row_ror:8 row_mask:0xf bank_mask:0xf bound_ctrl:1
	v_pk_fma_f32 v[156:157], v[126:127], v[82:83], v[156:157] op_sel:[0,1,0] op_sel_hi:[1,1,1]
	ds_read_b128 v[56:59], v196 offset:15360
	v_mov_b32_dpp v148, v147 quad_perm:[0,0,0,0] row_mask:0xf bank_mask:0xf
	v_mov_b32_dpp v149, v147 quad_perm:[1,1,1,1] row_mask:0xf bank_mask:0xf
	v_pk_fma_f32 v[120:121], v[96:97], v[148:149], v[150:151] op_sel:[0,0,0] op_sel_hi:[0,1,1]
	ds_read_b128 v[60:63], v196 offset:15616
	v_pk_fma_f32 v[122:123], v[96:97], v[148:149], v[152:153] op_sel:[1,0,0] op_sel_hi:[1,1,1]
	ds_read_b128 v[64:67], v196 offset:15872
	v_pk_fma_f32 v[124:125], v[98:99], v[148:149], v[154:155] op_sel:[0,0,0] op_sel_hi:[0,1,1]
	ds_read_b128 v[68:71], v196 offset:16128
	v_pk_fma_f32 v[126:127], v[98:99], v[148:149], v[156:157] op_sel:[1,0,0] op_sel_hi:[1,1,1]
	ds_read_b128 v[72:75], v196 offset:16384
	v_pk_mul_f32 v[132:133], v[120:121], v[20:21] op_sel:[0,0] op_sel_hi:[1,0]
	v_pk_mul_f32 v[128:129], v[120:121], v[84:85] op_sel:[0,0] op_sel_hi:[1,0]
	v_pk_fma_f32 v[132:133], v[122:123], v[20:21], v[132:133] op_sel:[0,1,0] op_sel_hi:[1,1,1]
	v_pk_fma_f32 v[128:129], v[122:123], v[84:85], v[128:129] op_sel:[0,1,0] op_sel_hi:[1,1,1]
	v_pk_fma_f32 v[132:133], v[124:125], v[22:23], v[132:133] op_sel:[0,0,0] op_sel_hi:[1,0,1]
	v_pk_fma_f32 v[128:129], v[124:125], v[86:87], v[128:129] op_sel:[0,0,0] op_sel_hi:[1,0,1]
	v_pk_fma_f32 v[132:133], v[126:127], v[22:23], v[132:133] op_sel:[0,1,0] op_sel_hi:[1,1,1]
	v_pk_fma_f32 v[128:129], v[126:127], v[86:87], v[128:129] op_sel:[0,1,0] op_sel_hi:[1,1,1]
	ds_read_b64 v[76:77], v197 offset:16640
	v_cndmask_b32_e64 v106, v147, v146, s[12:13]
	v_cndmask_b32_e64 v106, v106, v145, s[10:11]
	v_cndmask_b32_e64 v106, v106, v144, s[6:7]
	s_and_saveexec_b64 s[28:29], s[8:9]
	global_store_dword v[104:105], v106, off
	s_mov_b64 exec, s[28:29]
	v_lshl_add_u64 v[104:105], v[104:105], 0, s[26:27]
	s_waitcnt lgkmcnt(6)
	v_cndmask_b32_e64 v134, v133, v132, s[2:3]
	v_cndmask_b32_e64 v135, v132, v133, s[2:3]
	v_cndmask_b32_e64 v136, v129, v128, s[2:3]
	v_cndmask_b32_e64 v137, v128, v129, s[2:3]
	v_add_f32_dpp v138, v135, v134 quad_perm:[1,0,3,2] row_mask:0xf bank_mask:0xf bound_ctrl:1
	v_pk_mul_f32 v[150:151], v[16:17], v[28:29] op_sel:[0,0] op_sel_hi:[0,1]
	v_add_f32_dpp v139, v137, v136 quad_perm:[1,0,3,2] row_mask:0xf bank_mask:0xf bound_ctrl:1
	v_cndmask_b32_e64 v140, v139, v138, s[4:5]
	v_cndmask_b32_e64 v141, v138, v139, s[4:5]
	v_pk_mul_f32 v[152:153], v[16:17], v[28:29] op_sel:[1,0] op_sel_hi:[1,1]
	v_pk_mul_f32 v[154:155], v[18:19], v[28:29] op_sel:[0,0] op_sel_hi:[0,1]
	v_add_f32_dpp v142, v141, v140 quad_perm:[2,3,0,1] row_mask:0xf bank_mask:0xf bound_ctrl:1
	v_pk_mul_f32 v[156:157], v[18:19], v[28:29] op_sel:[1,0] op_sel_hi:[1,1]
	v_pk_fma_f32 v[150:151], v[120:121], v[8:9], v[150:151] op_sel:[0,0,0] op_sel_hi:[1,0,1]
	v_add_f32_dpp v142, v142, v142 row_ror:4 row_mask:0xf bank_mask:0xf bound_ctrl:1
	v_pk_fma_f32 v[152:153], v[122:123], v[8:9], v[152:153] op_sel:[0,1,0] op_sel_hi:[1,1,1]
	v_pk_fma_f32 v[154:155], v[124:125], v[10:11], v[154:155] op_sel:[0,0,0] op_sel_hi:[1,0,1]
	v_add_f32_dpp v144, v142, v142 row_ror:8 row_mask:0xf bank_mask:0xf bound_ctrl:1
	v_pk_fma_f32 v[156:157], v[126:127], v[10:11], v[156:157] op_sel:[0,1,0] op_sel_hi:[1,1,1]
	ds_read_b128 v[80:83], v196 offset:16896
	v_mov_b32_dpp v148, v144 quad_perm:[0,0,0,0] row_mask:0xf bank_mask:0xf
	v_mov_b32_dpp v149, v144 quad_perm:[1,1,1,1] row_mask:0xf bank_mask:0xf
	v_pk_fma_f32 v[120:121], v[24:25], v[148:149], v[150:151] op_sel:[0,0,0] op_sel_hi:[0,1,1]
	ds_read_b128 v[84:87], v196 offset:17152
	v_pk_fma_f32 v[122:123], v[24:25], v[148:149], v[152:153] op_sel:[1,0,0] op_sel_hi:[1,1,1]
	ds_read_b128 v[88:91], v196 offset:17408
	v_pk_fma_f32 v[124:125], v[26:27], v[148:149], v[154:155] op_sel:[0,0,0] op_sel_hi:[0,1,1]
	ds_read_b128 v[92:95], v196 offset:17664
	v_pk_fma_f32 v[126:127], v[26:27], v[148:149], v[156:157] op_sel:[1,0,0] op_sel_hi:[1,1,1]
	ds_read_b128 v[96:99], v196 offset:17920
	v_pk_mul_f32 v[132:133], v[120:121], v[44:45] op_sel:[0,0] op_sel_hi:[1,0]
	v_pk_mul_f32 v[128:129], v[120:121], v[12:13] op_sel:[0,0] op_sel_hi:[1,0]
	v_pk_fma_f32 v[132:133], v[122:123], v[44:45], v[132:133] op_sel:[0,1,0] op_sel_hi:[1,1,1]
	v_pk_fma_f32 v[128:129], v[122:123], v[12:13], v[128:129] op_sel:[0,1,0] op_sel_hi:[1,1,1]
	v_pk_fma_f32 v[132:133], v[124:125], v[46:47], v[132:133] op_sel:[0,0,0] op_sel_hi:[1,0,1]
	v_pk_fma_f32 v[128:129], v[124:125], v[14:15], v[128:129] op_sel:[0,0,0] op_sel_hi:[1,0,1]
	v_pk_fma_f32 v[132:133], v[126:127], v[46:47], v[132:133] op_sel:[0,1,0] op_sel_hi:[1,1,1]
	v_pk_fma_f32 v[128:129], v[126:127], v[14:15], v[128:129] op_sel:[0,1,0] op_sel_hi:[1,1,1]
	ds_read_b64 v[100:101], v197 offset:18176
	s_waitcnt lgkmcnt(6)
	v_cndmask_b32_e64 v134, v133, v132, s[2:3]
	v_cndmask_b32_e64 v135, v132, v133, s[2:3]
	v_cndmask_b32_e64 v136, v129, v128, s[2:3]
	v_cndmask_b32_e64 v137, v128, v129, s[2:3]
	v_add_f32_dpp v138, v135, v134 quad_perm:[1,0,3,2] row_mask:0xf bank_mask:0xf bound_ctrl:1
	v_pk_mul_f32 v[150:151], v[40:41], v[52:53] op_sel:[0,0] op_sel_hi:[0,1]
	v_add_f32_dpp v139, v137, v136 quad_perm:[1,0,3,2] row_mask:0xf bank_mask:0xf bound_ctrl:1
	v_cndmask_b32_e64 v140, v139, v138, s[4:5]
	v_cndmask_b32_e64 v141, v138, v139, s[4:5]
	v_pk_mul_f32 v[152:153], v[40:41], v[52:53] op_sel:[1,0] op_sel_hi:[1,1]
	v_pk_mul_f32 v[154:155], v[42:43], v[52:53] op_sel:[0,0] op_sel_hi:[0,1]
	v_add_f32_dpp v142, v141, v140 quad_perm:[2,3,0,1] row_mask:0xf bank_mask:0xf bound_ctrl:1
	v_pk_mul_f32 v[156:157], v[42:43], v[52:53] op_sel:[1,0] op_sel_hi:[1,1]
	v_pk_fma_f32 v[150:151], v[120:121], v[32:33], v[150:151] op_sel:[0,0,0] op_sel_hi:[1,0,1]
	v_add_f32_dpp v142, v142, v142 row_ror:4 row_mask:0xf bank_mask:0xf bound_ctrl:1
	v_pk_fma_f32 v[152:153], v[122:123], v[32:33], v[152:153] op_sel:[0,1,0] op_sel_hi:[1,1,1]
	v_pk_fma_f32 v[154:155], v[124:125], v[34:35], v[154:155] op_sel:[0,0,0] op_sel_hi:[1,0,1]
	v_add_f32_dpp v145, v142, v142 row_ror:8 row_mask:0xf bank_mask:0xf bound_ctrl:1
	v_pk_fma_f32 v[156:157], v[126:127], v[34:35], v[156:157] op_sel:[0,1,0] op_sel_hi:[1,1,1]
	ds_read_b128 v[8:11], v196 offset:18432
	v_mov_b32_dpp v148, v145 quad_perm:[0,0,0,0] row_mask:0xf bank_mask:0xf
	v_mov_b32_dpp v149, v145 quad_perm:[1,1,1,1] row_mask:0xf bank_mask:0xf
	v_pk_fma_f32 v[120:121], v[48:49], v[148:149], v[150:151] op_sel:[0,0,0] op_sel_hi:[0,1,1]
	ds_read_b128 v[12:15], v196 offset:18688
	v_pk_fma_f32 v[122:123], v[48:49], v[148:149], v[152:153] op_sel:[1,0,0] op_sel_hi:[1,1,1]
	ds_read_b128 v[16:19], v196 offset:18944
	v_pk_fma_f32 v[124:125], v[50:51], v[148:149], v[154:155] op_sel:[0,0,0] op_sel_hi:[0,1,1]
	ds_read_b128 v[20:23], v196 offset:19200
	v_pk_fma_f32 v[126:127], v[50:51], v[148:149], v[156:157] op_sel:[1,0,0] op_sel_hi:[1,1,1]
	ds_read_b128 v[24:27], v196 offset:19456
	v_pk_mul_f32 v[132:133], v[120:121], v[68:69] op_sel:[0,0] op_sel_hi:[1,0]
	v_pk_mul_f32 v[128:129], v[120:121], v[36:37] op_sel:[0,0] op_sel_hi:[1,0]
	v_pk_fma_f32 v[132:133], v[122:123], v[68:69], v[132:133] op_sel:[0,1,0] op_sel_hi:[1,1,1]
	v_pk_fma_f32 v[128:129], v[122:123], v[36:37], v[128:129] op_sel:[0,1,0] op_sel_hi:[1,1,1]
	v_pk_fma_f32 v[132:133], v[124:125], v[70:71], v[132:133] op_sel:[0,0,0] op_sel_hi:[1,0,1]
	v_pk_fma_f32 v[128:129], v[124:125], v[38:39], v[128:129] op_sel:[0,0,0] op_sel_hi:[1,0,1]
	v_pk_fma_f32 v[132:133], v[126:127], v[70:71], v[132:133] op_sel:[0,1,0] op_sel_hi:[1,1,1]
	v_pk_fma_f32 v[128:129], v[126:127], v[38:39], v[128:129] op_sel:[0,1,0] op_sel_hi:[1,1,1]
	ds_read_b64 v[28:29], v197 offset:19712
	s_waitcnt lgkmcnt(6)
	v_cndmask_b32_e64 v134, v133, v132, s[2:3]
	v_cndmask_b32_e64 v135, v132, v133, s[2:3]
	v_cndmask_b32_e64 v136, v129, v128, s[2:3]
	v_cndmask_b32_e64 v137, v128, v129, s[2:3]
	v_add_f32_dpp v138, v135, v134 quad_perm:[1,0,3,2] row_mask:0xf bank_mask:0xf bound_ctrl:1
	v_pk_mul_f32 v[150:151], v[64:65], v[76:77] op_sel:[0,0] op_sel_hi:[0,1]
	v_add_f32_dpp v139, v137, v136 quad_perm:[1,0,3,2] row_mask:0xf bank_mask:0xf bound_ctrl:1
	v_cndmask_b32_e64 v140, v139, v138, s[4:5]
	v_cndmask_b32_e64 v141, v138, v139, s[4:5]
	v_pk_mul_f32 v[152:153], v[64:65], v[76:77] op_sel:[1,0] op_sel_hi:[1,1]
	v_pk_mul_f32 v[154:155], v[66:67], v[76:77] op_sel:[0,0] op_sel_hi:[0,1]
	v_add_f32_dpp v142, v141, v140 quad_perm:[2,3,0,1] row_mask:0xf bank_mask:0xf bound_ctrl:1
	v_pk_mul_f32 v[156:157], v[66:67], v[76:77] op_sel:[1,0] op_sel_hi:[1,1]
	v_pk_fma_f32 v[150:151], v[120:121], v[56:57], v[150:151] op_sel:[0,0,0] op_sel_hi:[1,0,1]
	v_add_f32_dpp v142, v142, v142 row_ror:4 row_mask:0xf bank_mask:0xf bound_ctrl:1
	v_pk_fma_f32 v[152:153], v[122:123], v[56:57], v[152:153] op_sel:[0,1,0] op_sel_hi:[1,1,1]
	v_pk_fma_f32 v[154:155], v[124:125], v[58:59], v[154:155] op_sel:[0,0,0] op_sel_hi:[1,0,1]
	v_add_f32_dpp v146, v142, v142 row_ror:8 row_mask:0xf bank_mask:0xf bound_ctrl:1
	v_pk_fma_f32 v[156:157], v[126:127], v[58:59], v[156:157] op_sel:[0,1,0] op_sel_hi:[1,1,1]
	ds_read_b128 v[32:35], v196 offset:19968
	v_mov_b32_dpp v148, v146 quad_perm:[0,0,0,0] row_mask:0xf bank_mask:0xf
	v_mov_b32_dpp v149, v146 quad_perm:[1,1,1,1] row_mask:0xf bank_mask:0xf
	v_pk_fma_f32 v[120:121], v[72:73], v[148:149], v[150:151] op_sel:[0,0,0] op_sel_hi:[0,1,1]
	ds_read_b128 v[36:39], v196 offset:20224
	v_pk_fma_f32 v[122:123], v[72:73], v[148:149], v[152:153] op_sel:[1,0,0] op_sel_hi:[1,1,1]
	ds_read_b128 v[40:43], v196 offset:20480
	v_pk_fma_f32 v[124:125], v[74:75], v[148:149], v[154:155] op_sel:[0,0,0] op_sel_hi:[0,1,1]
	ds_read_b128 v[44:47], v196 offset:20736
	v_pk_fma_f32 v[126:127], v[74:75], v[148:149], v[156:157] op_sel:[1,0,0] op_sel_hi:[1,1,1]
	ds_read_b128 v[48:51], v196 offset:20992
	v_pk_mul_f32 v[132:133], v[120:121], v[92:93] op_sel:[0,0] op_sel_hi:[1,0]
	v_pk_mul_f32 v[128:129], v[120:121], v[60:61] op_sel:[0,0] op_sel_hi:[1,0]
	v_pk_fma_f32 v[132:133], v[122:123], v[92:93], v[132:133] op_sel:[0,1,0] op_sel_hi:[1,1,1]
	v_pk_fma_f32 v[128:129], v[122:123], v[60:61], v[128:129] op_sel:[0,1,0] op_sel_hi:[1,1,1]
	v_pk_fma_f32 v[132:133], v[124:125], v[94:95], v[132:133] op_sel:[0,0,0] op_sel_hi:[1,0,1]
	v_pk_fma_f32 v[128:129], v[124:125], v[62:63], v[128:129] op_sel:[0,0,0] op_sel_hi:[1,0,1]
	v_pk_fma_f32 v[132:133], v[126:127], v[94:95], v[132:133] op_sel:[0,1,0] op_sel_hi:[1,1,1]
	v_pk_fma_f32 v[128:129], v[126:127], v[62:63], v[128:129] op_sel:[0,1,0] op_sel_hi:[1,1,1]
	ds_read_b64 v[52:53], v197 offset:21248
	s_waitcnt lgkmcnt(6)
	v_cndmask_b32_e64 v134, v133, v132, s[2:3]
	v_cndmask_b32_e64 v135, v132, v133, s[2:3]
	v_cndmask_b32_e64 v136, v129, v128, s[2:3]
	v_cndmask_b32_e64 v137, v128, v129, s[2:3]
	v_add_f32_dpp v138, v135, v134 quad_perm:[1,0,3,2] row_mask:0xf bank_mask:0xf bound_ctrl:1
	v_pk_mul_f32 v[150:151], v[88:89], v[100:101] op_sel:[0,0] op_sel_hi:[0,1]
	v_add_f32_dpp v139, v137, v136 quad_perm:[1,0,3,2] row_mask:0xf bank_mask:0xf bound_ctrl:1
	v_cndmask_b32_e64 v140, v139, v138, s[4:5]
	v_cndmask_b32_e64 v141, v138, v139, s[4:5]
	v_pk_mul_f32 v[152:153], v[88:89], v[100:101] op_sel:[1,0] op_sel_hi:[1,1]
	v_pk_mul_f32 v[154:155], v[90:91], v[100:101] op_sel:[0,0] op_sel_hi:[0,1]
	v_add_f32_dpp v142, v141, v140 quad_perm:[2,3,0,1] row_mask:0xf bank_mask:0xf bound_ctrl:1
	v_pk_mul_f32 v[156:157], v[90:91], v[100:101] op_sel:[1,0] op_sel_hi:[1,1]
	v_pk_fma_f32 v[150:151], v[120:121], v[80:81], v[150:151] op_sel:[0,0,0] op_sel_hi:[1,0,1]
	v_add_f32_dpp v142, v142, v142 row_ror:4 row_mask:0xf bank_mask:0xf bound_ctrl:1
	v_pk_fma_f32 v[152:153], v[122:123], v[80:81], v[152:153] op_sel:[0,1,0] op_sel_hi:[1,1,1]
	v_pk_fma_f32 v[154:155], v[124:125], v[82:83], v[154:155] op_sel:[0,0,0] op_sel_hi:[1,0,1]
	v_add_f32_dpp v147, v142, v142 row_ror:8 row_mask:0xf bank_mask:0xf bound_ctrl:1
	v_pk_fma_f32 v[156:157], v[126:127], v[82:83], v[156:157] op_sel:[0,1,0] op_sel_hi:[1,1,1]
	ds_read_b128 v[56:59], v196 offset:21504
	v_mov_b32_dpp v148, v147 quad_perm:[0,0,0,0] row_mask:0xf bank_mask:0xf
	v_mov_b32_dpp v149, v147 quad_perm:[1,1,1,1] row_mask:0xf bank_mask:0xf
	v_pk_fma_f32 v[120:121], v[96:97], v[148:149], v[150:151] op_sel:[0,0,0] op_sel_hi:[0,1,1]
	ds_read_b128 v[60:63], v196 offset:21760
	v_pk_fma_f32 v[122:123], v[96:97], v[148:149], v[152:153] op_sel:[1,0,0] op_sel_hi:[1,1,1]
	ds_read_b128 v[64:67], v196 offset:22016
	v_pk_fma_f32 v[124:125], v[98:99], v[148:149], v[154:155] op_sel:[0,0,0] op_sel_hi:[0,1,1]
	ds_read_b128 v[68:71], v196 offset:22272
	v_pk_fma_f32 v[126:127], v[98:99], v[148:149], v[156:157] op_sel:[1,0,0] op_sel_hi:[1,1,1]
	ds_read_b128 v[72:75], v196 offset:22528
	v_pk_mul_f32 v[132:133], v[120:121], v[20:21] op_sel:[0,0] op_sel_hi:[1,0]
	v_pk_mul_f32 v[128:129], v[120:121], v[84:85] op_sel:[0,0] op_sel_hi:[1,0]
	v_pk_fma_f32 v[132:133], v[122:123], v[20:21], v[132:133] op_sel:[0,1,0] op_sel_hi:[1,1,1]
	v_pk_fma_f32 v[128:129], v[122:123], v[84:85], v[128:129] op_sel:[0,1,0] op_sel_hi:[1,1,1]
	v_pk_fma_f32 v[132:133], v[124:125], v[22:23], v[132:133] op_sel:[0,0,0] op_sel_hi:[1,0,1]
	v_pk_fma_f32 v[128:129], v[124:125], v[86:87], v[128:129] op_sel:[0,0,0] op_sel_hi:[1,0,1]
	v_pk_fma_f32 v[132:133], v[126:127], v[22:23], v[132:133] op_sel:[0,1,0] op_sel_hi:[1,1,1]
	v_pk_fma_f32 v[128:129], v[126:127], v[86:87], v[128:129] op_sel:[0,1,0] op_sel_hi:[1,1,1]
	ds_read_b64 v[76:77], v197 offset:22784
	v_cndmask_b32_e64 v106, v147, v146, s[12:13]
	v_cndmask_b32_e64 v106, v106, v145, s[10:11]
	v_cndmask_b32_e64 v106, v106, v144, s[6:7]
	s_and_saveexec_b64 s[28:29], s[8:9]
	global_store_dword v[104:105], v106, off
	s_mov_b64 exec, s[28:29]
	v_lshl_add_u64 v[104:105], v[104:105], 0, s[26:27]
	s_waitcnt lgkmcnt(6)
	v_cndmask_b32_e64 v134, v133, v132, s[2:3]
	v_cndmask_b32_e64 v135, v132, v133, s[2:3]
	v_cndmask_b32_e64 v136, v129, v128, s[2:3]
	v_cndmask_b32_e64 v137, v128, v129, s[2:3]
	v_add_f32_dpp v138, v135, v134 quad_perm:[1,0,3,2] row_mask:0xf bank_mask:0xf bound_ctrl:1
	v_pk_mul_f32 v[150:151], v[16:17], v[28:29] op_sel:[0,0] op_sel_hi:[0,1]
	v_add_f32_dpp v139, v137, v136 quad_perm:[1,0,3,2] row_mask:0xf bank_mask:0xf bound_ctrl:1
	v_cndmask_b32_e64 v140, v139, v138, s[4:5]
	v_cndmask_b32_e64 v141, v138, v139, s[4:5]
	v_pk_mul_f32 v[152:153], v[16:17], v[28:29] op_sel:[1,0] op_sel_hi:[1,1]
	v_pk_mul_f32 v[154:155], v[18:19], v[28:29] op_sel:[0,0] op_sel_hi:[0,1]
	v_add_f32_dpp v142, v141, v140 quad_perm:[2,3,0,1] row_mask:0xf bank_mask:0xf bound_ctrl:1
	v_pk_mul_f32 v[156:157], v[18:19], v[28:29] op_sel:[1,0] op_sel_hi:[1,1]
	v_pk_fma_f32 v[150:151], v[120:121], v[8:9], v[150:151] op_sel:[0,0,0] op_sel_hi:[1,0,1]
	v_add_f32_dpp v142, v142, v142 row_ror:4 row_mask:0xf bank_mask:0xf bound_ctrl:1
	v_pk_fma_f32 v[152:153], v[122:123], v[8:9], v[152:153] op_sel:[0,1,0] op_sel_hi:[1,1,1]
	v_pk_fma_f32 v[154:155], v[124:125], v[10:11], v[154:155] op_sel:[0,0,0] op_sel_hi:[1,0,1]
	v_add_f32_dpp v144, v142, v142 row_ror:8 row_mask:0xf bank_mask:0xf bound_ctrl:1
	v_pk_fma_f32 v[156:157], v[126:127], v[10:11], v[156:157] op_sel:[0,1,0] op_sel_hi:[1,1,1]
	ds_read_b128 v[80:83], v196 offset:23040
	v_mov_b32_dpp v148, v144 quad_perm:[0,0,0,0] row_mask:0xf bank_mask:0xf
	v_mov_b32_dpp v149, v144 quad_perm:[1,1,1,1] row_mask:0xf bank_mask:0xf
	v_pk_fma_f32 v[120:121], v[24:25], v[148:149], v[150:151] op_sel:[0,0,0] op_sel_hi:[0,1,1]
	ds_read_b128 v[84:87], v196 offset:23296
	v_pk_fma_f32 v[122:123], v[24:25], v[148:149], v[152:153] op_sel:[1,0,0] op_sel_hi:[1,1,1]
	ds_read_b128 v[88:91], v196 offset:23552
	v_pk_fma_f32 v[124:125], v[26:27], v[148:149], v[154:155] op_sel:[0,0,0] op_sel_hi:[0,1,1]
	ds_read_b128 v[92:95], v196 offset:23808
	v_pk_fma_f32 v[126:127], v[26:27], v[148:149], v[156:157] op_sel:[1,0,0] op_sel_hi:[1,1,1]
	ds_read_b128 v[96:99], v196 offset:24064
	v_pk_mul_f32 v[132:133], v[120:121], v[44:45] op_sel:[0,0] op_sel_hi:[1,0]
	v_pk_mul_f32 v[128:129], v[120:121], v[12:13] op_sel:[0,0] op_sel_hi:[1,0]
	v_pk_fma_f32 v[132:133], v[122:123], v[44:45], v[132:133] op_sel:[0,1,0] op_sel_hi:[1,1,1]
	v_pk_fma_f32 v[128:129], v[122:123], v[12:13], v[128:129] op_sel:[0,1,0] op_sel_hi:[1,1,1]
	v_pk_fma_f32 v[132:133], v[124:125], v[46:47], v[132:133] op_sel:[0,0,0] op_sel_hi:[1,0,1]
	v_pk_fma_f32 v[128:129], v[124:125], v[14:15], v[128:129] op_sel:[0,0,0] op_sel_hi:[1,0,1]
	v_pk_fma_f32 v[132:133], v[126:127], v[46:47], v[132:133] op_sel:[0,1,0] op_sel_hi:[1,1,1]
	v_pk_fma_f32 v[128:129], v[126:127], v[14:15], v[128:129] op_sel:[0,1,0] op_sel_hi:[1,1,1]
	ds_read_b64 v[100:101], v197 offset:24320
	s_waitcnt lgkmcnt(6)
	v_cndmask_b32_e64 v134, v133, v132, s[2:3]
	v_cndmask_b32_e64 v135, v132, v133, s[2:3]
	v_cndmask_b32_e64 v136, v129, v128, s[2:3]
	v_cndmask_b32_e64 v137, v128, v129, s[2:3]
	v_add_f32_dpp v138, v135, v134 quad_perm:[1,0,3,2] row_mask:0xf bank_mask:0xf bound_ctrl:1
	v_pk_mul_f32 v[150:151], v[40:41], v[52:53] op_sel:[0,0] op_sel_hi:[0,1]
	v_add_f32_dpp v139, v137, v136 quad_perm:[1,0,3,2] row_mask:0xf bank_mask:0xf bound_ctrl:1
	v_cndmask_b32_e64 v140, v139, v138, s[4:5]
	v_cndmask_b32_e64 v141, v138, v139, s[4:5]
	v_pk_mul_f32 v[152:153], v[40:41], v[52:53] op_sel:[1,0] op_sel_hi:[1,1]
	v_pk_mul_f32 v[154:155], v[42:43], v[52:53] op_sel:[0,0] op_sel_hi:[0,1]
	v_add_f32_dpp v142, v141, v140 quad_perm:[2,3,0,1] row_mask:0xf bank_mask:0xf bound_ctrl:1
	v_pk_mul_f32 v[156:157], v[42:43], v[52:53] op_sel:[1,0] op_sel_hi:[1,1]
	v_pk_fma_f32 v[150:151], v[120:121], v[32:33], v[150:151] op_sel:[0,0,0] op_sel_hi:[1,0,1]
	v_add_f32_dpp v142, v142, v142 row_ror:4 row_mask:0xf bank_mask:0xf bound_ctrl:1
	v_pk_fma_f32 v[152:153], v[122:123], v[32:33], v[152:153] op_sel:[0,1,0] op_sel_hi:[1,1,1]
	v_pk_fma_f32 v[154:155], v[124:125], v[34:35], v[154:155] op_sel:[0,0,0] op_sel_hi:[1,0,1]
	v_add_f32_dpp v145, v142, v142 row_ror:8 row_mask:0xf bank_mask:0xf bound_ctrl:1
	v_pk_fma_f32 v[156:157], v[126:127], v[34:35], v[156:157] op_sel:[0,1,0] op_sel_hi:[1,1,1]
	ds_read_b128 v[8:11], v196 offset:24576
	v_mov_b32_dpp v148, v145 quad_perm:[0,0,0,0] row_mask:0xf bank_mask:0xf
	v_mov_b32_dpp v149, v145 quad_perm:[1,1,1,1] row_mask:0xf bank_mask:0xf
	v_pk_fma_f32 v[120:121], v[48:49], v[148:149], v[150:151] op_sel:[0,0,0] op_sel_hi:[0,1,1]
	ds_read_b128 v[12:15], v196 offset:24832
	v_pk_fma_f32 v[122:123], v[48:49], v[148:149], v[152:153] op_sel:[1,0,0] op_sel_hi:[1,1,1]
	ds_read_b128 v[16:19], v196 offset:25088
	v_pk_fma_f32 v[124:125], v[50:51], v[148:149], v[154:155] op_sel:[0,0,0] op_sel_hi:[0,1,1]
	ds_read_b128 v[20:23], v196 offset:25344
	v_pk_fma_f32 v[126:127], v[50:51], v[148:149], v[156:157] op_sel:[1,0,0] op_sel_hi:[1,1,1]
	ds_read_b128 v[24:27], v196 offset:25600
	v_pk_mul_f32 v[132:133], v[120:121], v[68:69] op_sel:[0,0] op_sel_hi:[1,0]
	v_pk_mul_f32 v[128:129], v[120:121], v[36:37] op_sel:[0,0] op_sel_hi:[1,0]
	v_pk_fma_f32 v[132:133], v[122:123], v[68:69], v[132:133] op_sel:[0,1,0] op_sel_hi:[1,1,1]
	v_pk_fma_f32 v[128:129], v[122:123], v[36:37], v[128:129] op_sel:[0,1,0] op_sel_hi:[1,1,1]
	v_pk_fma_f32 v[132:133], v[124:125], v[70:71], v[132:133] op_sel:[0,0,0] op_sel_hi:[1,0,1]
	v_pk_fma_f32 v[128:129], v[124:125], v[38:39], v[128:129] op_sel:[0,0,0] op_sel_hi:[1,0,1]
	v_pk_fma_f32 v[132:133], v[126:127], v[70:71], v[132:133] op_sel:[0,1,0] op_sel_hi:[1,1,1]
	v_pk_fma_f32 v[128:129], v[126:127], v[38:39], v[128:129] op_sel:[0,1,0] op_sel_hi:[1,1,1]
	ds_read_b64 v[28:29], v197 offset:25856
	s_waitcnt lgkmcnt(6)
	v_cndmask_b32_e64 v134, v133, v132, s[2:3]
	v_cndmask_b32_e64 v135, v132, v133, s[2:3]
	v_cndmask_b32_e64 v136, v129, v128, s[2:3]
	v_cndmask_b32_e64 v137, v128, v129, s[2:3]
	v_add_f32_dpp v138, v135, v134 quad_perm:[1,0,3,2] row_mask:0xf bank_mask:0xf bound_ctrl:1
	v_pk_mul_f32 v[150:151], v[64:65], v[76:77] op_sel:[0,0] op_sel_hi:[0,1]
	v_add_f32_dpp v139, v137, v136 quad_perm:[1,0,3,2] row_mask:0xf bank_mask:0xf bound_ctrl:1
	v_cndmask_b32_e64 v140, v139, v138, s[4:5]
	v_cndmask_b32_e64 v141, v138, v139, s[4:5]
	v_pk_mul_f32 v[152:153], v[64:65], v[76:77] op_sel:[1,0] op_sel_hi:[1,1]
	v_pk_mul_f32 v[154:155], v[66:67], v[76:77] op_sel:[0,0] op_sel_hi:[0,1]
	v_add_f32_dpp v142, v141, v140 quad_perm:[2,3,0,1] row_mask:0xf bank_mask:0xf bound_ctrl:1
	v_pk_mul_f32 v[156:157], v[66:67], v[76:77] op_sel:[1,0] op_sel_hi:[1,1]
	v_pk_fma_f32 v[150:151], v[120:121], v[56:57], v[150:151] op_sel:[0,0,0] op_sel_hi:[1,0,1]
	v_add_f32_dpp v142, v142, v142 row_ror:4 row_mask:0xf bank_mask:0xf bound_ctrl:1
	v_pk_fma_f32 v[152:153], v[122:123], v[56:57], v[152:153] op_sel:[0,1,0] op_sel_hi:[1,1,1]
	v_pk_fma_f32 v[154:155], v[124:125], v[58:59], v[154:155] op_sel:[0,0,0] op_sel_hi:[1,0,1]
	v_add_f32_dpp v146, v142, v142 row_ror:8 row_mask:0xf bank_mask:0xf bound_ctrl:1
	v_pk_fma_f32 v[156:157], v[126:127], v[58:59], v[156:157] op_sel:[0,1,0] op_sel_hi:[1,1,1]
	ds_read_b128 v[32:35], v196 offset:26112
	v_mov_b32_dpp v148, v146 quad_perm:[0,0,0,0] row_mask:0xf bank_mask:0xf
	v_mov_b32_dpp v149, v146 quad_perm:[1,1,1,1] row_mask:0xf bank_mask:0xf
	v_pk_fma_f32 v[120:121], v[72:73], v[148:149], v[150:151] op_sel:[0,0,0] op_sel_hi:[0,1,1]
	ds_read_b128 v[36:39], v196 offset:26368
	v_pk_fma_f32 v[122:123], v[72:73], v[148:149], v[152:153] op_sel:[1,0,0] op_sel_hi:[1,1,1]
	ds_read_b128 v[40:43], v196 offset:26624
	v_pk_fma_f32 v[124:125], v[74:75], v[148:149], v[154:155] op_sel:[0,0,0] op_sel_hi:[0,1,1]
	ds_read_b128 v[44:47], v196 offset:26880
	v_pk_fma_f32 v[126:127], v[74:75], v[148:149], v[156:157] op_sel:[1,0,0] op_sel_hi:[1,1,1]
	ds_read_b128 v[48:51], v196 offset:27136
	v_pk_mul_f32 v[132:133], v[120:121], v[92:93] op_sel:[0,0] op_sel_hi:[1,0]
	v_pk_mul_f32 v[128:129], v[120:121], v[60:61] op_sel:[0,0] op_sel_hi:[1,0]
	v_pk_fma_f32 v[132:133], v[122:123], v[92:93], v[132:133] op_sel:[0,1,0] op_sel_hi:[1,1,1]
	v_pk_fma_f32 v[128:129], v[122:123], v[60:61], v[128:129] op_sel:[0,1,0] op_sel_hi:[1,1,1]
	v_pk_fma_f32 v[132:133], v[124:125], v[94:95], v[132:133] op_sel:[0,0,0] op_sel_hi:[1,0,1]
	v_pk_fma_f32 v[128:129], v[124:125], v[62:63], v[128:129] op_sel:[0,0,0] op_sel_hi:[1,0,1]
	v_pk_fma_f32 v[132:133], v[126:127], v[94:95], v[132:133] op_sel:[0,1,0] op_sel_hi:[1,1,1]
	v_pk_fma_f32 v[128:129], v[126:127], v[62:63], v[128:129] op_sel:[0,1,0] op_sel_hi:[1,1,1]
	ds_read_b64 v[52:53], v197 offset:27392
	s_waitcnt lgkmcnt(6)
	v_cndmask_b32_e64 v134, v133, v132, s[2:3]
	v_cndmask_b32_e64 v135, v132, v133, s[2:3]
	v_cndmask_b32_e64 v136, v129, v128, s[2:3]
	v_cndmask_b32_e64 v137, v128, v129, s[2:3]
	v_add_f32_dpp v138, v135, v134 quad_perm:[1,0,3,2] row_mask:0xf bank_mask:0xf bound_ctrl:1
	v_pk_mul_f32 v[150:151], v[88:89], v[100:101] op_sel:[0,0] op_sel_hi:[0,1]
	v_add_f32_dpp v139, v137, v136 quad_perm:[1,0,3,2] row_mask:0xf bank_mask:0xf bound_ctrl:1
	v_cndmask_b32_e64 v140, v139, v138, s[4:5]
	v_cndmask_b32_e64 v141, v138, v139, s[4:5]
	v_pk_mul_f32 v[152:153], v[88:89], v[100:101] op_sel:[1,0] op_sel_hi:[1,1]
	v_pk_mul_f32 v[154:155], v[90:91], v[100:101] op_sel:[0,0] op_sel_hi:[0,1]
	v_add_f32_dpp v142, v141, v140 quad_perm:[2,3,0,1] row_mask:0xf bank_mask:0xf bound_ctrl:1
	v_pk_mul_f32 v[156:157], v[90:91], v[100:101] op_sel:[1,0] op_sel_hi:[1,1]
	v_pk_fma_f32 v[150:151], v[120:121], v[80:81], v[150:151] op_sel:[0,0,0] op_sel_hi:[1,0,1]
	v_add_f32_dpp v142, v142, v142 row_ror:4 row_mask:0xf bank_mask:0xf bound_ctrl:1
	v_pk_fma_f32 v[152:153], v[122:123], v[80:81], v[152:153] op_sel:[0,1,0] op_sel_hi:[1,1,1]
	v_pk_fma_f32 v[154:155], v[124:125], v[82:83], v[154:155] op_sel:[0,0,0] op_sel_hi:[1,0,1]
	v_add_f32_dpp v147, v142, v142 row_ror:8 row_mask:0xf bank_mask:0xf bound_ctrl:1
	v_pk_fma_f32 v[156:157], v[126:127], v[82:83], v[156:157] op_sel:[0,1,0] op_sel_hi:[1,1,1]
	ds_read_b128 v[56:59], v196 offset:27648
	v_mov_b32_dpp v148, v147 quad_perm:[0,0,0,0] row_mask:0xf bank_mask:0xf
	v_mov_b32_dpp v149, v147 quad_perm:[1,1,1,1] row_mask:0xf bank_mask:0xf
	v_pk_fma_f32 v[120:121], v[96:97], v[148:149], v[150:151] op_sel:[0,0,0] op_sel_hi:[0,1,1]
	ds_read_b128 v[60:63], v196 offset:27904
	v_pk_fma_f32 v[122:123], v[96:97], v[148:149], v[152:153] op_sel:[1,0,0] op_sel_hi:[1,1,1]
	ds_read_b128 v[64:67], v196 offset:28160
	v_pk_fma_f32 v[124:125], v[98:99], v[148:149], v[154:155] op_sel:[0,0,0] op_sel_hi:[0,1,1]
	ds_read_b128 v[68:71], v196 offset:28416
	v_pk_fma_f32 v[126:127], v[98:99], v[148:149], v[156:157] op_sel:[1,0,0] op_sel_hi:[1,1,1]
	ds_read_b128 v[72:75], v196 offset:28672
	v_pk_mul_f32 v[132:133], v[120:121], v[20:21] op_sel:[0,0] op_sel_hi:[1,0]
	v_pk_mul_f32 v[128:129], v[120:121], v[84:85] op_sel:[0,0] op_sel_hi:[1,0]
	v_pk_fma_f32 v[132:133], v[122:123], v[20:21], v[132:133] op_sel:[0,1,0] op_sel_hi:[1,1,1]
	v_pk_fma_f32 v[128:129], v[122:123], v[84:85], v[128:129] op_sel:[0,1,0] op_sel_hi:[1,1,1]
	v_pk_fma_f32 v[132:133], v[124:125], v[22:23], v[132:133] op_sel:[0,0,0] op_sel_hi:[1,0,1]
	v_pk_fma_f32 v[128:129], v[124:125], v[86:87], v[128:129] op_sel:[0,0,0] op_sel_hi:[1,0,1]
	v_pk_fma_f32 v[132:133], v[126:127], v[22:23], v[132:133] op_sel:[0,1,0] op_sel_hi:[1,1,1]
	v_pk_fma_f32 v[128:129], v[126:127], v[86:87], v[128:129] op_sel:[0,1,0] op_sel_hi:[1,1,1]
	ds_read_b64 v[76:77], v197 offset:28928
	v_cndmask_b32_e64 v106, v147, v146, s[12:13]
	v_cndmask_b32_e64 v106, v106, v145, s[10:11]
	v_cndmask_b32_e64 v106, v106, v144, s[6:7]
	s_and_saveexec_b64 s[28:29], s[8:9]
	global_store_dword v[104:105], v106, off
	s_mov_b64 exec, s[28:29]
	v_lshl_add_u64 v[104:105], v[104:105], 0, s[26:27]
	s_waitcnt lgkmcnt(6)
	v_cndmask_b32_e64 v134, v133, v132, s[2:3]
	v_cndmask_b32_e64 v135, v132, v133, s[2:3]
	v_cndmask_b32_e64 v136, v129, v128, s[2:3]
	v_cndmask_b32_e64 v137, v128, v129, s[2:3]
	v_add_f32_dpp v138, v135, v134 quad_perm:[1,0,3,2] row_mask:0xf bank_mask:0xf bound_ctrl:1
	v_pk_mul_f32 v[150:151], v[16:17], v[28:29] op_sel:[0,0] op_sel_hi:[0,1]
	v_add_f32_dpp v139, v137, v136 quad_perm:[1,0,3,2] row_mask:0xf bank_mask:0xf bound_ctrl:1
	v_cndmask_b32_e64 v140, v139, v138, s[4:5]
	v_cndmask_b32_e64 v141, v138, v139, s[4:5]
	v_pk_mul_f32 v[152:153], v[16:17], v[28:29] op_sel:[1,0] op_sel_hi:[1,1]
	v_pk_mul_f32 v[154:155], v[18:19], v[28:29] op_sel:[0,0] op_sel_hi:[0,1]
	v_add_f32_dpp v142, v141, v140 quad_perm:[2,3,0,1] row_mask:0xf bank_mask:0xf bound_ctrl:1
	v_pk_mul_f32 v[156:157], v[18:19], v[28:29] op_sel:[1,0] op_sel_hi:[1,1]
	v_pk_fma_f32 v[150:151], v[120:121], v[8:9], v[150:151] op_sel:[0,0,0] op_sel_hi:[1,0,1]
	v_add_f32_dpp v142, v142, v142 row_ror:4 row_mask:0xf bank_mask:0xf bound_ctrl:1
	v_pk_fma_f32 v[152:153], v[122:123], v[8:9], v[152:153] op_sel:[0,1,0] op_sel_hi:[1,1,1]
	v_pk_fma_f32 v[154:155], v[124:125], v[10:11], v[154:155] op_sel:[0,0,0] op_sel_hi:[1,0,1]
	v_add_f32_dpp v144, v142, v142 row_ror:8 row_mask:0xf bank_mask:0xf bound_ctrl:1
	v_pk_fma_f32 v[156:157], v[126:127], v[10:11], v[156:157] op_sel:[0,1,0] op_sel_hi:[1,1,1]
	ds_read_b128 v[80:83], v196 offset:29184
	v_mov_b32_dpp v148, v144 quad_perm:[0,0,0,0] row_mask:0xf bank_mask:0xf
	v_mov_b32_dpp v149, v144 quad_perm:[1,1,1,1] row_mask:0xf bank_mask:0xf
	v_pk_fma_f32 v[120:121], v[24:25], v[148:149], v[150:151] op_sel:[0,0,0] op_sel_hi:[0,1,1]
	ds_read_b128 v[84:87], v196 offset:29440
	v_pk_fma_f32 v[122:123], v[24:25], v[148:149], v[152:153] op_sel:[1,0,0] op_sel_hi:[1,1,1]
	ds_read_b128 v[88:91], v196 offset:29696
	v_pk_fma_f32 v[124:125], v[26:27], v[148:149], v[154:155] op_sel:[0,0,0] op_sel_hi:[0,1,1]
	ds_read_b128 v[92:95], v196 offset:29952
	v_pk_fma_f32 v[126:127], v[26:27], v[148:149], v[156:157] op_sel:[1,0,0] op_sel_hi:[1,1,1]
	ds_read_b128 v[96:99], v196 offset:30208
	v_pk_mul_f32 v[132:133], v[120:121], v[44:45] op_sel:[0,0] op_sel_hi:[1,0]
	v_pk_mul_f32 v[128:129], v[120:121], v[12:13] op_sel:[0,0] op_sel_hi:[1,0]
	v_pk_fma_f32 v[132:133], v[122:123], v[44:45], v[132:133] op_sel:[0,1,0] op_sel_hi:[1,1,1]
	v_pk_fma_f32 v[128:129], v[122:123], v[12:13], v[128:129] op_sel:[0,1,0] op_sel_hi:[1,1,1]
	v_pk_fma_f32 v[132:133], v[124:125], v[46:47], v[132:133] op_sel:[0,0,0] op_sel_hi:[1,0,1]
	v_pk_fma_f32 v[128:129], v[124:125], v[14:15], v[128:129] op_sel:[0,0,0] op_sel_hi:[1,0,1]
	v_pk_fma_f32 v[132:133], v[126:127], v[46:47], v[132:133] op_sel:[0,1,0] op_sel_hi:[1,1,1]
	v_pk_fma_f32 v[128:129], v[126:127], v[14:15], v[128:129] op_sel:[0,1,0] op_sel_hi:[1,1,1]
	ds_read_b64 v[100:101], v197 offset:30464
	s_waitcnt lgkmcnt(6)
	v_cndmask_b32_e64 v134, v133, v132, s[2:3]
	v_cndmask_b32_e64 v135, v132, v133, s[2:3]
	v_cndmask_b32_e64 v136, v129, v128, s[2:3]
	v_cndmask_b32_e64 v137, v128, v129, s[2:3]
	v_add_f32_dpp v138, v135, v134 quad_perm:[1,0,3,2] row_mask:0xf bank_mask:0xf bound_ctrl:1
	v_pk_mul_f32 v[150:151], v[40:41], v[52:53] op_sel:[0,0] op_sel_hi:[0,1]
	v_add_f32_dpp v139, v137, v136 quad_perm:[1,0,3,2] row_mask:0xf bank_mask:0xf bound_ctrl:1
	v_cndmask_b32_e64 v140, v139, v138, s[4:5]
	v_cndmask_b32_e64 v141, v138, v139, s[4:5]
	v_pk_mul_f32 v[152:153], v[40:41], v[52:53] op_sel:[1,0] op_sel_hi:[1,1]
	v_pk_mul_f32 v[154:155], v[42:43], v[52:53] op_sel:[0,0] op_sel_hi:[0,1]
	v_add_f32_dpp v142, v141, v140 quad_perm:[2,3,0,1] row_mask:0xf bank_mask:0xf bound_ctrl:1
	v_pk_mul_f32 v[156:157], v[42:43], v[52:53] op_sel:[1,0] op_sel_hi:[1,1]
	v_pk_fma_f32 v[150:151], v[120:121], v[32:33], v[150:151] op_sel:[0,0,0] op_sel_hi:[1,0,1]
	v_add_f32_dpp v142, v142, v142 row_ror:4 row_mask:0xf bank_mask:0xf bound_ctrl:1
	v_pk_fma_f32 v[152:153], v[122:123], v[32:33], v[152:153] op_sel:[0,1,0] op_sel_hi:[1,1,1]
	v_pk_fma_f32 v[154:155], v[124:125], v[34:35], v[154:155] op_sel:[0,0,0] op_sel_hi:[1,0,1]
	v_add_f32_dpp v145, v142, v142 row_ror:8 row_mask:0xf bank_mask:0xf bound_ctrl:1
	v_pk_fma_f32 v[156:157], v[126:127], v[34:35], v[156:157] op_sel:[0,1,0] op_sel_hi:[1,1,1]
	ds_read_b128 v[8:11], v196 offset:30720
	v_mov_b32_dpp v148, v145 quad_perm:[0,0,0,0] row_mask:0xf bank_mask:0xf
	v_mov_b32_dpp v149, v145 quad_perm:[1,1,1,1] row_mask:0xf bank_mask:0xf
	v_pk_fma_f32 v[120:121], v[48:49], v[148:149], v[150:151] op_sel:[0,0,0] op_sel_hi:[0,1,1]
	ds_read_b128 v[12:15], v196 offset:30976
	v_pk_fma_f32 v[122:123], v[48:49], v[148:149], v[152:153] op_sel:[1,0,0] op_sel_hi:[1,1,1]
	ds_read_b128 v[16:19], v196 offset:31232
	v_pk_fma_f32 v[124:125], v[50:51], v[148:149], v[154:155] op_sel:[0,0,0] op_sel_hi:[0,1,1]
	ds_read_b128 v[20:23], v196 offset:31488
	v_pk_fma_f32 v[126:127], v[50:51], v[148:149], v[156:157] op_sel:[1,0,0] op_sel_hi:[1,1,1]
	ds_read_b128 v[24:27], v196 offset:31744
	v_pk_mul_f32 v[132:133], v[120:121], v[68:69] op_sel:[0,0] op_sel_hi:[1,0]
	v_pk_mul_f32 v[128:129], v[120:121], v[36:37] op_sel:[0,0] op_sel_hi:[1,0]
	v_pk_fma_f32 v[132:133], v[122:123], v[68:69], v[132:133] op_sel:[0,1,0] op_sel_hi:[1,1,1]
	v_pk_fma_f32 v[128:129], v[122:123], v[36:37], v[128:129] op_sel:[0,1,0] op_sel_hi:[1,1,1]
	v_pk_fma_f32 v[132:133], v[124:125], v[70:71], v[132:133] op_sel:[0,0,0] op_sel_hi:[1,0,1]
	v_pk_fma_f32 v[128:129], v[124:125], v[38:39], v[128:129] op_sel:[0,0,0] op_sel_hi:[1,0,1]
	v_pk_fma_f32 v[132:133], v[126:127], v[70:71], v[132:133] op_sel:[0,1,0] op_sel_hi:[1,1,1]
	v_pk_fma_f32 v[128:129], v[126:127], v[38:39], v[128:129] op_sel:[0,1,0] op_sel_hi:[1,1,1]
	ds_read_b64 v[28:29], v197 offset:32000
	s_waitcnt lgkmcnt(6)
	v_cndmask_b32_e64 v134, v133, v132, s[2:3]
	v_cndmask_b32_e64 v135, v132, v133, s[2:3]
	v_cndmask_b32_e64 v136, v129, v128, s[2:3]
	v_cndmask_b32_e64 v137, v128, v129, s[2:3]
	v_add_f32_dpp v138, v135, v134 quad_perm:[1,0,3,2] row_mask:0xf bank_mask:0xf bound_ctrl:1
	v_pk_mul_f32 v[150:151], v[64:65], v[76:77] op_sel:[0,0] op_sel_hi:[0,1]
	v_add_f32_dpp v139, v137, v136 quad_perm:[1,0,3,2] row_mask:0xf bank_mask:0xf bound_ctrl:1
	v_cndmask_b32_e64 v140, v139, v138, s[4:5]
	v_cndmask_b32_e64 v141, v138, v139, s[4:5]
	v_pk_mul_f32 v[152:153], v[64:65], v[76:77] op_sel:[1,0] op_sel_hi:[1,1]
	v_pk_mul_f32 v[154:155], v[66:67], v[76:77] op_sel:[0,0] op_sel_hi:[0,1]
	v_add_f32_dpp v142, v141, v140 quad_perm:[2,3,0,1] row_mask:0xf bank_mask:0xf bound_ctrl:1
	v_pk_mul_f32 v[156:157], v[66:67], v[76:77] op_sel:[1,0] op_sel_hi:[1,1]
	v_pk_fma_f32 v[150:151], v[120:121], v[56:57], v[150:151] op_sel:[0,0,0] op_sel_hi:[1,0,1]
	v_add_f32_dpp v142, v142, v142 row_ror:4 row_mask:0xf bank_mask:0xf bound_ctrl:1
	v_pk_fma_f32 v[152:153], v[122:123], v[56:57], v[152:153] op_sel:[0,1,0] op_sel_hi:[1,1,1]
	v_pk_fma_f32 v[154:155], v[124:125], v[58:59], v[154:155] op_sel:[0,0,0] op_sel_hi:[1,0,1]
	v_add_f32_dpp v146, v142, v142 row_ror:8 row_mask:0xf bank_mask:0xf bound_ctrl:1
	v_pk_fma_f32 v[156:157], v[126:127], v[58:59], v[156:157] op_sel:[0,1,0] op_sel_hi:[1,1,1]
	ds_read_b128 v[32:35], v196 offset:32256
	v_mov_b32_dpp v148, v146 quad_perm:[0,0,0,0] row_mask:0xf bank_mask:0xf
	v_mov_b32_dpp v149, v146 quad_perm:[1,1,1,1] row_mask:0xf bank_mask:0xf
	v_pk_fma_f32 v[120:121], v[72:73], v[148:149], v[150:151] op_sel:[0,0,0] op_sel_hi:[0,1,1]
	ds_read_b128 v[36:39], v196 offset:32512
	v_pk_fma_f32 v[122:123], v[72:73], v[148:149], v[152:153] op_sel:[1,0,0] op_sel_hi:[1,1,1]
	ds_read_b128 v[40:43], v196 offset:32768
	v_pk_fma_f32 v[124:125], v[74:75], v[148:149], v[154:155] op_sel:[0,0,0] op_sel_hi:[0,1,1]
	ds_read_b128 v[44:47], v196 offset:33024
	v_pk_fma_f32 v[126:127], v[74:75], v[148:149], v[156:157] op_sel:[1,0,0] op_sel_hi:[1,1,1]
	ds_read_b128 v[48:51], v196 offset:33280
	v_pk_mul_f32 v[132:133], v[120:121], v[92:93] op_sel:[0,0] op_sel_hi:[1,0]
	v_pk_mul_f32 v[128:129], v[120:121], v[60:61] op_sel:[0,0] op_sel_hi:[1,0]
	v_pk_fma_f32 v[132:133], v[122:123], v[92:93], v[132:133] op_sel:[0,1,0] op_sel_hi:[1,1,1]
	v_pk_fma_f32 v[128:129], v[122:123], v[60:61], v[128:129] op_sel:[0,1,0] op_sel_hi:[1,1,1]
	v_pk_fma_f32 v[132:133], v[124:125], v[94:95], v[132:133] op_sel:[0,0,0] op_sel_hi:[1,0,1]
	v_pk_fma_f32 v[128:129], v[124:125], v[62:63], v[128:129] op_sel:[0,0,0] op_sel_hi:[1,0,1]
	v_pk_fma_f32 v[132:133], v[126:127], v[94:95], v[132:133] op_sel:[0,1,0] op_sel_hi:[1,1,1]
	v_pk_fma_f32 v[128:129], v[126:127], v[62:63], v[128:129] op_sel:[0,1,0] op_sel_hi:[1,1,1]
	ds_read_b64 v[52:53], v197 offset:33536
	s_waitcnt lgkmcnt(6)
	v_cndmask_b32_e64 v134, v133, v132, s[2:3]
	v_cndmask_b32_e64 v135, v132, v133, s[2:3]
	v_cndmask_b32_e64 v136, v129, v128, s[2:3]
	v_cndmask_b32_e64 v137, v128, v129, s[2:3]
	v_add_f32_dpp v138, v135, v134 quad_perm:[1,0,3,2] row_mask:0xf bank_mask:0xf bound_ctrl:1
	v_pk_mul_f32 v[150:151], v[88:89], v[100:101] op_sel:[0,0] op_sel_hi:[0,1]
	v_add_f32_dpp v139, v137, v136 quad_perm:[1,0,3,2] row_mask:0xf bank_mask:0xf bound_ctrl:1
	v_cndmask_b32_e64 v140, v139, v138, s[4:5]
	v_cndmask_b32_e64 v141, v138, v139, s[4:5]
	v_pk_mul_f32 v[152:153], v[88:89], v[100:101] op_sel:[1,0] op_sel_hi:[1,1]
	v_pk_mul_f32 v[154:155], v[90:91], v[100:101] op_sel:[0,0] op_sel_hi:[0,1]
	v_add_f32_dpp v142, v141, v140 quad_perm:[2,3,0,1] row_mask:0xf bank_mask:0xf bound_ctrl:1
	v_pk_mul_f32 v[156:157], v[90:91], v[100:101] op_sel:[1,0] op_sel_hi:[1,1]
	v_pk_fma_f32 v[150:151], v[120:121], v[80:81], v[150:151] op_sel:[0,0,0] op_sel_hi:[1,0,1]
	v_add_f32_dpp v142, v142, v142 row_ror:4 row_mask:0xf bank_mask:0xf bound_ctrl:1
	v_pk_fma_f32 v[152:153], v[122:123], v[80:81], v[152:153] op_sel:[0,1,0] op_sel_hi:[1,1,1]
	v_pk_fma_f32 v[154:155], v[124:125], v[82:83], v[154:155] op_sel:[0,0,0] op_sel_hi:[1,0,1]
	v_add_f32_dpp v147, v142, v142 row_ror:8 row_mask:0xf bank_mask:0xf bound_ctrl:1
	v_pk_fma_f32 v[156:157], v[126:127], v[82:83], v[156:157] op_sel:[0,1,0] op_sel_hi:[1,1,1]
	ds_read_b128 v[56:59], v196 offset:33792
	v_mov_b32_dpp v148, v147 quad_perm:[0,0,0,0] row_mask:0xf bank_mask:0xf
	v_mov_b32_dpp v149, v147 quad_perm:[1,1,1,1] row_mask:0xf bank_mask:0xf
	v_pk_fma_f32 v[120:121], v[96:97], v[148:149], v[150:151] op_sel:[0,0,0] op_sel_hi:[0,1,1]
	ds_read_b128 v[60:63], v196 offset:34048
	v_pk_fma_f32 v[122:123], v[96:97], v[148:149], v[152:153] op_sel:[1,0,0] op_sel_hi:[1,1,1]
	ds_read_b128 v[64:67], v196 offset:34304
	v_pk_fma_f32 v[124:125], v[98:99], v[148:149], v[154:155] op_sel:[0,0,0] op_sel_hi:[0,1,1]
	ds_read_b128 v[68:71], v196 offset:34560
	v_pk_fma_f32 v[126:127], v[98:99], v[148:149], v[156:157] op_sel:[1,0,0] op_sel_hi:[1,1,1]
	ds_read_b128 v[72:75], v196 offset:34816
	v_pk_mul_f32 v[132:133], v[120:121], v[20:21] op_sel:[0,0] op_sel_hi:[1,0]
	v_pk_mul_f32 v[128:129], v[120:121], v[84:85] op_sel:[0,0] op_sel_hi:[1,0]
	v_pk_fma_f32 v[132:133], v[122:123], v[20:21], v[132:133] op_sel:[0,1,0] op_sel_hi:[1,1,1]
	v_pk_fma_f32 v[128:129], v[122:123], v[84:85], v[128:129] op_sel:[0,1,0] op_sel_hi:[1,1,1]
	v_pk_fma_f32 v[132:133], v[124:125], v[22:23], v[132:133] op_sel:[0,0,0] op_sel_hi:[1,0,1]
	v_pk_fma_f32 v[128:129], v[124:125], v[86:87], v[128:129] op_sel:[0,0,0] op_sel_hi:[1,0,1]
	v_pk_fma_f32 v[132:133], v[126:127], v[22:23], v[132:133] op_sel:[0,1,0] op_sel_hi:[1,1,1]
	v_pk_fma_f32 v[128:129], v[126:127], v[86:87], v[128:129] op_sel:[0,1,0] op_sel_hi:[1,1,1]
	ds_read_b64 v[76:77], v197 offset:35072
	v_cndmask_b32_e64 v106, v147, v146, s[12:13]
	v_cndmask_b32_e64 v106, v106, v145, s[10:11]
	v_cndmask_b32_e64 v106, v106, v144, s[6:7]
	s_and_saveexec_b64 s[28:29], s[8:9]
	global_store_dword v[104:105], v106, off
	s_mov_b64 exec, s[28:29]
	v_lshl_add_u64 v[104:105], v[104:105], 0, s[26:27]
	s_waitcnt lgkmcnt(6)
	v_cndmask_b32_e64 v134, v133, v132, s[2:3]
	v_cndmask_b32_e64 v135, v132, v133, s[2:3]
	v_cndmask_b32_e64 v136, v129, v128, s[2:3]
	v_cndmask_b32_e64 v137, v128, v129, s[2:3]
	v_add_f32_dpp v138, v135, v134 quad_perm:[1,0,3,2] row_mask:0xf bank_mask:0xf bound_ctrl:1
	v_pk_mul_f32 v[150:151], v[16:17], v[28:29] op_sel:[0,0] op_sel_hi:[0,1]
	v_add_f32_dpp v139, v137, v136 quad_perm:[1,0,3,2] row_mask:0xf bank_mask:0xf bound_ctrl:1
	v_cndmask_b32_e64 v140, v139, v138, s[4:5]
	v_cndmask_b32_e64 v141, v138, v139, s[4:5]
	v_pk_mul_f32 v[152:153], v[16:17], v[28:29] op_sel:[1,0] op_sel_hi:[1,1]
	v_pk_mul_f32 v[154:155], v[18:19], v[28:29] op_sel:[0,0] op_sel_hi:[0,1]
	v_add_f32_dpp v142, v141, v140 quad_perm:[2,3,0,1] row_mask:0xf bank_mask:0xf bound_ctrl:1
	v_pk_mul_f32 v[156:157], v[18:19], v[28:29] op_sel:[1,0] op_sel_hi:[1,1]
	v_pk_fma_f32 v[150:151], v[120:121], v[8:9], v[150:151] op_sel:[0,0,0] op_sel_hi:[1,0,1]
	v_add_f32_dpp v142, v142, v142 row_ror:4 row_mask:0xf bank_mask:0xf bound_ctrl:1
	v_pk_fma_f32 v[152:153], v[122:123], v[8:9], v[152:153] op_sel:[0,1,0] op_sel_hi:[1,1,1]
	v_pk_fma_f32 v[154:155], v[124:125], v[10:11], v[154:155] op_sel:[0,0,0] op_sel_hi:[1,0,1]
	v_add_f32_dpp v144, v142, v142 row_ror:8 row_mask:0xf bank_mask:0xf bound_ctrl:1
	v_pk_fma_f32 v[156:157], v[126:127], v[10:11], v[156:157] op_sel:[0,1,0] op_sel_hi:[1,1,1]
	ds_read_b128 v[80:83], v196 offset:35328
	v_mov_b32_dpp v148, v144 quad_perm:[0,0,0,0] row_mask:0xf bank_mask:0xf
	v_mov_b32_dpp v149, v144 quad_perm:[1,1,1,1] row_mask:0xf bank_mask:0xf
	v_pk_fma_f32 v[120:121], v[24:25], v[148:149], v[150:151] op_sel:[0,0,0] op_sel_hi:[0,1,1]
	ds_read_b128 v[84:87], v196 offset:35584
	v_pk_fma_f32 v[122:123], v[24:25], v[148:149], v[152:153] op_sel:[1,0,0] op_sel_hi:[1,1,1]
	ds_read_b128 v[88:91], v196 offset:35840
	v_pk_fma_f32 v[124:125], v[26:27], v[148:149], v[154:155] op_sel:[0,0,0] op_sel_hi:[0,1,1]
	ds_read_b128 v[92:95], v196 offset:36096
	v_pk_fma_f32 v[126:127], v[26:27], v[148:149], v[156:157] op_sel:[1,0,0] op_sel_hi:[1,1,1]
	ds_read_b128 v[96:99], v196 offset:36352
	v_pk_mul_f32 v[132:133], v[120:121], v[44:45] op_sel:[0,0] op_sel_hi:[1,0]
	v_pk_mul_f32 v[128:129], v[120:121], v[12:13] op_sel:[0,0] op_sel_hi:[1,0]
	v_pk_fma_f32 v[132:133], v[122:123], v[44:45], v[132:133] op_sel:[0,1,0] op_sel_hi:[1,1,1]
	v_pk_fma_f32 v[128:129], v[122:123], v[12:13], v[128:129] op_sel:[0,1,0] op_sel_hi:[1,1,1]
	v_pk_fma_f32 v[132:133], v[124:125], v[46:47], v[132:133] op_sel:[0,0,0] op_sel_hi:[1,0,1]
	v_pk_fma_f32 v[128:129], v[124:125], v[14:15], v[128:129] op_sel:[0,0,0] op_sel_hi:[1,0,1]
	v_pk_fma_f32 v[132:133], v[126:127], v[46:47], v[132:133] op_sel:[0,1,0] op_sel_hi:[1,1,1]
	v_pk_fma_f32 v[128:129], v[126:127], v[14:15], v[128:129] op_sel:[0,1,0] op_sel_hi:[1,1,1]
	ds_read_b64 v[100:101], v197 offset:36608
	s_waitcnt lgkmcnt(6)
	v_cndmask_b32_e64 v134, v133, v132, s[2:3]
	v_cndmask_b32_e64 v135, v132, v133, s[2:3]
	v_cndmask_b32_e64 v136, v129, v128, s[2:3]
	v_cndmask_b32_e64 v137, v128, v129, s[2:3]
	v_add_f32_dpp v138, v135, v134 quad_perm:[1,0,3,2] row_mask:0xf bank_mask:0xf bound_ctrl:1
	v_pk_mul_f32 v[150:151], v[40:41], v[52:53] op_sel:[0,0] op_sel_hi:[0,1]
	v_add_f32_dpp v139, v137, v136 quad_perm:[1,0,3,2] row_mask:0xf bank_mask:0xf bound_ctrl:1
	v_cndmask_b32_e64 v140, v139, v138, s[4:5]
	v_cndmask_b32_e64 v141, v138, v139, s[4:5]
	v_pk_mul_f32 v[152:153], v[40:41], v[52:53] op_sel:[1,0] op_sel_hi:[1,1]
	v_pk_mul_f32 v[154:155], v[42:43], v[52:53] op_sel:[0,0] op_sel_hi:[0,1]
	v_add_f32_dpp v142, v141, v140 quad_perm:[2,3,0,1] row_mask:0xf bank_mask:0xf bound_ctrl:1
	v_pk_mul_f32 v[156:157], v[42:43], v[52:53] op_sel:[1,0] op_sel_hi:[1,1]
	v_pk_fma_f32 v[150:151], v[120:121], v[32:33], v[150:151] op_sel:[0,0,0] op_sel_hi:[1,0,1]
	v_add_f32_dpp v142, v142, v142 row_ror:4 row_mask:0xf bank_mask:0xf bound_ctrl:1
	v_pk_fma_f32 v[152:153], v[122:123], v[32:33], v[152:153] op_sel:[0,1,0] op_sel_hi:[1,1,1]
	v_pk_fma_f32 v[154:155], v[124:125], v[34:35], v[154:155] op_sel:[0,0,0] op_sel_hi:[1,0,1]
	v_add_f32_dpp v145, v142, v142 row_ror:8 row_mask:0xf bank_mask:0xf bound_ctrl:1
	v_pk_fma_f32 v[156:157], v[126:127], v[34:35], v[156:157] op_sel:[0,1,0] op_sel_hi:[1,1,1]
	ds_read_b128 v[8:11], v196 offset:36864
	v_mov_b32_dpp v148, v145 quad_perm:[0,0,0,0] row_mask:0xf bank_mask:0xf
	v_mov_b32_dpp v149, v145 quad_perm:[1,1,1,1] row_mask:0xf bank_mask:0xf
	v_pk_fma_f32 v[120:121], v[48:49], v[148:149], v[150:151] op_sel:[0,0,0] op_sel_hi:[0,1,1]
	ds_read_b128 v[12:15], v196 offset:37120
	v_pk_fma_f32 v[122:123], v[48:49], v[148:149], v[152:153] op_sel:[1,0,0] op_sel_hi:[1,1,1]
	ds_read_b128 v[16:19], v196 offset:37376
	v_pk_fma_f32 v[124:125], v[50:51], v[148:149], v[154:155] op_sel:[0,0,0] op_sel_hi:[0,1,1]
	ds_read_b128 v[20:23], v196 offset:37632
	v_pk_fma_f32 v[126:127], v[50:51], v[148:149], v[156:157] op_sel:[1,0,0] op_sel_hi:[1,1,1]
	ds_read_b128 v[24:27], v196 offset:37888
	v_pk_mul_f32 v[132:133], v[120:121], v[68:69] op_sel:[0,0] op_sel_hi:[1,0]
	v_pk_mul_f32 v[128:129], v[120:121], v[36:37] op_sel:[0,0] op_sel_hi:[1,0]
	v_pk_fma_f32 v[132:133], v[122:123], v[68:69], v[132:133] op_sel:[0,1,0] op_sel_hi:[1,1,1]
	v_pk_fma_f32 v[128:129], v[122:123], v[36:37], v[128:129] op_sel:[0,1,0] op_sel_hi:[1,1,1]
	v_pk_fma_f32 v[132:133], v[124:125], v[70:71], v[132:133] op_sel:[0,0,0] op_sel_hi:[1,0,1]
	v_pk_fma_f32 v[128:129], v[124:125], v[38:39], v[128:129] op_sel:[0,0,0] op_sel_hi:[1,0,1]
	v_pk_fma_f32 v[132:133], v[126:127], v[70:71], v[132:133] op_sel:[0,1,0] op_sel_hi:[1,1,1]
	v_pk_fma_f32 v[128:129], v[126:127], v[38:39], v[128:129] op_sel:[0,1,0] op_sel_hi:[1,1,1]
	ds_read_b64 v[28:29], v197 offset:38144
	s_waitcnt lgkmcnt(6)
	v_cndmask_b32_e64 v134, v133, v132, s[2:3]
	v_cndmask_b32_e64 v135, v132, v133, s[2:3]
	v_cndmask_b32_e64 v136, v129, v128, s[2:3]
	v_cndmask_b32_e64 v137, v128, v129, s[2:3]
	v_add_f32_dpp v138, v135, v134 quad_perm:[1,0,3,2] row_mask:0xf bank_mask:0xf bound_ctrl:1
	v_pk_mul_f32 v[150:151], v[64:65], v[76:77] op_sel:[0,0] op_sel_hi:[0,1]
	v_add_f32_dpp v139, v137, v136 quad_perm:[1,0,3,2] row_mask:0xf bank_mask:0xf bound_ctrl:1
	v_cndmask_b32_e64 v140, v139, v138, s[4:5]
	v_cndmask_b32_e64 v141, v138, v139, s[4:5]
	v_pk_mul_f32 v[152:153], v[64:65], v[76:77] op_sel:[1,0] op_sel_hi:[1,1]
	v_pk_mul_f32 v[154:155], v[66:67], v[76:77] op_sel:[0,0] op_sel_hi:[0,1]
	v_add_f32_dpp v142, v141, v140 quad_perm:[2,3,0,1] row_mask:0xf bank_mask:0xf bound_ctrl:1
	v_pk_mul_f32 v[156:157], v[66:67], v[76:77] op_sel:[1,0] op_sel_hi:[1,1]
	v_pk_fma_f32 v[150:151], v[120:121], v[56:57], v[150:151] op_sel:[0,0,0] op_sel_hi:[1,0,1]
	v_add_f32_dpp v142, v142, v142 row_ror:4 row_mask:0xf bank_mask:0xf bound_ctrl:1
	v_pk_fma_f32 v[152:153], v[122:123], v[56:57], v[152:153] op_sel:[0,1,0] op_sel_hi:[1,1,1]
	v_pk_fma_f32 v[154:155], v[124:125], v[58:59], v[154:155] op_sel:[0,0,0] op_sel_hi:[1,0,1]
	v_add_f32_dpp v146, v142, v142 row_ror:8 row_mask:0xf bank_mask:0xf bound_ctrl:1
	v_pk_fma_f32 v[156:157], v[126:127], v[58:59], v[156:157] op_sel:[0,1,0] op_sel_hi:[1,1,1]
	ds_read_b128 v[32:35], v196 offset:38400
	v_mov_b32_dpp v148, v146 quad_perm:[0,0,0,0] row_mask:0xf bank_mask:0xf
	v_mov_b32_dpp v149, v146 quad_perm:[1,1,1,1] row_mask:0xf bank_mask:0xf
	v_pk_fma_f32 v[120:121], v[72:73], v[148:149], v[150:151] op_sel:[0,0,0] op_sel_hi:[0,1,1]
	ds_read_b128 v[36:39], v196 offset:38656
	v_pk_fma_f32 v[122:123], v[72:73], v[148:149], v[152:153] op_sel:[1,0,0] op_sel_hi:[1,1,1]
	ds_read_b128 v[40:43], v196 offset:38912
	v_pk_fma_f32 v[124:125], v[74:75], v[148:149], v[154:155] op_sel:[0,0,0] op_sel_hi:[0,1,1]
	ds_read_b128 v[44:47], v196 offset:39168
	v_pk_fma_f32 v[126:127], v[74:75], v[148:149], v[156:157] op_sel:[1,0,0] op_sel_hi:[1,1,1]
	ds_read_b128 v[48:51], v196 offset:39424
	v_pk_mul_f32 v[132:133], v[120:121], v[92:93] op_sel:[0,0] op_sel_hi:[1,0]
	v_pk_mul_f32 v[128:129], v[120:121], v[60:61] op_sel:[0,0] op_sel_hi:[1,0]
	v_pk_fma_f32 v[132:133], v[122:123], v[92:93], v[132:133] op_sel:[0,1,0] op_sel_hi:[1,1,1]
	v_pk_fma_f32 v[128:129], v[122:123], v[60:61], v[128:129] op_sel:[0,1,0] op_sel_hi:[1,1,1]
	v_pk_fma_f32 v[132:133], v[124:125], v[94:95], v[132:133] op_sel:[0,0,0] op_sel_hi:[1,0,1]
	v_pk_fma_f32 v[128:129], v[124:125], v[62:63], v[128:129] op_sel:[0,0,0] op_sel_hi:[1,0,1]
	v_pk_fma_f32 v[132:133], v[126:127], v[94:95], v[132:133] op_sel:[0,1,0] op_sel_hi:[1,1,1]
	v_pk_fma_f32 v[128:129], v[126:127], v[62:63], v[128:129] op_sel:[0,1,0] op_sel_hi:[1,1,1]
	ds_read_b64 v[52:53], v197 offset:39680
	s_waitcnt lgkmcnt(6)
	v_cndmask_b32_e64 v134, v133, v132, s[2:3]
	v_cndmask_b32_e64 v135, v132, v133, s[2:3]
	v_cndmask_b32_e64 v136, v129, v128, s[2:3]
	v_cndmask_b32_e64 v137, v128, v129, s[2:3]
	v_add_f32_dpp v138, v135, v134 quad_perm:[1,0,3,2] row_mask:0xf bank_mask:0xf bound_ctrl:1
	v_pk_mul_f32 v[150:151], v[88:89], v[100:101] op_sel:[0,0] op_sel_hi:[0,1]
	v_add_f32_dpp v139, v137, v136 quad_perm:[1,0,3,2] row_mask:0xf bank_mask:0xf bound_ctrl:1
	v_cndmask_b32_e64 v140, v139, v138, s[4:5]
	v_cndmask_b32_e64 v141, v138, v139, s[4:5]
	v_pk_mul_f32 v[152:153], v[88:89], v[100:101] op_sel:[1,0] op_sel_hi:[1,1]
	v_pk_mul_f32 v[154:155], v[90:91], v[100:101] op_sel:[0,0] op_sel_hi:[0,1]
	v_add_f32_dpp v142, v141, v140 quad_perm:[2,3,0,1] row_mask:0xf bank_mask:0xf bound_ctrl:1
	v_pk_mul_f32 v[156:157], v[90:91], v[100:101] op_sel:[1,0] op_sel_hi:[1,1]
	v_pk_fma_f32 v[150:151], v[120:121], v[80:81], v[150:151] op_sel:[0,0,0] op_sel_hi:[1,0,1]
	v_add_f32_dpp v142, v142, v142 row_ror:4 row_mask:0xf bank_mask:0xf bound_ctrl:1
	v_pk_fma_f32 v[152:153], v[122:123], v[80:81], v[152:153] op_sel:[0,1,0] op_sel_hi:[1,1,1]
	v_pk_fma_f32 v[154:155], v[124:125], v[82:83], v[154:155] op_sel:[0,0,0] op_sel_hi:[1,0,1]
	v_add_f32_dpp v147, v142, v142 row_ror:8 row_mask:0xf bank_mask:0xf bound_ctrl:1
	v_pk_fma_f32 v[156:157], v[126:127], v[82:83], v[156:157] op_sel:[0,1,0] op_sel_hi:[1,1,1]
	ds_read_b128 v[56:59], v196 offset:39936
	v_mov_b32_dpp v148, v147 quad_perm:[0,0,0,0] row_mask:0xf bank_mask:0xf
	v_mov_b32_dpp v149, v147 quad_perm:[1,1,1,1] row_mask:0xf bank_mask:0xf
	v_pk_fma_f32 v[120:121], v[96:97], v[148:149], v[150:151] op_sel:[0,0,0] op_sel_hi:[0,1,1]
	ds_read_b128 v[60:63], v196 offset:40192
	v_pk_fma_f32 v[122:123], v[96:97], v[148:149], v[152:153] op_sel:[1,0,0] op_sel_hi:[1,1,1]
	ds_read_b128 v[64:67], v196 offset:40448
	v_pk_fma_f32 v[124:125], v[98:99], v[148:149], v[154:155] op_sel:[0,0,0] op_sel_hi:[0,1,1]
	ds_read_b128 v[68:71], v196 offset:40704
	v_pk_fma_f32 v[126:127], v[98:99], v[148:149], v[156:157] op_sel:[1,0,0] op_sel_hi:[1,1,1]
	ds_read_b128 v[72:75], v196 offset:40960
	v_pk_mul_f32 v[132:133], v[120:121], v[20:21] op_sel:[0,0] op_sel_hi:[1,0]
	v_pk_mul_f32 v[128:129], v[120:121], v[84:85] op_sel:[0,0] op_sel_hi:[1,0]
	v_pk_fma_f32 v[132:133], v[122:123], v[20:21], v[132:133] op_sel:[0,1,0] op_sel_hi:[1,1,1]
	v_pk_fma_f32 v[128:129], v[122:123], v[84:85], v[128:129] op_sel:[0,1,0] op_sel_hi:[1,1,1]
	v_pk_fma_f32 v[132:133], v[124:125], v[22:23], v[132:133] op_sel:[0,0,0] op_sel_hi:[1,0,1]
	v_pk_fma_f32 v[128:129], v[124:125], v[86:87], v[128:129] op_sel:[0,0,0] op_sel_hi:[1,0,1]
	v_pk_fma_f32 v[132:133], v[126:127], v[22:23], v[132:133] op_sel:[0,1,0] op_sel_hi:[1,1,1]
	v_pk_fma_f32 v[128:129], v[126:127], v[86:87], v[128:129] op_sel:[0,1,0] op_sel_hi:[1,1,1]
	ds_read_b64 v[76:77], v197 offset:41216
	v_cndmask_b32_e64 v106, v147, v146, s[12:13]
	v_cndmask_b32_e64 v106, v106, v145, s[10:11]
	v_cndmask_b32_e64 v106, v106, v144, s[6:7]
	s_and_saveexec_b64 s[28:29], s[8:9]
	global_store_dword v[104:105], v106, off
	s_mov_b64 exec, s[28:29]
	v_lshl_add_u64 v[104:105], v[104:105], 0, s[26:27]
	s_waitcnt lgkmcnt(6)
	v_cndmask_b32_e64 v134, v133, v132, s[2:3]
	v_cndmask_b32_e64 v135, v132, v133, s[2:3]
	v_cndmask_b32_e64 v136, v129, v128, s[2:3]
	v_cndmask_b32_e64 v137, v128, v129, s[2:3]
	v_add_f32_dpp v138, v135, v134 quad_perm:[1,0,3,2] row_mask:0xf bank_mask:0xf bound_ctrl:1
	v_pk_mul_f32 v[150:151], v[16:17], v[28:29] op_sel:[0,0] op_sel_hi:[0,1]
	v_add_f32_dpp v139, v137, v136 quad_perm:[1,0,3,2] row_mask:0xf bank_mask:0xf bound_ctrl:1
	v_cndmask_b32_e64 v140, v139, v138, s[4:5]
	v_cndmask_b32_e64 v141, v138, v139, s[4:5]
	v_pk_mul_f32 v[152:153], v[16:17], v[28:29] op_sel:[1,0] op_sel_hi:[1,1]
	v_pk_mul_f32 v[154:155], v[18:19], v[28:29] op_sel:[0,0] op_sel_hi:[0,1]
	v_add_f32_dpp v142, v141, v140 quad_perm:[2,3,0,1] row_mask:0xf bank_mask:0xf bound_ctrl:1
	v_pk_mul_f32 v[156:157], v[18:19], v[28:29] op_sel:[1,0] op_sel_hi:[1,1]
	v_pk_fma_f32 v[150:151], v[120:121], v[8:9], v[150:151] op_sel:[0,0,0] op_sel_hi:[1,0,1]
	v_add_f32_dpp v142, v142, v142 row_ror:4 row_mask:0xf bank_mask:0xf bound_ctrl:1
	v_pk_fma_f32 v[152:153], v[122:123], v[8:9], v[152:153] op_sel:[0,1,0] op_sel_hi:[1,1,1]
	v_pk_fma_f32 v[154:155], v[124:125], v[10:11], v[154:155] op_sel:[0,0,0] op_sel_hi:[1,0,1]
	v_add_f32_dpp v144, v142, v142 row_ror:8 row_mask:0xf bank_mask:0xf bound_ctrl:1
	v_pk_fma_f32 v[156:157], v[126:127], v[10:11], v[156:157] op_sel:[0,1,0] op_sel_hi:[1,1,1]
	ds_read_b128 v[80:83], v196 offset:41472
	v_mov_b32_dpp v148, v144 quad_perm:[0,0,0,0] row_mask:0xf bank_mask:0xf
	v_mov_b32_dpp v149, v144 quad_perm:[1,1,1,1] row_mask:0xf bank_mask:0xf
	v_pk_fma_f32 v[120:121], v[24:25], v[148:149], v[150:151] op_sel:[0,0,0] op_sel_hi:[0,1,1]
	ds_read_b128 v[84:87], v196 offset:41728
	v_pk_fma_f32 v[122:123], v[24:25], v[148:149], v[152:153] op_sel:[1,0,0] op_sel_hi:[1,1,1]
	ds_read_b128 v[88:91], v196 offset:41984
	v_pk_fma_f32 v[124:125], v[26:27], v[148:149], v[154:155] op_sel:[0,0,0] op_sel_hi:[0,1,1]
	ds_read_b128 v[92:95], v196 offset:42240
	v_pk_fma_f32 v[126:127], v[26:27], v[148:149], v[156:157] op_sel:[1,0,0] op_sel_hi:[1,1,1]
	ds_read_b128 v[96:99], v196 offset:42496
	v_pk_mul_f32 v[132:133], v[120:121], v[44:45] op_sel:[0,0] op_sel_hi:[1,0]
	v_pk_mul_f32 v[128:129], v[120:121], v[12:13] op_sel:[0,0] op_sel_hi:[1,0]
	v_pk_fma_f32 v[132:133], v[122:123], v[44:45], v[132:133] op_sel:[0,1,0] op_sel_hi:[1,1,1]
	v_pk_fma_f32 v[128:129], v[122:123], v[12:13], v[128:129] op_sel:[0,1,0] op_sel_hi:[1,1,1]
	v_pk_fma_f32 v[132:133], v[124:125], v[46:47], v[132:133] op_sel:[0,0,0] op_sel_hi:[1,0,1]
	v_pk_fma_f32 v[128:129], v[124:125], v[14:15], v[128:129] op_sel:[0,0,0] op_sel_hi:[1,0,1]
	v_pk_fma_f32 v[132:133], v[126:127], v[46:47], v[132:133] op_sel:[0,1,0] op_sel_hi:[1,1,1]
	v_pk_fma_f32 v[128:129], v[126:127], v[14:15], v[128:129] op_sel:[0,1,0] op_sel_hi:[1,1,1]
	ds_read_b64 v[100:101], v197 offset:42752
	s_waitcnt lgkmcnt(6)
	v_cndmask_b32_e64 v134, v133, v132, s[2:3]
	v_cndmask_b32_e64 v135, v132, v133, s[2:3]
	v_cndmask_b32_e64 v136, v129, v128, s[2:3]
	v_cndmask_b32_e64 v137, v128, v129, s[2:3]
	v_add_f32_dpp v138, v135, v134 quad_perm:[1,0,3,2] row_mask:0xf bank_mask:0xf bound_ctrl:1
	v_pk_mul_f32 v[150:151], v[40:41], v[52:53] op_sel:[0,0] op_sel_hi:[0,1]
	v_add_f32_dpp v139, v137, v136 quad_perm:[1,0,3,2] row_mask:0xf bank_mask:0xf bound_ctrl:1
	v_cndmask_b32_e64 v140, v139, v138, s[4:5]
	v_cndmask_b32_e64 v141, v138, v139, s[4:5]
	v_pk_mul_f32 v[152:153], v[40:41], v[52:53] op_sel:[1,0] op_sel_hi:[1,1]
	v_pk_mul_f32 v[154:155], v[42:43], v[52:53] op_sel:[0,0] op_sel_hi:[0,1]
	v_add_f32_dpp v142, v141, v140 quad_perm:[2,3,0,1] row_mask:0xf bank_mask:0xf bound_ctrl:1
	v_pk_mul_f32 v[156:157], v[42:43], v[52:53] op_sel:[1,0] op_sel_hi:[1,1]
	v_pk_fma_f32 v[150:151], v[120:121], v[32:33], v[150:151] op_sel:[0,0,0] op_sel_hi:[1,0,1]
	v_add_f32_dpp v142, v142, v142 row_ror:4 row_mask:0xf bank_mask:0xf bound_ctrl:1
	v_pk_fma_f32 v[152:153], v[122:123], v[32:33], v[152:153] op_sel:[0,1,0] op_sel_hi:[1,1,1]
	v_pk_fma_f32 v[154:155], v[124:125], v[34:35], v[154:155] op_sel:[0,0,0] op_sel_hi:[1,0,1]
	v_add_f32_dpp v145, v142, v142 row_ror:8 row_mask:0xf bank_mask:0xf bound_ctrl:1
	v_pk_fma_f32 v[156:157], v[126:127], v[34:35], v[156:157] op_sel:[0,1,0] op_sel_hi:[1,1,1]
	ds_read_b128 v[8:11], v196 offset:43008
	v_mov_b32_dpp v148, v145 quad_perm:[0,0,0,0] row_mask:0xf bank_mask:0xf
	v_mov_b32_dpp v149, v145 quad_perm:[1,1,1,1] row_mask:0xf bank_mask:0xf
	v_pk_fma_f32 v[120:121], v[48:49], v[148:149], v[150:151] op_sel:[0,0,0] op_sel_hi:[0,1,1]
	ds_read_b128 v[12:15], v196 offset:43264
	v_pk_fma_f32 v[122:123], v[48:49], v[148:149], v[152:153] op_sel:[1,0,0] op_sel_hi:[1,1,1]
	ds_read_b128 v[16:19], v196 offset:43520
	v_pk_fma_f32 v[124:125], v[50:51], v[148:149], v[154:155] op_sel:[0,0,0] op_sel_hi:[0,1,1]
	ds_read_b128 v[20:23], v196 offset:43776
	v_pk_fma_f32 v[126:127], v[50:51], v[148:149], v[156:157] op_sel:[1,0,0] op_sel_hi:[1,1,1]
	ds_read_b128 v[24:27], v196 offset:44032
	v_pk_mul_f32 v[132:133], v[120:121], v[68:69] op_sel:[0,0] op_sel_hi:[1,0]
	v_pk_mul_f32 v[128:129], v[120:121], v[36:37] op_sel:[0,0] op_sel_hi:[1,0]
	v_pk_fma_f32 v[132:133], v[122:123], v[68:69], v[132:133] op_sel:[0,1,0] op_sel_hi:[1,1,1]
	v_pk_fma_f32 v[128:129], v[122:123], v[36:37], v[128:129] op_sel:[0,1,0] op_sel_hi:[1,1,1]
	v_pk_fma_f32 v[132:133], v[124:125], v[70:71], v[132:133] op_sel:[0,0,0] op_sel_hi:[1,0,1]
	v_pk_fma_f32 v[128:129], v[124:125], v[38:39], v[128:129] op_sel:[0,0,0] op_sel_hi:[1,0,1]
	v_pk_fma_f32 v[132:133], v[126:127], v[70:71], v[132:133] op_sel:[0,1,0] op_sel_hi:[1,1,1]
	v_pk_fma_f32 v[128:129], v[126:127], v[38:39], v[128:129] op_sel:[0,1,0] op_sel_hi:[1,1,1]
	ds_read_b64 v[28:29], v197 offset:44288
	s_waitcnt lgkmcnt(6)
	v_cndmask_b32_e64 v134, v133, v132, s[2:3]
	v_cndmask_b32_e64 v135, v132, v133, s[2:3]
	v_cndmask_b32_e64 v136, v129, v128, s[2:3]
	v_cndmask_b32_e64 v137, v128, v129, s[2:3]
	v_add_f32_dpp v138, v135, v134 quad_perm:[1,0,3,2] row_mask:0xf bank_mask:0xf bound_ctrl:1
	v_pk_mul_f32 v[150:151], v[64:65], v[76:77] op_sel:[0,0] op_sel_hi:[0,1]
	v_add_f32_dpp v139, v137, v136 quad_perm:[1,0,3,2] row_mask:0xf bank_mask:0xf bound_ctrl:1
	v_cndmask_b32_e64 v140, v139, v138, s[4:5]
	v_cndmask_b32_e64 v141, v138, v139, s[4:5]
	v_pk_mul_f32 v[152:153], v[64:65], v[76:77] op_sel:[1,0] op_sel_hi:[1,1]
	v_pk_mul_f32 v[154:155], v[66:67], v[76:77] op_sel:[0,0] op_sel_hi:[0,1]
	v_add_f32_dpp v142, v141, v140 quad_perm:[2,3,0,1] row_mask:0xf bank_mask:0xf bound_ctrl:1
	v_pk_mul_f32 v[156:157], v[66:67], v[76:77] op_sel:[1,0] op_sel_hi:[1,1]
	v_pk_fma_f32 v[150:151], v[120:121], v[56:57], v[150:151] op_sel:[0,0,0] op_sel_hi:[1,0,1]
	v_add_f32_dpp v142, v142, v142 row_ror:4 row_mask:0xf bank_mask:0xf bound_ctrl:1
	v_pk_fma_f32 v[152:153], v[122:123], v[56:57], v[152:153] op_sel:[0,1,0] op_sel_hi:[1,1,1]
	v_pk_fma_f32 v[154:155], v[124:125], v[58:59], v[154:155] op_sel:[0,0,0] op_sel_hi:[1,0,1]
	v_add_f32_dpp v146, v142, v142 row_ror:8 row_mask:0xf bank_mask:0xf bound_ctrl:1
	v_pk_fma_f32 v[156:157], v[126:127], v[58:59], v[156:157] op_sel:[0,1,0] op_sel_hi:[1,1,1]
	ds_read_b128 v[32:35], v196 offset:44544
	v_mov_b32_dpp v148, v146 quad_perm:[0,0,0,0] row_mask:0xf bank_mask:0xf
	v_mov_b32_dpp v149, v146 quad_perm:[1,1,1,1] row_mask:0xf bank_mask:0xf
	v_pk_fma_f32 v[120:121], v[72:73], v[148:149], v[150:151] op_sel:[0,0,0] op_sel_hi:[0,1,1]
	ds_read_b128 v[36:39], v196 offset:44800
	v_pk_fma_f32 v[122:123], v[72:73], v[148:149], v[152:153] op_sel:[1,0,0] op_sel_hi:[1,1,1]
	ds_read_b128 v[40:43], v196 offset:45056
	v_pk_fma_f32 v[124:125], v[74:75], v[148:149], v[154:155] op_sel:[0,0,0] op_sel_hi:[0,1,1]
	ds_read_b128 v[44:47], v196 offset:45312
	v_pk_fma_f32 v[126:127], v[74:75], v[148:149], v[156:157] op_sel:[1,0,0] op_sel_hi:[1,1,1]
	ds_read_b128 v[48:51], v196 offset:45568
	v_pk_mul_f32 v[132:133], v[120:121], v[92:93] op_sel:[0,0] op_sel_hi:[1,0]
	v_pk_mul_f32 v[128:129], v[120:121], v[60:61] op_sel:[0,0] op_sel_hi:[1,0]
	v_pk_fma_f32 v[132:133], v[122:123], v[92:93], v[132:133] op_sel:[0,1,0] op_sel_hi:[1,1,1]
	v_pk_fma_f32 v[128:129], v[122:123], v[60:61], v[128:129] op_sel:[0,1,0] op_sel_hi:[1,1,1]
	v_pk_fma_f32 v[132:133], v[124:125], v[94:95], v[132:133] op_sel:[0,0,0] op_sel_hi:[1,0,1]
	v_pk_fma_f32 v[128:129], v[124:125], v[62:63], v[128:129] op_sel:[0,0,0] op_sel_hi:[1,0,1]
	v_pk_fma_f32 v[132:133], v[126:127], v[94:95], v[132:133] op_sel:[0,1,0] op_sel_hi:[1,1,1]
	v_pk_fma_f32 v[128:129], v[126:127], v[62:63], v[128:129] op_sel:[0,1,0] op_sel_hi:[1,1,1]
	ds_read_b64 v[52:53], v197 offset:45824
	s_waitcnt lgkmcnt(6)
	v_cndmask_b32_e64 v134, v133, v132, s[2:3]
	v_cndmask_b32_e64 v135, v132, v133, s[2:3]
	v_cndmask_b32_e64 v136, v129, v128, s[2:3]
	v_cndmask_b32_e64 v137, v128, v129, s[2:3]
	v_add_f32_dpp v138, v135, v134 quad_perm:[1,0,3,2] row_mask:0xf bank_mask:0xf bound_ctrl:1
	v_pk_mul_f32 v[150:151], v[88:89], v[100:101] op_sel:[0,0] op_sel_hi:[0,1]
	v_add_f32_dpp v139, v137, v136 quad_perm:[1,0,3,2] row_mask:0xf bank_mask:0xf bound_ctrl:1
	v_cndmask_b32_e64 v140, v139, v138, s[4:5]
	v_cndmask_b32_e64 v141, v138, v139, s[4:5]
	v_pk_mul_f32 v[152:153], v[88:89], v[100:101] op_sel:[1,0] op_sel_hi:[1,1]
	v_pk_mul_f32 v[154:155], v[90:91], v[100:101] op_sel:[0,0] op_sel_hi:[0,1]
	v_add_f32_dpp v142, v141, v140 quad_perm:[2,3,0,1] row_mask:0xf bank_mask:0xf bound_ctrl:1
	v_pk_mul_f32 v[156:157], v[90:91], v[100:101] op_sel:[1,0] op_sel_hi:[1,1]
	v_pk_fma_f32 v[150:151], v[120:121], v[80:81], v[150:151] op_sel:[0,0,0] op_sel_hi:[1,0,1]
	v_add_f32_dpp v142, v142, v142 row_ror:4 row_mask:0xf bank_mask:0xf bound_ctrl:1
	v_pk_fma_f32 v[152:153], v[122:123], v[80:81], v[152:153] op_sel:[0,1,0] op_sel_hi:[1,1,1]
	v_pk_fma_f32 v[154:155], v[124:125], v[82:83], v[154:155] op_sel:[0,0,0] op_sel_hi:[1,0,1]
	v_add_f32_dpp v147, v142, v142 row_ror:8 row_mask:0xf bank_mask:0xf bound_ctrl:1
	v_pk_fma_f32 v[156:157], v[126:127], v[82:83], v[156:157] op_sel:[0,1,0] op_sel_hi:[1,1,1]
	ds_read_b128 v[56:59], v196 offset:46080
	v_mov_b32_dpp v148, v147 quad_perm:[0,0,0,0] row_mask:0xf bank_mask:0xf
	v_mov_b32_dpp v149, v147 quad_perm:[1,1,1,1] row_mask:0xf bank_mask:0xf
	v_pk_fma_f32 v[120:121], v[96:97], v[148:149], v[150:151] op_sel:[0,0,0] op_sel_hi:[0,1,1]
	ds_read_b128 v[60:63], v196 offset:46336
	v_pk_fma_f32 v[122:123], v[96:97], v[148:149], v[152:153] op_sel:[1,0,0] op_sel_hi:[1,1,1]
	ds_read_b128 v[64:67], v196 offset:46592
	v_pk_fma_f32 v[124:125], v[98:99], v[148:149], v[154:155] op_sel:[0,0,0] op_sel_hi:[0,1,1]
	ds_read_b128 v[68:71], v196 offset:46848
	v_pk_fma_f32 v[126:127], v[98:99], v[148:149], v[156:157] op_sel:[1,0,0] op_sel_hi:[1,1,1]
	ds_read_b128 v[72:75], v196 offset:47104
	v_pk_mul_f32 v[132:133], v[120:121], v[20:21] op_sel:[0,0] op_sel_hi:[1,0]
	v_pk_mul_f32 v[128:129], v[120:121], v[84:85] op_sel:[0,0] op_sel_hi:[1,0]
	v_pk_fma_f32 v[132:133], v[122:123], v[20:21], v[132:133] op_sel:[0,1,0] op_sel_hi:[1,1,1]
	v_pk_fma_f32 v[128:129], v[122:123], v[84:85], v[128:129] op_sel:[0,1,0] op_sel_hi:[1,1,1]
	v_pk_fma_f32 v[132:133], v[124:125], v[22:23], v[132:133] op_sel:[0,0,0] op_sel_hi:[1,0,1]
	v_pk_fma_f32 v[128:129], v[124:125], v[86:87], v[128:129] op_sel:[0,0,0] op_sel_hi:[1,0,1]
	v_pk_fma_f32 v[132:133], v[126:127], v[22:23], v[132:133] op_sel:[0,1,0] op_sel_hi:[1,1,1]
	v_pk_fma_f32 v[128:129], v[126:127], v[86:87], v[128:129] op_sel:[0,1,0] op_sel_hi:[1,1,1]
	ds_read_b64 v[76:77], v197 offset:47360
	v_cndmask_b32_e64 v106, v147, v146, s[12:13]
	v_cndmask_b32_e64 v106, v106, v145, s[10:11]
	v_cndmask_b32_e64 v106, v106, v144, s[6:7]
	s_and_saveexec_b64 s[28:29], s[8:9]
	global_store_dword v[104:105], v106, off
	s_mov_b64 exec, s[28:29]
	v_lshl_add_u64 v[104:105], v[104:105], 0, s[26:27]
	s_waitcnt lgkmcnt(6)
	v_cndmask_b32_e64 v134, v133, v132, s[2:3]
	v_cndmask_b32_e64 v135, v132, v133, s[2:3]
	v_cndmask_b32_e64 v136, v129, v128, s[2:3]
	v_cndmask_b32_e64 v137, v128, v129, s[2:3]
	v_add_f32_dpp v138, v135, v134 quad_perm:[1,0,3,2] row_mask:0xf bank_mask:0xf bound_ctrl:1
	v_pk_mul_f32 v[150:151], v[16:17], v[28:29] op_sel:[0,0] op_sel_hi:[0,1]
	v_add_f32_dpp v139, v137, v136 quad_perm:[1,0,3,2] row_mask:0xf bank_mask:0xf bound_ctrl:1
	v_cndmask_b32_e64 v140, v139, v138, s[4:5]
	v_cndmask_b32_e64 v141, v138, v139, s[4:5]
	v_pk_mul_f32 v[152:153], v[16:17], v[28:29] op_sel:[1,0] op_sel_hi:[1,1]
	v_pk_mul_f32 v[154:155], v[18:19], v[28:29] op_sel:[0,0] op_sel_hi:[0,1]
	v_add_f32_dpp v142, v141, v140 quad_perm:[2,3,0,1] row_mask:0xf bank_mask:0xf bound_ctrl:1
	v_pk_mul_f32 v[156:157], v[18:19], v[28:29] op_sel:[1,0] op_sel_hi:[1,1]
	v_pk_fma_f32 v[150:151], v[120:121], v[8:9], v[150:151] op_sel:[0,0,0] op_sel_hi:[1,0,1]
	v_add_f32_dpp v142, v142, v142 row_ror:4 row_mask:0xf bank_mask:0xf bound_ctrl:1
	v_pk_fma_f32 v[152:153], v[122:123], v[8:9], v[152:153] op_sel:[0,1,0] op_sel_hi:[1,1,1]
	v_pk_fma_f32 v[154:155], v[124:125], v[10:11], v[154:155] op_sel:[0,0,0] op_sel_hi:[1,0,1]
	v_add_f32_dpp v144, v142, v142 row_ror:8 row_mask:0xf bank_mask:0xf bound_ctrl:1
	v_pk_fma_f32 v[156:157], v[126:127], v[10:11], v[156:157] op_sel:[0,1,0] op_sel_hi:[1,1,1]
	ds_read_b128 v[80:83], v196 offset:47616
	v_mov_b32_dpp v148, v144 quad_perm:[0,0,0,0] row_mask:0xf bank_mask:0xf
	v_mov_b32_dpp v149, v144 quad_perm:[1,1,1,1] row_mask:0xf bank_mask:0xf
	v_pk_fma_f32 v[120:121], v[24:25], v[148:149], v[150:151] op_sel:[0,0,0] op_sel_hi:[0,1,1]
	ds_read_b128 v[84:87], v196 offset:47872
	v_pk_fma_f32 v[122:123], v[24:25], v[148:149], v[152:153] op_sel:[1,0,0] op_sel_hi:[1,1,1]
	ds_read_b128 v[88:91], v196 offset:48128
	v_pk_fma_f32 v[124:125], v[26:27], v[148:149], v[154:155] op_sel:[0,0,0] op_sel_hi:[0,1,1]
	ds_read_b128 v[92:95], v196 offset:48384
	v_pk_fma_f32 v[126:127], v[26:27], v[148:149], v[156:157] op_sel:[1,0,0] op_sel_hi:[1,1,1]
	ds_read_b128 v[96:99], v196 offset:48640
	v_pk_mul_f32 v[132:133], v[120:121], v[44:45] op_sel:[0,0] op_sel_hi:[1,0]
	v_pk_mul_f32 v[128:129], v[120:121], v[12:13] op_sel:[0,0] op_sel_hi:[1,0]
	v_pk_fma_f32 v[132:133], v[122:123], v[44:45], v[132:133] op_sel:[0,1,0] op_sel_hi:[1,1,1]
	v_pk_fma_f32 v[128:129], v[122:123], v[12:13], v[128:129] op_sel:[0,1,0] op_sel_hi:[1,1,1]
	v_pk_fma_f32 v[132:133], v[124:125], v[46:47], v[132:133] op_sel:[0,0,0] op_sel_hi:[1,0,1]
	v_pk_fma_f32 v[128:129], v[124:125], v[14:15], v[128:129] op_sel:[0,0,0] op_sel_hi:[1,0,1]
	v_pk_fma_f32 v[132:133], v[126:127], v[46:47], v[132:133] op_sel:[0,1,0] op_sel_hi:[1,1,1]
	v_pk_fma_f32 v[128:129], v[126:127], v[14:15], v[128:129] op_sel:[0,1,0] op_sel_hi:[1,1,1]
	ds_read_b64 v[100:101], v197 offset:48896
	s_waitcnt lgkmcnt(6)
	v_cndmask_b32_e64 v134, v133, v132, s[2:3]
	v_cndmask_b32_e64 v135, v132, v133, s[2:3]
	v_cndmask_b32_e64 v136, v129, v128, s[2:3]
	v_cndmask_b32_e64 v137, v128, v129, s[2:3]
	v_add_f32_dpp v138, v135, v134 quad_perm:[1,0,3,2] row_mask:0xf bank_mask:0xf bound_ctrl:1
	v_pk_mul_f32 v[150:151], v[40:41], v[52:53] op_sel:[0,0] op_sel_hi:[0,1]
	v_add_f32_dpp v139, v137, v136 quad_perm:[1,0,3,2] row_mask:0xf bank_mask:0xf bound_ctrl:1
	v_cndmask_b32_e64 v140, v139, v138, s[4:5]
	v_cndmask_b32_e64 v141, v138, v139, s[4:5]
	v_pk_mul_f32 v[152:153], v[40:41], v[52:53] op_sel:[1,0] op_sel_hi:[1,1]
	v_pk_mul_f32 v[154:155], v[42:43], v[52:53] op_sel:[0,0] op_sel_hi:[0,1]
	v_add_f32_dpp v142, v141, v140 quad_perm:[2,3,0,1] row_mask:0xf bank_mask:0xf bound_ctrl:1
	v_pk_mul_f32 v[156:157], v[42:43], v[52:53] op_sel:[1,0] op_sel_hi:[1,1]
	v_pk_fma_f32 v[150:151], v[120:121], v[32:33], v[150:151] op_sel:[0,0,0] op_sel_hi:[1,0,1]
	v_add_f32_dpp v142, v142, v142 row_ror:4 row_mask:0xf bank_mask:0xf bound_ctrl:1
	v_pk_fma_f32 v[152:153], v[122:123], v[32:33], v[152:153] op_sel:[0,1,0] op_sel_hi:[1,1,1]
	v_pk_fma_f32 v[154:155], v[124:125], v[34:35], v[154:155] op_sel:[0,0,0] op_sel_hi:[1,0,1]
	v_add_f32_dpp v145, v142, v142 row_ror:8 row_mask:0xf bank_mask:0xf bound_ctrl:1
	v_pk_fma_f32 v[156:157], v[126:127], v[34:35], v[156:157] op_sel:[0,1,0] op_sel_hi:[1,1,1]
	s_nop 0
	v_mov_b32_dpp v148, v145 quad_perm:[0,0,0,0] row_mask:0xf bank_mask:0xf
	v_mov_b32_dpp v149, v145 quad_perm:[1,1,1,1] row_mask:0xf bank_mask:0xf
	v_pk_fma_f32 v[120:121], v[48:49], v[148:149], v[150:151] op_sel:[0,0,0] op_sel_hi:[0,1,1]
	v_pk_fma_f32 v[122:123], v[48:49], v[148:149], v[152:153] op_sel:[1,0,0] op_sel_hi:[1,1,1]
	v_pk_fma_f32 v[124:125], v[50:51], v[148:149], v[154:155] op_sel:[0,0,0] op_sel_hi:[0,1,1]
	v_pk_fma_f32 v[126:127], v[50:51], v[148:149], v[156:157] op_sel:[1,0,0] op_sel_hi:[1,1,1]
	v_pk_mul_f32 v[132:133], v[120:121], v[68:69] op_sel:[0,0] op_sel_hi:[1,0]
	v_pk_mul_f32 v[128:129], v[120:121], v[36:37] op_sel:[0,0] op_sel_hi:[1,0]
	v_pk_fma_f32 v[132:133], v[122:123], v[68:69], v[132:133] op_sel:[0,1,0] op_sel_hi:[1,1,1]
	v_pk_fma_f32 v[128:129], v[122:123], v[36:37], v[128:129] op_sel:[0,1,0] op_sel_hi:[1,1,1]
	v_pk_fma_f32 v[132:133], v[124:125], v[70:71], v[132:133] op_sel:[0,0,0] op_sel_hi:[1,0,1]
	v_pk_fma_f32 v[128:129], v[124:125], v[38:39], v[128:129] op_sel:[0,0,0] op_sel_hi:[1,0,1]
	v_pk_fma_f32 v[132:133], v[126:127], v[70:71], v[132:133] op_sel:[0,1,0] op_sel_hi:[1,1,1]
	v_pk_fma_f32 v[128:129], v[126:127], v[38:39], v[128:129] op_sel:[0,1,0] op_sel_hi:[1,1,1]
	s_waitcnt lgkmcnt(0)
	v_cndmask_b32_e64 v134, v133, v132, s[2:3]
	v_cndmask_b32_e64 v135, v132, v133, s[2:3]
	v_cndmask_b32_e64 v136, v129, v128, s[2:3]
	v_cndmask_b32_e64 v137, v128, v129, s[2:3]
	v_add_f32_dpp v138, v135, v134 quad_perm:[1,0,3,2] row_mask:0xf bank_mask:0xf bound_ctrl:1
	v_pk_mul_f32 v[150:151], v[64:65], v[76:77] op_sel:[0,0] op_sel_hi:[0,1]
	v_add_f32_dpp v139, v137, v136 quad_perm:[1,0,3,2] row_mask:0xf bank_mask:0xf bound_ctrl:1
	v_cndmask_b32_e64 v140, v139, v138, s[4:5]
	v_cndmask_b32_e64 v141, v138, v139, s[4:5]
	v_pk_mul_f32 v[152:153], v[64:65], v[76:77] op_sel:[1,0] op_sel_hi:[1,1]
	v_pk_mul_f32 v[154:155], v[66:67], v[76:77] op_sel:[0,0] op_sel_hi:[0,1]
	v_add_f32_dpp v142, v141, v140 quad_perm:[2,3,0,1] row_mask:0xf bank_mask:0xf bound_ctrl:1
	v_pk_mul_f32 v[156:157], v[66:67], v[76:77] op_sel:[1,0] op_sel_hi:[1,1]
	v_pk_fma_f32 v[150:151], v[120:121], v[56:57], v[150:151] op_sel:[0,0,0] op_sel_hi:[1,0,1]
	v_add_f32_dpp v142, v142, v142 row_ror:4 row_mask:0xf bank_mask:0xf bound_ctrl:1
	v_pk_fma_f32 v[152:153], v[122:123], v[56:57], v[152:153] op_sel:[0,1,0] op_sel_hi:[1,1,1]
	v_pk_fma_f32 v[154:155], v[124:125], v[58:59], v[154:155] op_sel:[0,0,0] op_sel_hi:[1,0,1]
	v_add_f32_dpp v146, v142, v142 row_ror:8 row_mask:0xf bank_mask:0xf bound_ctrl:1
	v_pk_fma_f32 v[156:157], v[126:127], v[58:59], v[156:157] op_sel:[0,1,0] op_sel_hi:[1,1,1]
	s_nop 0
	v_mov_b32_dpp v148, v146 quad_perm:[0,0,0,0] row_mask:0xf bank_mask:0xf
	v_mov_b32_dpp v149, v146 quad_perm:[1,1,1,1] row_mask:0xf bank_mask:0xf
	v_pk_fma_f32 v[120:121], v[72:73], v[148:149], v[150:151] op_sel:[0,0,0] op_sel_hi:[0,1,1]
	v_pk_fma_f32 v[122:123], v[72:73], v[148:149], v[152:153] op_sel:[1,0,0] op_sel_hi:[1,1,1]
	v_pk_fma_f32 v[124:125], v[74:75], v[148:149], v[154:155] op_sel:[0,0,0] op_sel_hi:[0,1,1]
	v_pk_fma_f32 v[126:127], v[74:75], v[148:149], v[156:157] op_sel:[1,0,0] op_sel_hi:[1,1,1]
	v_pk_mul_f32 v[132:133], v[120:121], v[92:93] op_sel:[0,0] op_sel_hi:[1,0]
	v_pk_mul_f32 v[128:129], v[120:121], v[60:61] op_sel:[0,0] op_sel_hi:[1,0]
	v_pk_fma_f32 v[132:133], v[122:123], v[92:93], v[132:133] op_sel:[0,1,0] op_sel_hi:[1,1,1]
	v_pk_fma_f32 v[128:129], v[122:123], v[60:61], v[128:129] op_sel:[0,1,0] op_sel_hi:[1,1,1]
	v_pk_fma_f32 v[132:133], v[124:125], v[94:95], v[132:133] op_sel:[0,0,0] op_sel_hi:[1,0,1]
	v_pk_fma_f32 v[128:129], v[124:125], v[62:63], v[128:129] op_sel:[0,0,0] op_sel_hi:[1,0,1]
	v_pk_fma_f32 v[132:133], v[126:127], v[94:95], v[132:133] op_sel:[0,1,0] op_sel_hi:[1,1,1]
	v_pk_fma_f32 v[128:129], v[126:127], v[62:63], v[128:129] op_sel:[0,1,0] op_sel_hi:[1,1,1]
	v_cndmask_b32_e64 v134, v133, v132, s[2:3]
	v_cndmask_b32_e64 v135, v132, v133, s[2:3]
	v_cndmask_b32_e64 v136, v129, v128, s[2:3]
	v_cndmask_b32_e64 v137, v128, v129, s[2:3]
	v_add_f32_dpp v138, v135, v134 quad_perm:[1,0,3,2] row_mask:0xf bank_mask:0xf bound_ctrl:1
	v_pk_mul_f32 v[150:151], v[88:89], v[100:101] op_sel:[0,0] op_sel_hi:[0,1]
	v_add_f32_dpp v139, v137, v136 quad_perm:[1,0,3,2] row_mask:0xf bank_mask:0xf bound_ctrl:1
	v_cndmask_b32_e64 v140, v139, v138, s[4:5]
	v_cndmask_b32_e64 v141, v138, v139, s[4:5]
	v_pk_mul_f32 v[152:153], v[88:89], v[100:101] op_sel:[1,0] op_sel_hi:[1,1]
	v_pk_mul_f32 v[154:155], v[90:91], v[100:101] op_sel:[0,0] op_sel_hi:[0,1]
	v_add_f32_dpp v142, v141, v140 quad_perm:[2,3,0,1] row_mask:0xf bank_mask:0xf bound_ctrl:1
	v_pk_mul_f32 v[156:157], v[90:91], v[100:101] op_sel:[1,0] op_sel_hi:[1,1]
	v_pk_fma_f32 v[150:151], v[120:121], v[80:81], v[150:151] op_sel:[0,0,0] op_sel_hi:[1,0,1]
	v_add_f32_dpp v142, v142, v142 row_ror:4 row_mask:0xf bank_mask:0xf bound_ctrl:1
	v_pk_fma_f32 v[152:153], v[122:123], v[80:81], v[152:153] op_sel:[0,1,0] op_sel_hi:[1,1,1]
	v_pk_fma_f32 v[154:155], v[124:125], v[82:83], v[154:155] op_sel:[0,0,0] op_sel_hi:[1,0,1]
	v_add_f32_dpp v147, v142, v142 row_ror:8 row_mask:0xf bank_mask:0xf bound_ctrl:1
	v_pk_fma_f32 v[156:157], v[126:127], v[82:83], v[156:157] op_sel:[0,1,0] op_sel_hi:[1,1,1]
	s_nop 0
	v_mov_b32_dpp v148, v147 quad_perm:[0,0,0,0] row_mask:0xf bank_mask:0xf
	v_mov_b32_dpp v149, v147 quad_perm:[1,1,1,1] row_mask:0xf bank_mask:0xf
	v_pk_fma_f32 v[120:121], v[96:97], v[148:149], v[150:151] op_sel:[0,0,0] op_sel_hi:[0,1,1]
	v_pk_fma_f32 v[122:123], v[96:97], v[148:149], v[152:153] op_sel:[1,0,0] op_sel_hi:[1,1,1]
	v_pk_fma_f32 v[124:125], v[98:99], v[148:149], v[154:155] op_sel:[0,0,0] op_sel_hi:[0,1,1]
	v_pk_fma_f32 v[126:127], v[98:99], v[148:149], v[156:157] op_sel:[1,0,0] op_sel_hi:[1,1,1]
	v_pk_mul_f32 v[128:129], v[120:121], v[84:85] op_sel:[0,0] op_sel_hi:[1,0]
	v_pk_fma_f32 v[128:129], v[122:123], v[84:85], v[128:129] op_sel:[0,1,0] op_sel_hi:[1,1,1]
	v_pk_fma_f32 v[128:129], v[124:125], v[86:87], v[128:129] op_sel:[0,0,0] op_sel_hi:[1,0,1]
	v_pk_fma_f32 v[128:129], v[126:127], v[86:87], v[128:129] op_sel:[0,1,0] op_sel_hi:[1,1,1]
	v_cndmask_b32_e64 v106, v147, v146, s[12:13]
	v_cndmask_b32_e64 v106, v106, v145, s[10:11]
	v_cndmask_b32_e64 v106, v106, v144, s[6:7]
	s_and_saveexec_b64 s[28:29], s[8:9]
	global_store_dword v[104:105], v106, off
	s_mov_b64 exec, s[28:29]
	v_mov_b32_e32 v74, v128
	v_mov_b32_e32 v75, v129
	s_mov_b64 s[22:23], -1
	s_and_b64 vcc, exec, s[18:19]
	s_cbranch_vccnz .LBB0_2815
